# all 10 GEMM main loops: MFMAs reordered into accumulator chains (k0,k1 of the same accumulator adjacent, SrcC forwarding), bit-identical math
# speedup vs baseline: 1.0121x; 1.0121x over previous
.LBB0_176:
	s_add_u32 s34, s26, 0xfff80080
	s_addc_u32 s35, s27, -1
	s_add_i32 s43, 0, 0x10000
	s_cmp_eq_u32 s33, 28
	s_cselect_b32 s37, s3, s35
	s_cselect_b32 s36, s10, s34
	s_cselect_b32 s35, s11, s29
	s_cselect_b32 s34, s21, s22
	s_add_i32 s66, 0, 0x14000
	v_add_u32_e32 v158, s43, v151
	v_add_u32_e32 v182, s66, v151
	ds_read_b128 v[142:145], v158
	ds_read_b128 v[146:149], v158 offset:1024
	ds_read_b128 v[154:157], v158 offset:2048
	ds_read_b128 v[158:161], v158 offset:3072
	ds_read_b128 v[162:165], v182
	ds_read_b128 v[166:169], v182 offset:1024
	ds_read_b128 v[178:181], v182 offset:2048
	ds_read_b128 v[182:185], v182 offset:3072
	v_lshl_add_u64 v[228:229], s[26:27], 0, v[138:139]
	s_add_i32 m0, s56, 0xc000
	ds_read_b128 v[186:189], v153
	ds_read_b128 v[190:193], v153 offset:1024
	ds_read_b128 v[194:197], v153 offset:2048
	ds_read_b128 v[208:211], v153 offset:3072
	ds_read_b128 v[212:215], v153 offset:4096
	ds_read_b128 v[216:219], v153 offset:5120
	ds_read_b128 v[220:223], v153 offset:6144
	ds_read_b128 v[224:227], v153 offset:7168
	global_load_lds_dwordx4 v[228:229], off
	v_lshl_add_u64 v[228:229], s[26:27], 0, v[140:141]
	s_add_i32 m0, s56, 0xe000
	s_nop 0
	global_load_lds_dwordx4 v[228:229], off
	s_waitcnt vmcnt(8)
	s_waitcnt lgkmcnt(0)
	s_barrier
	s_setprio 1
	s_waitcnt lgkmcnt(0)
	v_mfma_f32_16x16x32_bf16 v[128:131], v[142:145], v[186:189], v[128:131]
	v_mfma_f32_16x16x32_bf16 v[128:131], v[146:149], v[190:193], v[128:131]
	v_mfma_f32_16x16x32_bf16 v[124:127], v[154:157], v[186:189], v[124:127]
	v_mfma_f32_16x16x32_bf16 v[124:127], v[158:161], v[190:193], v[124:127]
	v_mfma_f32_16x16x32_bf16 v[112:115], v[142:145], v[194:197], v[112:115]
	v_mfma_f32_16x16x32_bf16 v[112:115], v[146:149], v[208:211], v[112:115]
	v_mfma_f32_16x16x32_bf16 v[108:111], v[154:157], v[194:197], v[108:111]
	v_mfma_f32_16x16x32_bf16 v[108:111], v[158:161], v[208:211], v[108:111]
	v_mfma_f32_16x16x32_bf16 v[96:99], v[142:145], v[212:215], v[96:99]
	v_mfma_f32_16x16x32_bf16 v[96:99], v[146:149], v[216:219], v[96:99]
	v_mfma_f32_16x16x32_bf16 v[92:95], v[154:157], v[212:215], v[92:95]
	v_mfma_f32_16x16x32_bf16 v[92:95], v[158:161], v[216:219], v[92:95]
	v_mfma_f32_16x16x32_bf16 v[80:83], v[142:145], v[220:223], v[80:83]
	v_mfma_f32_16x16x32_bf16 v[80:83], v[146:149], v[224:227], v[80:83]
	v_mfma_f32_16x16x32_bf16 v[76:79], v[154:157], v[220:223], v[76:79]
	v_mfma_f32_16x16x32_bf16 v[76:79], v[158:161], v[224:227], v[76:79]
	s_setprio 0
	s_setprio 1
	v_mfma_f32_16x16x32_bf16 v[120:123], v[162:165], v[186:189], v[120:123]
	v_mfma_f32_16x16x32_bf16 v[120:123], v[166:169], v[190:193], v[120:123]
	v_mfma_f32_16x16x32_bf16 v[116:119], v[178:181], v[186:189], v[116:119]
	v_mfma_f32_16x16x32_bf16 v[116:119], v[182:185], v[190:193], v[116:119]
	v_mfma_f32_16x16x32_bf16 v[104:107], v[162:165], v[194:197], v[104:107]
	v_mfma_f32_16x16x32_bf16 v[104:107], v[166:169], v[208:211], v[104:107]
	v_mfma_f32_16x16x32_bf16 v[100:103], v[178:181], v[194:197], v[100:103]
	v_mfma_f32_16x16x32_bf16 v[100:103], v[182:185], v[208:211], v[100:103]
	v_mfma_f32_16x16x32_bf16 v[88:91], v[162:165], v[212:215], v[88:91]
	v_mfma_f32_16x16x32_bf16 v[88:91], v[166:169], v[216:219], v[88:91]
	v_mfma_f32_16x16x32_bf16 v[84:87], v[178:181], v[212:215], v[84:87]
	v_mfma_f32_16x16x32_bf16 v[84:87], v[182:185], v[216:219], v[84:87]
	v_mfma_f32_16x16x32_bf16 v[72:75], v[162:165], v[220:223], v[72:75]
	v_mfma_f32_16x16x32_bf16 v[72:75], v[166:169], v[224:227], v[72:75]
	v_mfma_f32_16x16x32_bf16 v[68:71], v[178:181], v[220:223], v[68:71]
	v_mfma_f32_16x16x32_bf16 v[68:71], v[182:185], v[224:227], v[68:71]
	s_setprio 0
	s_barrier
	s_add_i32 s43, s43, s54
	v_lshl_add_u64 v[228:229], s[34:35], 0, v[2:3]
	s_mov_b32 m0, s43
	ds_read_b128 v[186:189], v153 offset:16384
	ds_read_b128 v[190:193], v153 offset:17408
	ds_read_b128 v[194:197], v153 offset:18432
	ds_read_b128 v[208:211], v153 offset:19456
	ds_read_b128 v[212:215], v153 offset:20480
	ds_read_b128 v[216:219], v153 offset:21504
	ds_read_b128 v[220:223], v153 offset:22528
	ds_read_b128 v[224:227], v153 offset:23552
	global_load_lds_dwordx4 v[228:229], off
	s_add_i32 m0, s43, 0x2000
	s_add_u32 s64, s34, 0x80000
	v_lshl_add_u64 v[230:231], s[34:35], 0, v[132:133]
	s_addc_u32 s65, s35, 0
	s_add_i32 s43, s66, s54
	global_load_lds_dwordx4 v[230:231], off
	v_lshl_add_u64 v[232:233], s[64:65], 0, v[2:3]
	s_mov_b32 m0, s43
	v_lshl_add_u64 v[234:235], s[36:37], 0, v[134:135]
	global_load_lds_dwordx4 v[232:233], off
	v_lshl_add_u64 v[232:233], s[64:65], 0, v[132:133]
	s_add_i32 m0, s43, 0x2000
	s_nop 0
	global_load_lds_dwordx4 v[232:233], off
	v_lshl_add_u64 v[232:233], s[36:37], 0, v[136:137]
	s_mov_b32 m0, s56
	s_nop 0
	global_load_lds_dwordx4 v[232:233], off
	s_mov_b32 m0, s57
	s_nop 0
	global_load_lds_dwordx4 v[234:235], off
	s_waitcnt vmcnt(8)
	s_waitcnt lgkmcnt(0)
	s_barrier
	s_setprio 1
	s_waitcnt lgkmcnt(0)
	v_mfma_f32_16x16x32_bf16 v[64:67], v[142:145], v[186:189], v[64:67]
	v_mfma_f32_16x16x32_bf16 v[64:67], v[146:149], v[190:193], v[64:67]
	v_mfma_f32_16x16x32_bf16 v[60:63], v[154:157], v[186:189], v[60:63]
	v_mfma_f32_16x16x32_bf16 v[60:63], v[158:161], v[190:193], v[60:63]
	v_mfma_f32_16x16x32_bf16 v[48:51], v[142:145], v[194:197], v[48:51]
	v_mfma_f32_16x16x32_bf16 v[48:51], v[146:149], v[208:211], v[48:51]
	v_mfma_f32_16x16x32_bf16 v[44:47], v[154:157], v[194:197], v[44:47]
	v_mfma_f32_16x16x32_bf16 v[44:47], v[158:161], v[208:211], v[44:47]
	v_mfma_f32_16x16x32_bf16 v[32:35], v[142:145], v[212:215], v[32:35]
	v_mfma_f32_16x16x32_bf16 v[32:35], v[146:149], v[216:219], v[32:35]
	v_mfma_f32_16x16x32_bf16 v[28:31], v[154:157], v[212:215], v[28:31]
	v_mfma_f32_16x16x32_bf16 v[28:31], v[158:161], v[216:219], v[28:31]
	v_mfma_f32_16x16x32_bf16 v[16:19], v[142:145], v[220:223], v[16:19]
	v_mfma_f32_16x16x32_bf16 v[16:19], v[146:149], v[224:227], v[16:19]
	v_mfma_f32_16x16x32_bf16 v[12:15], v[154:157], v[220:223], v[12:15]
	v_mfma_f32_16x16x32_bf16 v[12:15], v[158:161], v[224:227], v[12:15]
	s_setprio 0
	s_setprio 1
	v_mfma_f32_16x16x32_bf16 v[56:59], v[162:165], v[186:189], v[56:59]
	v_mfma_f32_16x16x32_bf16 v[56:59], v[166:169], v[190:193], v[56:59]
	v_mfma_f32_16x16x32_bf16 v[52:55], v[178:181], v[186:189], v[52:55]
	v_mfma_f32_16x16x32_bf16 v[52:55], v[182:185], v[190:193], v[52:55]
	v_mfma_f32_16x16x32_bf16 v[40:43], v[162:165], v[194:197], v[40:43]
	v_mfma_f32_16x16x32_bf16 v[40:43], v[166:169], v[208:211], v[40:43]
	v_mfma_f32_16x16x32_bf16 v[36:39], v[178:181], v[194:197], v[36:39]
	v_mfma_f32_16x16x32_bf16 v[36:39], v[182:185], v[208:211], v[36:39]
	v_mfma_f32_16x16x32_bf16 v[24:27], v[162:165], v[212:215], v[24:27]
	v_mfma_f32_16x16x32_bf16 v[24:27], v[166:169], v[216:219], v[24:27]
	v_mfma_f32_16x16x32_bf16 v[20:23], v[178:181], v[212:215], v[20:23]
	v_mfma_f32_16x16x32_bf16 v[20:23], v[182:185], v[216:219], v[20:23]
	v_mfma_f32_16x16x32_bf16 v[8:11], v[162:165], v[220:223], v[8:11]
	v_mfma_f32_16x16x32_bf16 v[8:11], v[166:169], v[224:227], v[8:11]
	v_mfma_f32_16x16x32_bf16 v[4:7], v[178:181], v[220:223], v[4:7]
	v_mfma_f32_16x16x32_bf16 v[4:7], v[182:185], v[224:227], v[4:7]
	s_setprio 0
	s_barrier
	s_add_i32 s43, 0, 0x18000
	s_add_i32 s64, 0, 0x1c000
	v_add_u32_e32 v158, s43, v151
	v_add_u32_e32 v182, s64, v151
	ds_read_b128 v[142:145], v158
	ds_read_b128 v[146:149], v158 offset:1024
	ds_read_b128 v[154:157], v158 offset:2048
	ds_read_b128 v[158:161], v158 offset:3072
	ds_read_b128 v[162:165], v182
	ds_read_b128 v[166:169], v182 offset:1024
	ds_read_b128 v[178:181], v182 offset:2048
	ds_read_b128 v[182:185], v182 offset:3072
	s_add_u32 s36, s36, 0x80000
	s_addc_u32 s37, s37, 0
	s_mov_b32 m0, s58
	v_lshl_add_u64 v[236:237], s[36:37], 0, v[136:137]
	ds_read_b128 v[186:189], v153 offset:32768
	ds_read_b128 v[190:193], v153 offset:33792
	ds_read_b128 v[194:197], v153 offset:34816
	ds_read_b128 v[208:211], v153 offset:35840
	ds_read_b128 v[212:215], v153 offset:36864
	ds_read_b128 v[216:219], v153 offset:37888
	ds_read_b128 v[220:223], v153 offset:38912
	ds_read_b128 v[224:227], v153 offset:39936
	global_load_lds_dwordx4 v[236:237], off
	v_lshl_add_u64 v[236:237], s[36:37], 0, v[134:135]
	s_mov_b32 m0, s59
	s_nop 0
	global_load_lds_dwordx4 v[236:237], off
	s_waitcnt vmcnt(8)
	s_waitcnt lgkmcnt(0)
	s_barrier
	s_setprio 1
	s_waitcnt lgkmcnt(0)
	v_mfma_f32_16x16x32_bf16 v[128:131], v[142:145], v[186:189], v[128:131]
	v_mfma_f32_16x16x32_bf16 v[128:131], v[146:149], v[190:193], v[128:131]
	v_mfma_f32_16x16x32_bf16 v[124:127], v[154:157], v[186:189], v[124:127]
	v_mfma_f32_16x16x32_bf16 v[124:127], v[158:161], v[190:193], v[124:127]
	v_mfma_f32_16x16x32_bf16 v[112:115], v[142:145], v[194:197], v[112:115]
	v_mfma_f32_16x16x32_bf16 v[112:115], v[146:149], v[208:211], v[112:115]
	v_mfma_f32_16x16x32_bf16 v[108:111], v[154:157], v[194:197], v[108:111]
	v_mfma_f32_16x16x32_bf16 v[108:111], v[158:161], v[208:211], v[108:111]
	v_mfma_f32_16x16x32_bf16 v[96:99], v[142:145], v[212:215], v[96:99]
	v_mfma_f32_16x16x32_bf16 v[96:99], v[146:149], v[216:219], v[96:99]
	v_mfma_f32_16x16x32_bf16 v[92:95], v[154:157], v[212:215], v[92:95]
	v_mfma_f32_16x16x32_bf16 v[92:95], v[158:161], v[216:219], v[92:95]
	v_mfma_f32_16x16x32_bf16 v[80:83], v[142:145], v[220:223], v[80:83]
	v_mfma_f32_16x16x32_bf16 v[80:83], v[146:149], v[224:227], v[80:83]
	v_mfma_f32_16x16x32_bf16 v[76:79], v[154:157], v[220:223], v[76:79]
	v_mfma_f32_16x16x32_bf16 v[76:79], v[158:161], v[224:227], v[76:79]
	s_setprio 0
	s_setprio 1
	v_mfma_f32_16x16x32_bf16 v[120:123], v[162:165], v[186:189], v[120:123]
	v_mfma_f32_16x16x32_bf16 v[120:123], v[166:169], v[190:193], v[120:123]
	v_mfma_f32_16x16x32_bf16 v[116:119], v[178:181], v[186:189], v[116:119]
	v_mfma_f32_16x16x32_bf16 v[116:119], v[182:185], v[190:193], v[116:119]
	v_mfma_f32_16x16x32_bf16 v[104:107], v[162:165], v[194:197], v[104:107]
	v_mfma_f32_16x16x32_bf16 v[104:107], v[166:169], v[208:211], v[104:107]
	v_mfma_f32_16x16x32_bf16 v[100:103], v[178:181], v[194:197], v[100:103]
	v_mfma_f32_16x16x32_bf16 v[100:103], v[182:185], v[208:211], v[100:103]
	v_mfma_f32_16x16x32_bf16 v[88:91], v[162:165], v[212:215], v[88:91]
	v_mfma_f32_16x16x32_bf16 v[88:91], v[166:169], v[216:219], v[88:91]
	v_mfma_f32_16x16x32_bf16 v[84:87], v[178:181], v[212:215], v[84:87]
	v_mfma_f32_16x16x32_bf16 v[84:87], v[182:185], v[216:219], v[84:87]
	v_mfma_f32_16x16x32_bf16 v[72:75], v[162:165], v[220:223], v[72:75]
	v_mfma_f32_16x16x32_bf16 v[72:75], v[166:169], v[224:227], v[72:75]
	v_mfma_f32_16x16x32_bf16 v[68:71], v[178:181], v[220:223], v[68:71]
	v_mfma_f32_16x16x32_bf16 v[68:71], v[182:185], v[224:227], v[68:71]
	s_setprio 0
	s_barrier
	s_add_i32 s36, s43, s54
	v_lshl_add_u64 v[228:229], v[228:229], 0, s[18:19]
	s_mov_b32 m0, s36
	ds_read_b128 v[186:189], v153 offset:49152
	ds_read_b128 v[190:193], v153 offset:50176
	ds_read_b128 v[194:197], v153 offset:51200
	ds_read_b128 v[208:211], v153 offset:52224
	ds_read_b128 v[212:215], v153 offset:53248
	ds_read_b128 v[216:219], v153 offset:54272
	ds_read_b128 v[220:223], v153 offset:55296
	ds_read_b128 v[224:227], v153 offset:56320
	global_load_lds_dwordx4 v[228:229], off
	s_add_i32 m0, s36, 0x2000
	s_add_u32 s34, s34, 0x80080
	v_lshl_add_u64 v[228:229], v[230:231], 0, s[18:19]
	s_addc_u32 s35, s35, 0
	s_add_i32 s36, s64, s54
	global_load_lds_dwordx4 v[228:229], off
	v_lshl_add_u64 v[228:229], s[34:35], 0, v[2:3]
	s_mov_b32 m0, s36
	s_nop 0
	global_load_lds_dwordx4 v[228:229], off
	v_lshl_add_u64 v[228:229], s[34:35], 0, v[132:133]
	s_add_i32 m0, s36, 0x2000
	s_nop 0
	global_load_lds_dwordx4 v[228:229], off
	v_lshl_add_u64 v[228:229], v[232:233], 0, s[18:19]
	s_mov_b32 m0, s60
	s_nop 0
	global_load_lds_dwordx4 v[228:229], off
	v_lshl_add_u64 v[228:229], v[234:235], 0, s[18:19]
	s_mov_b32 m0, s61
	s_nop 0
	global_load_lds_dwordx4 v[228:229], off
	s_waitcnt vmcnt(8)
	s_waitcnt lgkmcnt(0)
	s_barrier
	s_setprio 1
	s_waitcnt lgkmcnt(0)
	v_mfma_f32_16x16x32_bf16 v[64:67], v[142:145], v[186:189], v[64:67]
	v_mfma_f32_16x16x32_bf16 v[64:67], v[146:149], v[190:193], v[64:67]
	v_mfma_f32_16x16x32_bf16 v[60:63], v[154:157], v[186:189], v[60:63]
	v_mfma_f32_16x16x32_bf16 v[60:63], v[158:161], v[190:193], v[60:63]
	v_mfma_f32_16x16x32_bf16 v[48:51], v[142:145], v[194:197], v[48:51]
	v_mfma_f32_16x16x32_bf16 v[48:51], v[146:149], v[208:211], v[48:51]
	v_mfma_f32_16x16x32_bf16 v[44:47], v[154:157], v[194:197], v[44:47]
	v_mfma_f32_16x16x32_bf16 v[44:47], v[158:161], v[208:211], v[44:47]
	v_mfma_f32_16x16x32_bf16 v[32:35], v[142:145], v[212:215], v[32:35]
	v_mfma_f32_16x16x32_bf16 v[32:35], v[146:149], v[216:219], v[32:35]
	v_mfma_f32_16x16x32_bf16 v[28:31], v[154:157], v[212:215], v[28:31]
	v_mfma_f32_16x16x32_bf16 v[28:31], v[158:161], v[216:219], v[28:31]
	v_mfma_f32_16x16x32_bf16 v[16:19], v[142:145], v[220:223], v[16:19]
	v_mfma_f32_16x16x32_bf16 v[16:19], v[146:149], v[224:227], v[16:19]
	v_mfma_f32_16x16x32_bf16 v[12:15], v[154:157], v[220:223], v[12:15]
	v_mfma_f32_16x16x32_bf16 v[12:15], v[158:161], v[224:227], v[12:15]
	s_setprio 0
	s_setprio 1
	v_mfma_f32_16x16x32_bf16 v[56:59], v[162:165], v[186:189], v[56:59]
	v_mfma_f32_16x16x32_bf16 v[56:59], v[166:169], v[190:193], v[56:59]
	v_mfma_f32_16x16x32_bf16 v[52:55], v[178:181], v[186:189], v[52:55]
	v_mfma_f32_16x16x32_bf16 v[52:55], v[182:185], v[190:193], v[52:55]
	v_mfma_f32_16x16x32_bf16 v[40:43], v[162:165], v[194:197], v[40:43]
	v_mfma_f32_16x16x32_bf16 v[40:43], v[166:169], v[208:211], v[40:43]
	v_mfma_f32_16x16x32_bf16 v[36:39], v[178:181], v[194:197], v[36:39]
	v_mfma_f32_16x16x32_bf16 v[36:39], v[182:185], v[208:211], v[36:39]
	v_mfma_f32_16x16x32_bf16 v[24:27], v[162:165], v[212:215], v[24:27]
	v_mfma_f32_16x16x32_bf16 v[24:27], v[166:169], v[216:219], v[24:27]
	v_mfma_f32_16x16x32_bf16 v[20:23], v[178:181], v[212:215], v[20:23]
	v_mfma_f32_16x16x32_bf16 v[20:23], v[182:185], v[216:219], v[20:23]
	v_mfma_f32_16x16x32_bf16 v[8:11], v[162:165], v[220:223], v[8:11]
	v_mfma_f32_16x16x32_bf16 v[8:11], v[166:169], v[224:227], v[8:11]
	v_mfma_f32_16x16x32_bf16 v[4:7], v[178:181], v[220:223], v[4:7]
	v_mfma_f32_16x16x32_bf16 v[4:7], v[182:185], v[224:227], v[4:7]
	s_setprio 0
	s_barrier
	s_add_i32 s33, s33, 2
	s_add_u32 s26, s26, 0x100
	s_addc_u32 s27, s27, 0
	s_add_u32 s22, s22, 0x100
	s_addc_u32 s29, s29, 0
	s_cmp_gt_u32 s33, 29
	s_cbranch_scc0 .LBB0_176
	s_and_b64 vcc, exec, s[12:13]
	s_cbranch_vccz .LBB0_179
	s_barrier

.LBB0_198:
	s_add_u32 s34, s26, 0xfff80080
	s_addc_u32 s35, s27, -1
	s_add_i32 s43, 0, 0x10000
	s_cmp_eq_u32 s33, 28
	s_cselect_b32 s37, s3, s35
	s_cselect_b32 s36, s10, s34
	s_cselect_b32 s35, s11, s29
	s_cselect_b32 s34, s21, s22
	s_add_i32 s66, 0, 0x14000
	v_add_u32_e32 v164, s43, v152
	v_add_u32_e32 v168, s66, v152
	ds_read_b128 v[142:145], v164
	ds_read_b128 v[146:149], v164 offset:1024
	ds_read_b128 v[160:163], v164 offset:2048
	ds_read_b128 v[164:167], v164 offset:3072
	ds_read_b128 v[178:181], v168
	ds_read_b128 v[182:185], v168 offset:1024
	ds_read_b128 v[186:189], v168 offset:2048
	ds_read_b128 v[190:193], v168 offset:3072
	v_lshl_add_u64 v[168:169], s[26:27], 0, v[138:139]
	s_add_i32 m0, s56, 0xc000
	ds_read_b128 v[194:197], v159
	ds_read_b128 v[208:211], v159 offset:1024
	ds_read_b128 v[212:215], v159 offset:2048
	ds_read_b128 v[216:219], v159 offset:3072
	ds_read_b128 v[220:223], v159 offset:4096
	ds_read_b128 v[224:227], v159 offset:5120
	ds_read_b128 v[228:231], v159 offset:6144
	ds_read_b128 v[232:235], v159 offset:7168
	global_load_lds_dwordx4 v[168:169], off
	v_lshl_add_u64 v[168:169], s[26:27], 0, v[140:141]
	s_add_i32 m0, s56, 0xe000
	s_nop 0
	global_load_lds_dwordx4 v[168:169], off
	s_waitcnt vmcnt(8)
	s_waitcnt lgkmcnt(0)
	s_barrier
	s_setprio 1
	s_waitcnt lgkmcnt(0)
	v_mfma_f32_16x16x32_bf16 v[128:131], v[142:145], v[194:197], v[128:131]
	v_mfma_f32_16x16x32_bf16 v[128:131], v[146:149], v[208:211], v[128:131]
	v_mfma_f32_16x16x32_bf16 v[124:127], v[160:163], v[194:197], v[124:127]
	v_mfma_f32_16x16x32_bf16 v[124:127], v[164:167], v[208:211], v[124:127]
	v_mfma_f32_16x16x32_bf16 v[112:115], v[142:145], v[212:215], v[112:115]
	v_mfma_f32_16x16x32_bf16 v[112:115], v[146:149], v[216:219], v[112:115]
	v_mfma_f32_16x16x32_bf16 v[108:111], v[160:163], v[212:215], v[108:111]
	v_mfma_f32_16x16x32_bf16 v[108:111], v[164:167], v[216:219], v[108:111]
	v_mfma_f32_16x16x32_bf16 v[96:99], v[142:145], v[220:223], v[96:99]
	v_mfma_f32_16x16x32_bf16 v[96:99], v[146:149], v[224:227], v[96:99]
	v_mfma_f32_16x16x32_bf16 v[92:95], v[160:163], v[220:223], v[92:95]
	v_mfma_f32_16x16x32_bf16 v[92:95], v[164:167], v[224:227], v[92:95]
	v_mfma_f32_16x16x32_bf16 v[80:83], v[142:145], v[228:231], v[80:83]
	v_mfma_f32_16x16x32_bf16 v[80:83], v[146:149], v[232:235], v[80:83]
	v_mfma_f32_16x16x32_bf16 v[76:79], v[160:163], v[228:231], v[76:79]
	v_mfma_f32_16x16x32_bf16 v[76:79], v[164:167], v[232:235], v[76:79]
	s_setprio 0
	s_setprio 1
	v_mfma_f32_16x16x32_bf16 v[120:123], v[178:181], v[194:197], v[120:123]
	v_mfma_f32_16x16x32_bf16 v[120:123], v[182:185], v[208:211], v[120:123]
	v_mfma_f32_16x16x32_bf16 v[116:119], v[186:189], v[194:197], v[116:119]
	v_mfma_f32_16x16x32_bf16 v[116:119], v[190:193], v[208:211], v[116:119]
	v_mfma_f32_16x16x32_bf16 v[104:107], v[178:181], v[212:215], v[104:107]
	v_mfma_f32_16x16x32_bf16 v[104:107], v[182:185], v[216:219], v[104:107]
	v_mfma_f32_16x16x32_bf16 v[100:103], v[186:189], v[212:215], v[100:103]
	v_mfma_f32_16x16x32_bf16 v[100:103], v[190:193], v[216:219], v[100:103]
	v_mfma_f32_16x16x32_bf16 v[88:91], v[178:181], v[220:223], v[88:91]
	v_mfma_f32_16x16x32_bf16 v[88:91], v[182:185], v[224:227], v[88:91]
	v_mfma_f32_16x16x32_bf16 v[84:87], v[186:189], v[220:223], v[84:87]
	v_mfma_f32_16x16x32_bf16 v[84:87], v[190:193], v[224:227], v[84:87]
	v_mfma_f32_16x16x32_bf16 v[72:75], v[178:181], v[228:231], v[72:75]
	v_mfma_f32_16x16x32_bf16 v[72:75], v[182:185], v[232:235], v[72:75]
	v_mfma_f32_16x16x32_bf16 v[68:71], v[186:189], v[228:231], v[68:71]
	v_mfma_f32_16x16x32_bf16 v[68:71], v[190:193], v[232:235], v[68:71]
	s_setprio 0
	s_barrier
	s_add_i32 s43, s43, s54
	v_lshl_add_u64 v[168:169], s[34:35], 0, v[2:3]
	s_mov_b32 m0, s43
	ds_read_b128 v[194:197], v159 offset:16384
	ds_read_b128 v[208:211], v159 offset:17408
	ds_read_b128 v[212:215], v159 offset:18432
	ds_read_b128 v[216:219], v159 offset:19456
	ds_read_b128 v[220:223], v159 offset:20480
	ds_read_b128 v[224:227], v159 offset:21504
	ds_read_b128 v[228:231], v159 offset:22528
	ds_read_b128 v[232:235], v159 offset:23552
	global_load_lds_dwordx4 v[168:169], off
	s_add_i32 m0, s43, 0x2000
	s_add_u32 s64, s34, 0x80000
	v_lshl_add_u64 v[236:237], s[34:35], 0, v[132:133]
	s_addc_u32 s65, s35, 0
	s_add_i32 s43, s66, s54
	global_load_lds_dwordx4 v[236:237], off
	v_lshl_add_u64 v[238:239], s[64:65], 0, v[2:3]
	s_mov_b32 m0, s43
	v_lshl_add_u64 v[240:241], s[36:37], 0, v[134:135]
	global_load_lds_dwordx4 v[238:239], off
	v_lshl_add_u64 v[238:239], s[64:65], 0, v[132:133]
	s_add_i32 m0, s43, 0x2000
	s_nop 0
	global_load_lds_dwordx4 v[238:239], off
	v_lshl_add_u64 v[238:239], s[36:37], 0, v[136:137]
	s_mov_b32 m0, s56
	s_nop 0
	global_load_lds_dwordx4 v[238:239], off
	s_mov_b32 m0, s57
	s_nop 0
	global_load_lds_dwordx4 v[240:241], off
	s_waitcnt vmcnt(8)
	s_waitcnt lgkmcnt(0)
	s_barrier
	s_setprio 1
	s_waitcnt lgkmcnt(0)
	v_mfma_f32_16x16x32_bf16 v[64:67], v[142:145], v[194:197], v[64:67]
	v_mfma_f32_16x16x32_bf16 v[64:67], v[146:149], v[208:211], v[64:67]
	v_mfma_f32_16x16x32_bf16 v[60:63], v[160:163], v[194:197], v[60:63]
	v_mfma_f32_16x16x32_bf16 v[60:63], v[164:167], v[208:211], v[60:63]
	v_mfma_f32_16x16x32_bf16 v[48:51], v[142:145], v[212:215], v[48:51]
	v_mfma_f32_16x16x32_bf16 v[48:51], v[146:149], v[216:219], v[48:51]
	v_mfma_f32_16x16x32_bf16 v[44:47], v[160:163], v[212:215], v[44:47]
	v_mfma_f32_16x16x32_bf16 v[44:47], v[164:167], v[216:219], v[44:47]
	v_mfma_f32_16x16x32_bf16 v[32:35], v[142:145], v[220:223], v[32:35]
	v_mfma_f32_16x16x32_bf16 v[32:35], v[146:149], v[224:227], v[32:35]
	v_mfma_f32_16x16x32_bf16 v[28:31], v[160:163], v[220:223], v[28:31]
	v_mfma_f32_16x16x32_bf16 v[28:31], v[164:167], v[224:227], v[28:31]
	v_mfma_f32_16x16x32_bf16 v[16:19], v[142:145], v[228:231], v[16:19]
	v_mfma_f32_16x16x32_bf16 v[16:19], v[146:149], v[232:235], v[16:19]
	v_mfma_f32_16x16x32_bf16 v[12:15], v[160:163], v[228:231], v[12:15]
	v_mfma_f32_16x16x32_bf16 v[12:15], v[164:167], v[232:235], v[12:15]
	s_setprio 0
	s_setprio 1
	v_mfma_f32_16x16x32_bf16 v[56:59], v[178:181], v[194:197], v[56:59]
	v_mfma_f32_16x16x32_bf16 v[56:59], v[182:185], v[208:211], v[56:59]
	v_mfma_f32_16x16x32_bf16 v[52:55], v[186:189], v[194:197], v[52:55]
	v_mfma_f32_16x16x32_bf16 v[52:55], v[190:193], v[208:211], v[52:55]
	v_mfma_f32_16x16x32_bf16 v[40:43], v[178:181], v[212:215], v[40:43]
	v_mfma_f32_16x16x32_bf16 v[40:43], v[182:185], v[216:219], v[40:43]
	v_mfma_f32_16x16x32_bf16 v[36:39], v[186:189], v[212:215], v[36:39]
	v_mfma_f32_16x16x32_bf16 v[36:39], v[190:193], v[216:219], v[36:39]
	v_mfma_f32_16x16x32_bf16 v[24:27], v[178:181], v[220:223], v[24:27]
	v_mfma_f32_16x16x32_bf16 v[24:27], v[182:185], v[224:227], v[24:27]
	v_mfma_f32_16x16x32_bf16 v[20:23], v[186:189], v[220:223], v[20:23]
	v_mfma_f32_16x16x32_bf16 v[20:23], v[190:193], v[224:227], v[20:23]
	v_mfma_f32_16x16x32_bf16 v[8:11], v[178:181], v[228:231], v[8:11]
	v_mfma_f32_16x16x32_bf16 v[8:11], v[182:185], v[232:235], v[8:11]
	v_mfma_f32_16x16x32_bf16 v[4:7], v[186:189], v[228:231], v[4:7]
	v_mfma_f32_16x16x32_bf16 v[4:7], v[190:193], v[232:235], v[4:7]
	s_setprio 0
	s_barrier
	s_add_i32 s43, 0, 0x18000
	s_add_i32 s64, 0, 0x1c000
	v_add_u32_e32 v164, s43, v152
	v_add_u32_e32 v190, s64, v152
	ds_read_b128 v[142:145], v164
	ds_read_b128 v[146:149], v164 offset:1024
	ds_read_b128 v[160:163], v164 offset:2048
	ds_read_b128 v[164:167], v164 offset:3072
	ds_read_b128 v[178:181], v190
	ds_read_b128 v[182:185], v190 offset:1024
	ds_read_b128 v[186:189], v190 offset:2048
	ds_read_b128 v[190:193], v190 offset:3072
	s_add_u32 s36, s36, 0x80000
	s_addc_u32 s37, s37, 0
	s_mov_b32 m0, s58
	v_lshl_add_u64 v[242:243], s[36:37], 0, v[136:137]
	ds_read_b128 v[194:197], v159 offset:32768
	ds_read_b128 v[208:211], v159 offset:33792
	ds_read_b128 v[212:215], v159 offset:34816
	ds_read_b128 v[216:219], v159 offset:35840
	ds_read_b128 v[220:223], v159 offset:36864
	ds_read_b128 v[224:227], v159 offset:37888
	ds_read_b128 v[228:231], v159 offset:38912
	ds_read_b128 v[232:235], v159 offset:39936
	global_load_lds_dwordx4 v[242:243], off
	v_lshl_add_u64 v[242:243], s[36:37], 0, v[134:135]
	s_mov_b32 m0, s59
	s_nop 0
	global_load_lds_dwordx4 v[242:243], off
	s_waitcnt vmcnt(8)
	s_waitcnt lgkmcnt(0)
	s_barrier
	s_setprio 1
	s_waitcnt lgkmcnt(0)
	v_mfma_f32_16x16x32_bf16 v[128:131], v[142:145], v[194:197], v[128:131]
	v_mfma_f32_16x16x32_bf16 v[128:131], v[146:149], v[208:211], v[128:131]
	v_mfma_f32_16x16x32_bf16 v[124:127], v[160:163], v[194:197], v[124:127]
	v_mfma_f32_16x16x32_bf16 v[124:127], v[164:167], v[208:211], v[124:127]
	v_mfma_f32_16x16x32_bf16 v[112:115], v[142:145], v[212:215], v[112:115]
	v_mfma_f32_16x16x32_bf16 v[112:115], v[146:149], v[216:219], v[112:115]
	v_mfma_f32_16x16x32_bf16 v[108:111], v[160:163], v[212:215], v[108:111]
	v_mfma_f32_16x16x32_bf16 v[108:111], v[164:167], v[216:219], v[108:111]
	v_mfma_f32_16x16x32_bf16 v[96:99], v[142:145], v[220:223], v[96:99]
	v_mfma_f32_16x16x32_bf16 v[96:99], v[146:149], v[224:227], v[96:99]
	v_mfma_f32_16x16x32_bf16 v[92:95], v[160:163], v[220:223], v[92:95]
	v_mfma_f32_16x16x32_bf16 v[92:95], v[164:167], v[224:227], v[92:95]
	v_mfma_f32_16x16x32_bf16 v[80:83], v[142:145], v[228:231], v[80:83]
	v_mfma_f32_16x16x32_bf16 v[80:83], v[146:149], v[232:235], v[80:83]
	v_mfma_f32_16x16x32_bf16 v[76:79], v[160:163], v[228:231], v[76:79]
	v_mfma_f32_16x16x32_bf16 v[76:79], v[164:167], v[232:235], v[76:79]
	s_setprio 0
	s_setprio 1
	v_mfma_f32_16x16x32_bf16 v[120:123], v[178:181], v[194:197], v[120:123]
	v_mfma_f32_16x16x32_bf16 v[120:123], v[182:185], v[208:211], v[120:123]
	v_mfma_f32_16x16x32_bf16 v[116:119], v[186:189], v[194:197], v[116:119]
	v_mfma_f32_16x16x32_bf16 v[116:119], v[190:193], v[208:211], v[116:119]
	v_mfma_f32_16x16x32_bf16 v[104:107], v[178:181], v[212:215], v[104:107]
	v_mfma_f32_16x16x32_bf16 v[104:107], v[182:185], v[216:219], v[104:107]
	v_mfma_f32_16x16x32_bf16 v[100:103], v[186:189], v[212:215], v[100:103]
	v_mfma_f32_16x16x32_bf16 v[100:103], v[190:193], v[216:219], v[100:103]
	v_mfma_f32_16x16x32_bf16 v[88:91], v[178:181], v[220:223], v[88:91]
	v_mfma_f32_16x16x32_bf16 v[88:91], v[182:185], v[224:227], v[88:91]
	v_mfma_f32_16x16x32_bf16 v[84:87], v[186:189], v[220:223], v[84:87]
	v_mfma_f32_16x16x32_bf16 v[84:87], v[190:193], v[224:227], v[84:87]
	v_mfma_f32_16x16x32_bf16 v[72:75], v[178:181], v[228:231], v[72:75]
	v_mfma_f32_16x16x32_bf16 v[72:75], v[182:185], v[232:235], v[72:75]
	v_mfma_f32_16x16x32_bf16 v[68:71], v[186:189], v[228:231], v[68:71]
	v_mfma_f32_16x16x32_bf16 v[68:71], v[190:193], v[232:235], v[68:71]
	s_setprio 0
	s_barrier
	s_add_i32 s36, s43, s54
	v_lshl_add_u64 v[168:169], v[168:169], 0, s[18:19]
	s_mov_b32 m0, s36
	ds_read_b128 v[194:197], v159 offset:49152
	ds_read_b128 v[208:211], v159 offset:50176
	ds_read_b128 v[212:215], v159 offset:51200
	ds_read_b128 v[216:219], v159 offset:52224
	ds_read_b128 v[220:223], v159 offset:53248
	ds_read_b128 v[224:227], v159 offset:54272
	ds_read_b128 v[228:231], v159 offset:55296
	ds_read_b128 v[232:235], v159 offset:56320
	global_load_lds_dwordx4 v[168:169], off
	s_add_i32 m0, s36, 0x2000
	s_add_u32 s34, s34, 0x80080
	v_lshl_add_u64 v[168:169], v[236:237], 0, s[18:19]
	s_addc_u32 s35, s35, 0
	s_add_i32 s36, s64, s54
	global_load_lds_dwordx4 v[168:169], off
	v_lshl_add_u64 v[168:169], s[34:35], 0, v[2:3]
	s_mov_b32 m0, s36
	s_nop 0
	global_load_lds_dwordx4 v[168:169], off
	v_lshl_add_u64 v[168:169], s[34:35], 0, v[132:133]
	s_add_i32 m0, s36, 0x2000
	s_nop 0
	global_load_lds_dwordx4 v[168:169], off
	v_lshl_add_u64 v[168:169], v[238:239], 0, s[18:19]
	s_mov_b32 m0, s60
	s_nop 0
	global_load_lds_dwordx4 v[168:169], off
	v_lshl_add_u64 v[168:169], v[240:241], 0, s[18:19]
	s_mov_b32 m0, s61
	s_nop 0
	global_load_lds_dwordx4 v[168:169], off
	s_waitcnt vmcnt(8)
	s_waitcnt lgkmcnt(0)
	s_barrier
	s_setprio 1
	s_waitcnt lgkmcnt(0)
	v_mfma_f32_16x16x32_bf16 v[64:67], v[142:145], v[194:197], v[64:67]
	v_mfma_f32_16x16x32_bf16 v[64:67], v[146:149], v[208:211], v[64:67]
	v_mfma_f32_16x16x32_bf16 v[60:63], v[160:163], v[194:197], v[60:63]
	v_mfma_f32_16x16x32_bf16 v[60:63], v[164:167], v[208:211], v[60:63]
	v_mfma_f32_16x16x32_bf16 v[48:51], v[142:145], v[212:215], v[48:51]
	v_mfma_f32_16x16x32_bf16 v[48:51], v[146:149], v[216:219], v[48:51]
	v_mfma_f32_16x16x32_bf16 v[44:47], v[160:163], v[212:215], v[44:47]
	v_mfma_f32_16x16x32_bf16 v[44:47], v[164:167], v[216:219], v[44:47]
	v_mfma_f32_16x16x32_bf16 v[32:35], v[142:145], v[220:223], v[32:35]
	v_mfma_f32_16x16x32_bf16 v[32:35], v[146:149], v[224:227], v[32:35]
	v_mfma_f32_16x16x32_bf16 v[28:31], v[160:163], v[220:223], v[28:31]
	v_mfma_f32_16x16x32_bf16 v[28:31], v[164:167], v[224:227], v[28:31]
	v_mfma_f32_16x16x32_bf16 v[16:19], v[142:145], v[228:231], v[16:19]
	v_mfma_f32_16x16x32_bf16 v[16:19], v[146:149], v[232:235], v[16:19]
	v_mfma_f32_16x16x32_bf16 v[12:15], v[160:163], v[228:231], v[12:15]
	v_mfma_f32_16x16x32_bf16 v[12:15], v[164:167], v[232:235], v[12:15]
	s_setprio 0
	s_setprio 1
	v_mfma_f32_16x16x32_bf16 v[56:59], v[178:181], v[194:197], v[56:59]
	v_mfma_f32_16x16x32_bf16 v[56:59], v[182:185], v[208:211], v[56:59]
	v_mfma_f32_16x16x32_bf16 v[52:55], v[186:189], v[194:197], v[52:55]
	v_mfma_f32_16x16x32_bf16 v[52:55], v[190:193], v[208:211], v[52:55]
	v_mfma_f32_16x16x32_bf16 v[40:43], v[178:181], v[212:215], v[40:43]
	v_mfma_f32_16x16x32_bf16 v[40:43], v[182:185], v[216:219], v[40:43]
	v_mfma_f32_16x16x32_bf16 v[36:39], v[186:189], v[212:215], v[36:39]
	v_mfma_f32_16x16x32_bf16 v[36:39], v[190:193], v[216:219], v[36:39]
	v_mfma_f32_16x16x32_bf16 v[24:27], v[178:181], v[220:223], v[24:27]
	v_mfma_f32_16x16x32_bf16 v[24:27], v[182:185], v[224:227], v[24:27]
	v_mfma_f32_16x16x32_bf16 v[20:23], v[186:189], v[220:223], v[20:23]
	v_mfma_f32_16x16x32_bf16 v[20:23], v[190:193], v[224:227], v[20:23]
	v_mfma_f32_16x16x32_bf16 v[8:11], v[178:181], v[228:231], v[8:11]
	v_mfma_f32_16x16x32_bf16 v[8:11], v[182:185], v[232:235], v[8:11]
	v_mfma_f32_16x16x32_bf16 v[4:7], v[186:189], v[228:231], v[4:7]
	v_mfma_f32_16x16x32_bf16 v[4:7], v[190:193], v[232:235], v[4:7]
	s_setprio 0
	s_barrier
	s_add_i32 s33, s33, 2
	s_add_u32 s26, s26, 0x100
	s_addc_u32 s27, s27, 0
	s_add_u32 s22, s22, 0x100
	s_addc_u32 s29, s29, 0
	s_cmp_gt_u32 s33, 29
	s_cbranch_scc0 .LBB0_198
	s_and_b64 vcc, exec, s[12:13]
	s_cbranch_vccz .LBB0_201
	s_barrier

.LBB0_708:
	s_add_u32 s42, s40, 0xfff80080
	s_addc_u32 s43, s41, -1
	s_add_i32 s61, 0, 0x10000
	s_cmp_eq_u32 s55, 28
	s_cselect_b32 s45, s27, s43
	s_cselect_b32 s44, s51, s42
	v_add_u32_e32 v142, s61, v144
	s_cselect_b32 s43, s13, s54
	s_cselect_b32 s42, s52, s53
	s_add_i32 s65, 0, 0x14000
	ds_read_b128 v[148:151], v142
	ds_read_b128 v[152:155], v142 offset:1024
	ds_read_b128 v[156:159], v142 offset:2048
	ds_read_b128 v[160:163], v142 offset:3072
	v_add_u32_e32 v142, s65, v144
	ds_read_b128 v[164:167], v142
	ds_read_b128 v[178:181], v142 offset:1024
	ds_read_b128 v[182:185], v142 offset:2048
	ds_read_b128 v[186:189], v142 offset:3072
	v_lshl_add_u64 v[142:143], s[40:41], 0, v[138:139]
	s_add_i32 m0, s21, 0xc000
	ds_read_b128 v[190:193], v146
	ds_read_b128 v[194:197], v146 offset:1024
	ds_read_b128 v[208:211], v146 offset:2048
	ds_read_b128 v[212:215], v146 offset:3072
	ds_read_b128 v[216:219], v146 offset:4096
	ds_read_b128 v[220:223], v146 offset:5120
	ds_read_b128 v[224:227], v146 offset:6144
	ds_read_b128 v[228:231], v146 offset:7168
	global_load_lds_dwordx4 v[142:143], off
	v_lshl_add_u64 v[142:143], s[40:41], 0, v[140:141]
	s_add_i32 m0, s21, 0xe000
	s_nop 0
	global_load_lds_dwordx4 v[142:143], off
	s_waitcnt vmcnt(8)
	s_waitcnt lgkmcnt(0)
	s_barrier
	s_setprio 1
	s_waitcnt lgkmcnt(0)
	v_mfma_f32_16x16x32_bf16 v[128:131], v[148:151], v[190:193], v[128:131]
	v_mfma_f32_16x16x32_bf16 v[128:131], v[152:155], v[194:197], v[128:131]
	v_mfma_f32_16x16x32_bf16 v[124:127], v[156:159], v[190:193], v[124:127]
	v_mfma_f32_16x16x32_bf16 v[124:127], v[160:163], v[194:197], v[124:127]
	v_mfma_f32_16x16x32_bf16 v[120:123], v[148:151], v[208:211], v[120:123]
	v_mfma_f32_16x16x32_bf16 v[120:123], v[152:155], v[212:215], v[120:123]
	v_mfma_f32_16x16x32_bf16 v[112:115], v[156:159], v[208:211], v[112:115]
	v_mfma_f32_16x16x32_bf16 v[112:115], v[160:163], v[212:215], v[112:115]
	v_mfma_f32_16x16x32_bf16 v[104:107], v[148:151], v[216:219], v[104:107]
	v_mfma_f32_16x16x32_bf16 v[104:107], v[152:155], v[220:223], v[104:107]
	v_mfma_f32_16x16x32_bf16 v[96:99], v[156:159], v[216:219], v[96:99]
	v_mfma_f32_16x16x32_bf16 v[96:99], v[160:163], v[220:223], v[96:99]
	v_mfma_f32_16x16x32_bf16 v[88:91], v[148:151], v[224:227], v[88:91]
	v_mfma_f32_16x16x32_bf16 v[88:91], v[152:155], v[228:231], v[88:91]
	v_mfma_f32_16x16x32_bf16 v[80:83], v[156:159], v[224:227], v[80:83]
	v_mfma_f32_16x16x32_bf16 v[80:83], v[160:163], v[228:231], v[80:83]
	s_setprio 0
	s_setprio 1
	v_mfma_f32_16x16x32_bf16 v[116:119], v[164:167], v[190:193], v[116:119]
	v_mfma_f32_16x16x32_bf16 v[116:119], v[178:181], v[194:197], v[116:119]
	v_mfma_f32_16x16x32_bf16 v[108:111], v[182:185], v[190:193], v[108:111]
	v_mfma_f32_16x16x32_bf16 v[108:111], v[186:189], v[194:197], v[108:111]
	v_mfma_f32_16x16x32_bf16 v[100:103], v[164:167], v[208:211], v[100:103]
	v_mfma_f32_16x16x32_bf16 v[100:103], v[178:181], v[212:215], v[100:103]
	v_mfma_f32_16x16x32_bf16 v[92:95], v[182:185], v[208:211], v[92:95]
	v_mfma_f32_16x16x32_bf16 v[92:95], v[186:189], v[212:215], v[92:95]
	v_mfma_f32_16x16x32_bf16 v[84:87], v[164:167], v[216:219], v[84:87]
	v_mfma_f32_16x16x32_bf16 v[84:87], v[178:181], v[220:223], v[84:87]
	v_mfma_f32_16x16x32_bf16 v[76:79], v[182:185], v[216:219], v[76:79]
	v_mfma_f32_16x16x32_bf16 v[76:79], v[186:189], v[220:223], v[76:79]
	v_mfma_f32_16x16x32_bf16 v[72:75], v[164:167], v[224:227], v[72:75]
	v_mfma_f32_16x16x32_bf16 v[72:75], v[178:181], v[228:231], v[72:75]
	v_mfma_f32_16x16x32_bf16 v[68:71], v[182:185], v[224:227], v[68:71]
	v_mfma_f32_16x16x32_bf16 v[68:71], v[186:189], v[228:231], v[68:71]
	s_setprio 0
	s_barrier
	s_add_i32 s61, s61, s11
	v_lshl_add_u64 v[142:143], s[42:43], 0, v[2:3]
	s_mov_b32 m0, s61
	ds_read_b128 v[190:193], v146 offset:16384
	ds_read_b128 v[194:197], v146 offset:17408
	ds_read_b128 v[208:211], v146 offset:18432
	ds_read_b128 v[212:215], v146 offset:19456
	ds_read_b128 v[216:219], v146 offset:20480
	ds_read_b128 v[220:223], v146 offset:21504
	ds_read_b128 v[224:227], v146 offset:22528
	ds_read_b128 v[228:231], v146 offset:23552
	global_load_lds_dwordx4 v[142:143], off
	s_add_i32 m0, s61, 0x2000
	s_add_u32 s62, s42, 0x80000
	v_lshl_add_u64 v[168:169], s[42:43], 0, v[136:137]
	s_addc_u32 s63, s43, 0
	s_add_i32 s61, s65, s11
	global_load_lds_dwordx4 v[168:169], off
	v_lshl_add_u64 v[232:233], s[62:63], 0, v[2:3]
	s_mov_b32 m0, s61
	v_lshl_add_u64 v[234:235], s[44:45], 0, v[134:135]
	global_load_lds_dwordx4 v[232:233], off
	v_lshl_add_u64 v[232:233], s[62:63], 0, v[136:137]
	s_add_i32 m0, s61, 0x2000
	s_nop 0
	global_load_lds_dwordx4 v[232:233], off
	v_lshl_add_u64 v[232:233], s[44:45], 0, v[132:133]
	s_mov_b32 m0, s21
	s_nop 0
	global_load_lds_dwordx4 v[232:233], off
	s_mov_b32 m0, s22
	s_nop 0
	global_load_lds_dwordx4 v[234:235], off
	s_waitcnt vmcnt(8)
	s_waitcnt lgkmcnt(0)
	s_barrier
	s_setprio 1
	s_waitcnt lgkmcnt(0)
	v_mfma_f32_16x16x32_bf16 v[64:67], v[148:151], v[190:193], v[64:67]
	v_mfma_f32_16x16x32_bf16 v[64:67], v[152:155], v[194:197], v[64:67]
	v_mfma_f32_16x16x32_bf16 v[60:63], v[156:159], v[190:193], v[60:63]
	v_mfma_f32_16x16x32_bf16 v[60:63], v[160:163], v[194:197], v[60:63]
	v_mfma_f32_16x16x32_bf16 v[56:59], v[148:151], v[208:211], v[56:59]
	v_mfma_f32_16x16x32_bf16 v[56:59], v[152:155], v[212:215], v[56:59]
	v_mfma_f32_16x16x32_bf16 v[48:51], v[156:159], v[208:211], v[48:51]
	v_mfma_f32_16x16x32_bf16 v[48:51], v[160:163], v[212:215], v[48:51]
	v_mfma_f32_16x16x32_bf16 v[40:43], v[148:151], v[216:219], v[40:43]
	v_mfma_f32_16x16x32_bf16 v[40:43], v[152:155], v[220:223], v[40:43]
	v_mfma_f32_16x16x32_bf16 v[32:35], v[156:159], v[216:219], v[32:35]
	v_mfma_f32_16x16x32_bf16 v[32:35], v[160:163], v[220:223], v[32:35]
	v_mfma_f32_16x16x32_bf16 v[24:27], v[148:151], v[224:227], v[24:27]
	v_mfma_f32_16x16x32_bf16 v[24:27], v[152:155], v[228:231], v[24:27]
	v_mfma_f32_16x16x32_bf16 v[16:19], v[156:159], v[224:227], v[16:19]
	v_mfma_f32_16x16x32_bf16 v[16:19], v[160:163], v[228:231], v[16:19]
	s_setprio 0
	s_setprio 1
	v_mfma_f32_16x16x32_bf16 v[52:55], v[164:167], v[190:193], v[52:55]
	v_mfma_f32_16x16x32_bf16 v[52:55], v[178:181], v[194:197], v[52:55]
	v_mfma_f32_16x16x32_bf16 v[44:47], v[182:185], v[190:193], v[44:47]
	v_mfma_f32_16x16x32_bf16 v[44:47], v[186:189], v[194:197], v[44:47]
	v_mfma_f32_16x16x32_bf16 v[36:39], v[164:167], v[208:211], v[36:39]
	v_mfma_f32_16x16x32_bf16 v[36:39], v[178:181], v[212:215], v[36:39]
	v_mfma_f32_16x16x32_bf16 v[28:31], v[182:185], v[208:211], v[28:31]
	v_mfma_f32_16x16x32_bf16 v[28:31], v[186:189], v[212:215], v[28:31]
	v_mfma_f32_16x16x32_bf16 v[20:23], v[164:167], v[216:219], v[20:23]
	v_mfma_f32_16x16x32_bf16 v[20:23], v[178:181], v[220:223], v[20:23]
	v_mfma_f32_16x16x32_bf16 v[12:15], v[182:185], v[216:219], v[12:15]
	v_mfma_f32_16x16x32_bf16 v[12:15], v[186:189], v[220:223], v[12:15]
	v_mfma_f32_16x16x32_bf16 v[8:11], v[164:167], v[224:227], v[8:11]
	v_mfma_f32_16x16x32_bf16 v[8:11], v[178:181], v[228:231], v[8:11]
	v_mfma_f32_16x16x32_bf16 v[4:7], v[182:185], v[224:227], v[4:7]
	v_mfma_f32_16x16x32_bf16 v[4:7], v[186:189], v[228:231], v[4:7]
	s_setprio 0
	s_barrier
	s_add_i32 s61, 0, 0x18000
	v_add_u32_e32 v147, s61, v144
	s_add_i32 s62, 0, 0x1c000
	ds_read_b128 v[148:151], v147
	ds_read_b128 v[152:155], v147 offset:1024
	ds_read_b128 v[156:159], v147 offset:2048
	ds_read_b128 v[160:163], v147 offset:3072
	v_add_u32_e32 v147, s62, v144
	ds_read_b128 v[164:167], v147
	ds_read_b128 v[178:181], v147 offset:1024
	ds_read_b128 v[182:185], v147 offset:2048
	ds_read_b128 v[186:189], v147 offset:3072
	s_add_u32 s44, s44, 0x80000
	s_addc_u32 s45, s45, 0
	s_mov_b32 m0, s33
	v_lshl_add_u64 v[236:237], s[44:45], 0, v[132:133]
	ds_read_b128 v[190:193], v146 offset:32768
	ds_read_b128 v[194:197], v146 offset:33792
	ds_read_b128 v[208:211], v146 offset:34816
	ds_read_b128 v[212:215], v146 offset:35840
	ds_read_b128 v[216:219], v146 offset:36864
	ds_read_b128 v[220:223], v146 offset:37888
	ds_read_b128 v[224:227], v146 offset:38912
	ds_read_b128 v[228:231], v146 offset:39936
	global_load_lds_dwordx4 v[236:237], off
	v_lshl_add_u64 v[236:237], s[44:45], 0, v[134:135]
	s_mov_b32 m0, s46
	s_nop 0
	global_load_lds_dwordx4 v[236:237], off
	s_waitcnt vmcnt(8)
	s_waitcnt lgkmcnt(0)
	s_barrier
	s_setprio 1
	s_waitcnt lgkmcnt(0)
	v_mfma_f32_16x16x32_bf16 v[128:131], v[148:151], v[190:193], v[128:131]
	v_mfma_f32_16x16x32_bf16 v[128:131], v[152:155], v[194:197], v[128:131]
	v_mfma_f32_16x16x32_bf16 v[124:127], v[156:159], v[190:193], v[124:127]
	v_mfma_f32_16x16x32_bf16 v[124:127], v[160:163], v[194:197], v[124:127]
	v_mfma_f32_16x16x32_bf16 v[120:123], v[148:151], v[208:211], v[120:123]
	v_mfma_f32_16x16x32_bf16 v[120:123], v[152:155], v[212:215], v[120:123]
	v_mfma_f32_16x16x32_bf16 v[112:115], v[156:159], v[208:211], v[112:115]
	v_mfma_f32_16x16x32_bf16 v[112:115], v[160:163], v[212:215], v[112:115]
	v_mfma_f32_16x16x32_bf16 v[104:107], v[148:151], v[216:219], v[104:107]
	v_mfma_f32_16x16x32_bf16 v[104:107], v[152:155], v[220:223], v[104:107]
	v_mfma_f32_16x16x32_bf16 v[96:99], v[156:159], v[216:219], v[96:99]
	v_mfma_f32_16x16x32_bf16 v[96:99], v[160:163], v[220:223], v[96:99]
	v_mfma_f32_16x16x32_bf16 v[88:91], v[148:151], v[224:227], v[88:91]
	v_mfma_f32_16x16x32_bf16 v[88:91], v[152:155], v[228:231], v[88:91]
	v_mfma_f32_16x16x32_bf16 v[80:83], v[156:159], v[224:227], v[80:83]
	v_mfma_f32_16x16x32_bf16 v[80:83], v[160:163], v[228:231], v[80:83]
	s_setprio 0
	s_setprio 1
	v_mfma_f32_16x16x32_bf16 v[116:119], v[164:167], v[190:193], v[116:119]
	v_mfma_f32_16x16x32_bf16 v[116:119], v[178:181], v[194:197], v[116:119]
	v_mfma_f32_16x16x32_bf16 v[108:111], v[182:185], v[190:193], v[108:111]
	v_mfma_f32_16x16x32_bf16 v[108:111], v[186:189], v[194:197], v[108:111]
	v_mfma_f32_16x16x32_bf16 v[100:103], v[164:167], v[208:211], v[100:103]
	v_mfma_f32_16x16x32_bf16 v[100:103], v[178:181], v[212:215], v[100:103]
	v_mfma_f32_16x16x32_bf16 v[92:95], v[182:185], v[208:211], v[92:95]
	v_mfma_f32_16x16x32_bf16 v[92:95], v[186:189], v[212:215], v[92:95]
	v_mfma_f32_16x16x32_bf16 v[84:87], v[164:167], v[216:219], v[84:87]
	v_mfma_f32_16x16x32_bf16 v[84:87], v[178:181], v[220:223], v[84:87]
	v_mfma_f32_16x16x32_bf16 v[76:79], v[182:185], v[216:219], v[76:79]
	v_mfma_f32_16x16x32_bf16 v[76:79], v[186:189], v[220:223], v[76:79]
	v_mfma_f32_16x16x32_bf16 v[72:75], v[164:167], v[224:227], v[72:75]
	v_mfma_f32_16x16x32_bf16 v[72:75], v[178:181], v[228:231], v[72:75]
	v_mfma_f32_16x16x32_bf16 v[68:71], v[182:185], v[224:227], v[68:71]
	v_mfma_f32_16x16x32_bf16 v[68:71], v[186:189], v[228:231], v[68:71]
	s_setprio 0
	s_barrier
	s_add_i32 s44, s61, s11
	v_lshl_add_u64 v[142:143], v[142:143], 0, s[18:19]
	s_mov_b32 m0, s44
	ds_read_b128 v[190:193], v146 offset:49152
	ds_read_b128 v[194:197], v146 offset:50176
	ds_read_b128 v[208:211], v146 offset:51200
	ds_read_b128 v[212:215], v146 offset:52224
	ds_read_b128 v[216:219], v146 offset:53248
	ds_read_b128 v[220:223], v146 offset:54272
	ds_read_b128 v[224:227], v146 offset:55296
	ds_read_b128 v[228:231], v146 offset:56320
	global_load_lds_dwordx4 v[142:143], off
	s_add_i32 m0, s44, 0x2000
	s_add_u32 s42, s42, 0x80080
	v_lshl_add_u64 v[142:143], v[168:169], 0, s[18:19]
	s_addc_u32 s43, s43, 0
	s_add_i32 s44, s62, s11
	global_load_lds_dwordx4 v[142:143], off
	v_lshl_add_u64 v[142:143], s[42:43], 0, v[2:3]
	s_mov_b32 m0, s44
	s_nop 0
	global_load_lds_dwordx4 v[142:143], off
	v_lshl_add_u64 v[142:143], s[42:43], 0, v[136:137]
	s_add_i32 m0, s44, 0x2000
	s_nop 0
	global_load_lds_dwordx4 v[142:143], off
	v_lshl_add_u64 v[142:143], v[232:233], 0, s[18:19]
	s_mov_b32 m0, s47
	s_nop 0
	global_load_lds_dwordx4 v[142:143], off
	v_lshl_add_u64 v[142:143], v[234:235], 0, s[18:19]
	s_mov_b32 m0, s48
	s_nop 0
	global_load_lds_dwordx4 v[142:143], off
	s_waitcnt vmcnt(8)
	s_waitcnt lgkmcnt(0)
	s_barrier
	s_setprio 1
	s_waitcnt lgkmcnt(0)
	v_mfma_f32_16x16x32_bf16 v[64:67], v[148:151], v[190:193], v[64:67]
	v_mfma_f32_16x16x32_bf16 v[64:67], v[152:155], v[194:197], v[64:67]
	v_mfma_f32_16x16x32_bf16 v[60:63], v[156:159], v[190:193], v[60:63]
	v_mfma_f32_16x16x32_bf16 v[60:63], v[160:163], v[194:197], v[60:63]
	v_mfma_f32_16x16x32_bf16 v[56:59], v[148:151], v[208:211], v[56:59]
	v_mfma_f32_16x16x32_bf16 v[56:59], v[152:155], v[212:215], v[56:59]
	v_mfma_f32_16x16x32_bf16 v[48:51], v[156:159], v[208:211], v[48:51]
	v_mfma_f32_16x16x32_bf16 v[48:51], v[160:163], v[212:215], v[48:51]
	v_mfma_f32_16x16x32_bf16 v[40:43], v[148:151], v[216:219], v[40:43]
	v_mfma_f32_16x16x32_bf16 v[40:43], v[152:155], v[220:223], v[40:43]
	v_mfma_f32_16x16x32_bf16 v[32:35], v[156:159], v[216:219], v[32:35]
	v_mfma_f32_16x16x32_bf16 v[32:35], v[160:163], v[220:223], v[32:35]
	v_mfma_f32_16x16x32_bf16 v[24:27], v[148:151], v[224:227], v[24:27]
	v_mfma_f32_16x16x32_bf16 v[24:27], v[152:155], v[228:231], v[24:27]
	v_mfma_f32_16x16x32_bf16 v[16:19], v[156:159], v[224:227], v[16:19]
	v_mfma_f32_16x16x32_bf16 v[16:19], v[160:163], v[228:231], v[16:19]
	s_setprio 0
	s_setprio 1
	v_mfma_f32_16x16x32_bf16 v[52:55], v[164:167], v[190:193], v[52:55]
	v_mfma_f32_16x16x32_bf16 v[52:55], v[178:181], v[194:197], v[52:55]
	v_mfma_f32_16x16x32_bf16 v[44:47], v[182:185], v[190:193], v[44:47]
	v_mfma_f32_16x16x32_bf16 v[44:47], v[186:189], v[194:197], v[44:47]
	v_mfma_f32_16x16x32_bf16 v[36:39], v[164:167], v[208:211], v[36:39]
	v_mfma_f32_16x16x32_bf16 v[36:39], v[178:181], v[212:215], v[36:39]
	v_mfma_f32_16x16x32_bf16 v[28:31], v[182:185], v[208:211], v[28:31]
	v_mfma_f32_16x16x32_bf16 v[28:31], v[186:189], v[212:215], v[28:31]
	v_mfma_f32_16x16x32_bf16 v[20:23], v[164:167], v[216:219], v[20:23]
	v_mfma_f32_16x16x32_bf16 v[20:23], v[178:181], v[220:223], v[20:23]
	v_mfma_f32_16x16x32_bf16 v[12:15], v[182:185], v[216:219], v[12:15]
	v_mfma_f32_16x16x32_bf16 v[12:15], v[186:189], v[220:223], v[12:15]
	v_mfma_f32_16x16x32_bf16 v[8:11], v[164:167], v[224:227], v[8:11]
	v_mfma_f32_16x16x32_bf16 v[8:11], v[178:181], v[228:231], v[8:11]
	v_mfma_f32_16x16x32_bf16 v[4:7], v[182:185], v[224:227], v[4:7]
	v_mfma_f32_16x16x32_bf16 v[4:7], v[186:189], v[228:231], v[4:7]
	s_setprio 0
	s_barrier
	s_add_i32 s55, s55, 2
	s_add_u32 s40, s40, 0x100
	s_addc_u32 s41, s41, 0
	s_add_u32 s53, s53, 0x100
	s_addc_u32 s54, s54, 0
	s_cmp_gt_u32 s55, 29
	s_cbranch_scc0 .LBB0_708
	s_and_b64 vcc, exec, s[8:9]
	s_cbranch_vccz .LBB0_711
	s_barrier

.LBB0_722:
	s_add_u32 s47, s38, s46
	s_addc_u32 s52, s39, 0
	s_add_u32 s50, s47, 0x100
	s_addc_u32 s51, s52, 0
	s_and_b64 s[48:49], s[44:45], exec
	s_cselect_b32 s49, s5, s51
	s_cselect_b32 s48, s70, s50
	s_add_u32 s46, s40, s46
	s_addc_u32 s50, s41, 0
	s_add_u32 s46, s46, 0x100
	s_addc_u32 s50, s50, 0
	s_add_i32 s83, 0, 0x10000
	s_and_b64 s[44:45], s[44:45], exec
	s_cselect_b32 s51, s71, s50
	s_cselect_b32 s50, s72, s46
	s_add_i32 s45, 0, 0x14000
	s_add_u32 s54, s47, 0x80080
	s_addc_u32 s55, s52, 0
	s_add_i32 s82, s83, s21
	s_add_i32 m0, s33, 0xc000
	s_add_i32 s85, s33, 0xe000
	s_add_i32 s77, s82, 0x2000
	v_add_u32_e32 v2, s83, v136
	s_add_u32 s52, s50, 0x80000
	ds_read_b128 v[140:143], v2
	ds_read_b128 v[144:147], v2 offset:1024
	ds_read_b128 v[148:151], v2 offset:2048
	ds_read_b128 v[152:155], v2 offset:3072
	v_add_u32_e32 v2, s45, v136
	s_addc_u32 s53, s51, 0
	s_add_i32 s81, s45, s21
	ds_read_b128 v[156:159], v2
	ds_read_b128 v[160:163], v2 offset:1024
	ds_read_b128 v[164:167], v2 offset:2048
	ds_read_b128 v[178:181], v2 offset:3072
	s_add_i32 s80, s81, 0x2000
	s_add_i32 s76, 0, 0x18000
	s_add_i32 s75, 0, 0x1c000
	s_add_u32 s46, s48, 0x80000
	s_addc_u32 s47, s49, 0
	s_add_i32 s74, s76, s21
	s_add_i32 s73, s74, 0x2000
	s_add_u32 s44, s50, 0x80080
	s_addc_u32 s45, s51, 0
	s_add_i32 s84, s75, s21
	s_add_i32 s83, s84, 0x2000
	v_lshl_add_u64 v[168:169], s[54:55], 0, v[134:135]
	ds_read_b128 v[182:185], v138
	ds_read_b128 v[186:189], v138 offset:1024
	ds_read_b128 v[190:193], v138 offset:2048
	ds_read_b128 v[194:197], v138 offset:3072
	ds_read_b128 v[208:211], v138 offset:4096
	ds_read_b128 v[212:215], v138 offset:5120
	ds_read_b128 v[216:219], v138 offset:6144
	ds_read_b128 v[220:223], v138 offset:7168
	global_load_lds_dwordx4 v[168:169], off
	v_lshl_add_u64 v[168:169], s[54:55], 0, v[132:133]
	s_mov_b32 m0, s85
	s_nop 0
	global_load_lds_dwordx4 v[168:169], off
	s_waitcnt vmcnt(8)
	s_waitcnt lgkmcnt(0)
	s_barrier
	s_setprio 1
	s_waitcnt lgkmcnt(0)
	v_mfma_f32_16x16x32_bf16 v[128:131], v[140:143], v[182:185], v[128:131]
	v_mfma_f32_16x16x32_bf16 v[128:131], v[144:147], v[186:189], v[128:131]
	v_mfma_f32_16x16x32_bf16 v[124:127], v[148:151], v[182:185], v[124:127]
	v_mfma_f32_16x16x32_bf16 v[124:127], v[152:155], v[186:189], v[124:127]
	v_mfma_f32_16x16x32_bf16 v[120:123], v[140:143], v[190:193], v[120:123]
	v_mfma_f32_16x16x32_bf16 v[120:123], v[144:147], v[194:197], v[120:123]
	v_mfma_f32_16x16x32_bf16 v[116:119], v[148:151], v[190:193], v[116:119]
	v_mfma_f32_16x16x32_bf16 v[116:119], v[152:155], v[194:197], v[116:119]
	v_mfma_f32_16x16x32_bf16 v[108:111], v[140:143], v[208:211], v[108:111]
	v_mfma_f32_16x16x32_bf16 v[108:111], v[144:147], v[212:215], v[108:111]
	v_mfma_f32_16x16x32_bf16 v[100:103], v[148:151], v[208:211], v[100:103]
	v_mfma_f32_16x16x32_bf16 v[100:103], v[152:155], v[212:215], v[100:103]
	v_mfma_f32_16x16x32_bf16 v[92:95], v[140:143], v[216:219], v[92:95]
	v_mfma_f32_16x16x32_bf16 v[92:95], v[144:147], v[220:223], v[92:95]
	v_mfma_f32_16x16x32_bf16 v[84:87], v[148:151], v[216:219], v[84:87]
	v_mfma_f32_16x16x32_bf16 v[84:87], v[152:155], v[220:223], v[84:87]
	s_setprio 0
	s_setprio 1
	v_mfma_f32_16x16x32_bf16 v[112:115], v[156:159], v[182:185], v[112:115]
	v_mfma_f32_16x16x32_bf16 v[112:115], v[160:163], v[186:189], v[112:115]
	v_mfma_f32_16x16x32_bf16 v[104:107], v[164:167], v[182:185], v[104:107]
	v_mfma_f32_16x16x32_bf16 v[104:107], v[178:181], v[186:189], v[104:107]
	v_mfma_f32_16x16x32_bf16 v[96:99], v[156:159], v[190:193], v[96:99]
	v_mfma_f32_16x16x32_bf16 v[96:99], v[160:163], v[194:197], v[96:99]
	v_mfma_f32_16x16x32_bf16 v[88:91], v[164:167], v[190:193], v[88:91]
	v_mfma_f32_16x16x32_bf16 v[88:91], v[178:181], v[194:197], v[88:91]
	v_mfma_f32_16x16x32_bf16 v[80:83], v[156:159], v[208:211], v[80:83]
	v_mfma_f32_16x16x32_bf16 v[80:83], v[160:163], v[212:215], v[80:83]
	v_mfma_f32_16x16x32_bf16 v[76:79], v[164:167], v[208:211], v[76:79]
	v_mfma_f32_16x16x32_bf16 v[76:79], v[178:181], v[212:215], v[76:79]
	v_mfma_f32_16x16x32_bf16 v[72:75], v[156:159], v[216:219], v[72:75]
	v_mfma_f32_16x16x32_bf16 v[72:75], v[160:163], v[220:223], v[72:75]
	v_mfma_f32_16x16x32_bf16 v[68:71], v[164:167], v[216:219], v[68:71]
	v_mfma_f32_16x16x32_bf16 v[68:71], v[178:181], v[220:223], v[68:71]
	s_setprio 0
	s_barrier
	s_mov_b32 m0, s82
	v_lshl_add_u64 v[168:169], s[50:51], 0, v[134:135]
	ds_read_b128 v[182:185], v138 offset:16384
	ds_read_b128 v[186:189], v138 offset:17408
	ds_read_b128 v[190:193], v138 offset:18432
	ds_read_b128 v[194:197], v138 offset:19456
	ds_read_b128 v[208:211], v138 offset:20480
	ds_read_b128 v[212:215], v138 offset:21504
	ds_read_b128 v[216:219], v138 offset:22528
	ds_read_b128 v[220:223], v138 offset:23552
	global_load_lds_dwordx4 v[168:169], off
	v_lshl_add_u64 v[224:225], s[50:51], 0, v[132:133]
	s_mov_b32 m0, s77
	v_lshl_add_u64 v[226:227], s[52:53], 0, v[134:135]
	global_load_lds_dwordx4 v[224:225], off
	s_mov_b32 m0, s81
	v_lshl_add_u64 v[228:229], s[48:49], 0, v[132:133]
	global_load_lds_dwordx4 v[226:227], off
	v_lshl_add_u64 v[226:227], s[52:53], 0, v[132:133]
	s_mov_b32 m0, s80
	s_nop 0
	global_load_lds_dwordx4 v[226:227], off
	v_lshl_add_u64 v[226:227], s[48:49], 0, v[134:135]
	s_mov_b32 m0, s33
	s_nop 0
	global_load_lds_dwordx4 v[226:227], off
	s_mov_b32 m0, s61
	s_nop 0
	global_load_lds_dwordx4 v[228:229], off
	s_waitcnt vmcnt(8)
	s_waitcnt lgkmcnt(0)
	s_barrier
	s_setprio 1
	s_waitcnt lgkmcnt(0)
	v_mfma_f32_16x16x32_bf16 v[64:67], v[140:143], v[182:185], v[64:67]
	v_mfma_f32_16x16x32_bf16 v[64:67], v[144:147], v[186:189], v[64:67]
	v_mfma_f32_16x16x32_bf16 v[60:63], v[148:151], v[182:185], v[60:63]
	v_mfma_f32_16x16x32_bf16 v[60:63], v[152:155], v[186:189], v[60:63]
	v_mfma_f32_16x16x32_bf16 v[56:59], v[140:143], v[190:193], v[56:59]
	v_mfma_f32_16x16x32_bf16 v[56:59], v[144:147], v[194:197], v[56:59]
	v_mfma_f32_16x16x32_bf16 v[52:55], v[148:151], v[190:193], v[52:55]
	v_mfma_f32_16x16x32_bf16 v[52:55], v[152:155], v[194:197], v[52:55]
	v_mfma_f32_16x16x32_bf16 v[40:43], v[140:143], v[208:211], v[40:43]
	v_mfma_f32_16x16x32_bf16 v[40:43], v[144:147], v[212:215], v[40:43]
	v_mfma_f32_16x16x32_bf16 v[36:39], v[148:151], v[208:211], v[36:39]
	v_mfma_f32_16x16x32_bf16 v[36:39], v[152:155], v[212:215], v[36:39]
	v_mfma_f32_16x16x32_bf16 v[24:27], v[140:143], v[216:219], v[24:27]
	v_mfma_f32_16x16x32_bf16 v[24:27], v[144:147], v[220:223], v[24:27]
	v_mfma_f32_16x16x32_bf16 v[20:23], v[148:151], v[216:219], v[20:23]
	v_mfma_f32_16x16x32_bf16 v[20:23], v[152:155], v[220:223], v[20:23]
	s_setprio 0
	s_setprio 1
	v_mfma_f32_16x16x32_bf16 v[48:51], v[156:159], v[182:185], v[48:51]
	v_mfma_f32_16x16x32_bf16 v[48:51], v[160:163], v[186:189], v[48:51]
	v_mfma_f32_16x16x32_bf16 v[44:47], v[164:167], v[182:185], v[44:47]
	v_mfma_f32_16x16x32_bf16 v[44:47], v[178:181], v[186:189], v[44:47]
	v_mfma_f32_16x16x32_bf16 v[32:35], v[156:159], v[190:193], v[32:35]
	v_mfma_f32_16x16x32_bf16 v[32:35], v[160:163], v[194:197], v[32:35]
	v_mfma_f32_16x16x32_bf16 v[28:31], v[164:167], v[190:193], v[28:31]
	v_mfma_f32_16x16x32_bf16 v[28:31], v[178:181], v[194:197], v[28:31]
	v_mfma_f32_16x16x32_bf16 v[16:19], v[156:159], v[208:211], v[16:19]
	v_mfma_f32_16x16x32_bf16 v[16:19], v[160:163], v[212:215], v[16:19]
	v_mfma_f32_16x16x32_bf16 v[12:15], v[164:167], v[208:211], v[12:15]
	v_mfma_f32_16x16x32_bf16 v[12:15], v[178:181], v[212:215], v[12:15]
	v_mfma_f32_16x16x32_bf16 v[8:11], v[156:159], v[216:219], v[8:11]
	v_mfma_f32_16x16x32_bf16 v[8:11], v[160:163], v[220:223], v[8:11]
	v_mfma_f32_16x16x32_bf16 v[4:7], v[164:167], v[216:219], v[4:7]
	v_mfma_f32_16x16x32_bf16 v[4:7], v[178:181], v[220:223], v[4:7]
	s_setprio 0
	s_barrier
	v_add_u32_e32 v2, s76, v136
	ds_read_b128 v[140:143], v2
	ds_read_b128 v[144:147], v2 offset:1024
	ds_read_b128 v[148:151], v2 offset:2048
	ds_read_b128 v[152:155], v2 offset:3072
	v_add_u32_e32 v2, s75, v136
	ds_read_b128 v[156:159], v2
	ds_read_b128 v[160:163], v2 offset:1024
	ds_read_b128 v[164:167], v2 offset:2048
	ds_read_b128 v[178:181], v2 offset:3072
	s_mov_b32 m0, s62
	v_lshl_add_u64 v[230:231], s[46:47], 0, v[134:135]
	ds_read_b128 v[182:185], v138 offset:32768
	ds_read_b128 v[186:189], v138 offset:33792
	ds_read_b128 v[190:193], v138 offset:34816
	ds_read_b128 v[194:197], v138 offset:35840
	ds_read_b128 v[208:211], v138 offset:36864
	ds_read_b128 v[212:215], v138 offset:37888
	ds_read_b128 v[216:219], v138 offset:38912
	ds_read_b128 v[220:223], v138 offset:39936
	global_load_lds_dwordx4 v[230:231], off
	v_lshl_add_u64 v[230:231], s[46:47], 0, v[132:133]
	s_mov_b32 m0, s63
	s_nop 0
	global_load_lds_dwordx4 v[230:231], off
	s_waitcnt vmcnt(8)
	s_waitcnt lgkmcnt(0)
	s_barrier
	s_setprio 1
	s_waitcnt lgkmcnt(0)
	v_mfma_f32_16x16x32_bf16 v[128:131], v[140:143], v[182:185], v[128:131]
	v_mfma_f32_16x16x32_bf16 v[128:131], v[144:147], v[186:189], v[128:131]
	v_mfma_f32_16x16x32_bf16 v[124:127], v[148:151], v[182:185], v[124:127]
	v_mfma_f32_16x16x32_bf16 v[124:127], v[152:155], v[186:189], v[124:127]
	v_mfma_f32_16x16x32_bf16 v[120:123], v[140:143], v[190:193], v[120:123]
	v_mfma_f32_16x16x32_bf16 v[120:123], v[144:147], v[194:197], v[120:123]
	v_mfma_f32_16x16x32_bf16 v[116:119], v[148:151], v[190:193], v[116:119]
	v_mfma_f32_16x16x32_bf16 v[116:119], v[152:155], v[194:197], v[116:119]
	v_mfma_f32_16x16x32_bf16 v[108:111], v[140:143], v[208:211], v[108:111]
	v_mfma_f32_16x16x32_bf16 v[108:111], v[144:147], v[212:215], v[108:111]
	v_mfma_f32_16x16x32_bf16 v[100:103], v[148:151], v[208:211], v[100:103]
	v_mfma_f32_16x16x32_bf16 v[100:103], v[152:155], v[212:215], v[100:103]
	v_mfma_f32_16x16x32_bf16 v[92:95], v[140:143], v[216:219], v[92:95]
	v_mfma_f32_16x16x32_bf16 v[92:95], v[144:147], v[220:223], v[92:95]
	v_mfma_f32_16x16x32_bf16 v[84:87], v[148:151], v[216:219], v[84:87]
	v_mfma_f32_16x16x32_bf16 v[84:87], v[152:155], v[220:223], v[84:87]
	s_setprio 0
	s_setprio 1
	v_mfma_f32_16x16x32_bf16 v[112:115], v[156:159], v[182:185], v[112:115]
	v_mfma_f32_16x16x32_bf16 v[112:115], v[160:163], v[186:189], v[112:115]
	v_mfma_f32_16x16x32_bf16 v[104:107], v[164:167], v[182:185], v[104:107]
	v_mfma_f32_16x16x32_bf16 v[104:107], v[178:181], v[186:189], v[104:107]
	v_mfma_f32_16x16x32_bf16 v[96:99], v[156:159], v[190:193], v[96:99]
	v_mfma_f32_16x16x32_bf16 v[96:99], v[160:163], v[194:197], v[96:99]
	v_mfma_f32_16x16x32_bf16 v[88:91], v[164:167], v[190:193], v[88:91]
	v_mfma_f32_16x16x32_bf16 v[88:91], v[178:181], v[194:197], v[88:91]
	v_mfma_f32_16x16x32_bf16 v[80:83], v[156:159], v[208:211], v[80:83]
	v_mfma_f32_16x16x32_bf16 v[80:83], v[160:163], v[212:215], v[80:83]
	v_mfma_f32_16x16x32_bf16 v[76:79], v[164:167], v[208:211], v[76:79]
	v_mfma_f32_16x16x32_bf16 v[76:79], v[178:181], v[212:215], v[76:79]
	v_mfma_f32_16x16x32_bf16 v[72:75], v[156:159], v[216:219], v[72:75]
	v_mfma_f32_16x16x32_bf16 v[72:75], v[160:163], v[220:223], v[72:75]
	v_mfma_f32_16x16x32_bf16 v[68:71], v[164:167], v[216:219], v[68:71]
	v_mfma_f32_16x16x32_bf16 v[68:71], v[178:181], v[220:223], v[68:71]
	s_setprio 0
	s_barrier
	s_mov_b32 m0, s74
	v_lshl_add_u64 v[168:169], v[168:169], 0, s[18:19]
	ds_read_b128 v[182:185], v138 offset:49152
	ds_read_b128 v[186:189], v138 offset:50176
	ds_read_b128 v[190:193], v138 offset:51200
	ds_read_b128 v[194:197], v138 offset:52224
	ds_read_b128 v[208:211], v138 offset:53248
	ds_read_b128 v[212:215], v138 offset:54272
	ds_read_b128 v[216:219], v138 offset:55296
	ds_read_b128 v[220:223], v138 offset:56320
	global_load_lds_dwordx4 v[168:169], off
	v_lshl_add_u64 v[168:169], v[224:225], 0, s[18:19]
	s_mov_b32 m0, s73
	s_nop 0
	global_load_lds_dwordx4 v[168:169], off
	v_lshl_add_u64 v[168:169], s[44:45], 0, v[134:135]
	s_mov_b32 m0, s84
	s_nop 0
	global_load_lds_dwordx4 v[168:169], off
	v_lshl_add_u64 v[168:169], s[44:45], 0, v[132:133]
	s_mov_b32 m0, s83
	s_nop 0
	global_load_lds_dwordx4 v[168:169], off
	v_lshl_add_u64 v[168:169], v[226:227], 0, s[18:19]
	s_mov_b32 m0, s65
	s_nop 0
	global_load_lds_dwordx4 v[168:169], off
	v_lshl_add_u64 v[168:169], v[228:229], 0, s[18:19]
	s_mov_b32 m0, s66
	s_nop 0
	global_load_lds_dwordx4 v[168:169], off
	s_waitcnt vmcnt(8)
	s_waitcnt lgkmcnt(0)
	s_barrier
	s_setprio 1
	s_waitcnt lgkmcnt(0)
	v_mfma_f32_16x16x32_bf16 v[64:67], v[140:143], v[182:185], v[64:67]
	v_mfma_f32_16x16x32_bf16 v[64:67], v[144:147], v[186:189], v[64:67]
	v_mfma_f32_16x16x32_bf16 v[60:63], v[148:151], v[182:185], v[60:63]
	v_mfma_f32_16x16x32_bf16 v[60:63], v[152:155], v[186:189], v[60:63]
	v_mfma_f32_16x16x32_bf16 v[56:59], v[140:143], v[190:193], v[56:59]
	v_mfma_f32_16x16x32_bf16 v[56:59], v[144:147], v[194:197], v[56:59]
	v_mfma_f32_16x16x32_bf16 v[52:55], v[148:151], v[190:193], v[52:55]
	v_mfma_f32_16x16x32_bf16 v[52:55], v[152:155], v[194:197], v[52:55]
	v_mfma_f32_16x16x32_bf16 v[40:43], v[140:143], v[208:211], v[40:43]
	v_mfma_f32_16x16x32_bf16 v[40:43], v[144:147], v[212:215], v[40:43]
	v_mfma_f32_16x16x32_bf16 v[36:39], v[148:151], v[208:211], v[36:39]
	v_mfma_f32_16x16x32_bf16 v[36:39], v[152:155], v[212:215], v[36:39]
	v_mfma_f32_16x16x32_bf16 v[24:27], v[140:143], v[216:219], v[24:27]
	v_mfma_f32_16x16x32_bf16 v[24:27], v[144:147], v[220:223], v[24:27]
	v_mfma_f32_16x16x32_bf16 v[20:23], v[148:151], v[216:219], v[20:23]
	v_mfma_f32_16x16x32_bf16 v[20:23], v[152:155], v[220:223], v[20:23]
	s_setprio 0
	s_setprio 1
	v_mfma_f32_16x16x32_bf16 v[48:51], v[156:159], v[182:185], v[48:51]
	v_mfma_f32_16x16x32_bf16 v[48:51], v[160:163], v[186:189], v[48:51]
	v_mfma_f32_16x16x32_bf16 v[44:47], v[164:167], v[182:185], v[44:47]
	v_mfma_f32_16x16x32_bf16 v[44:47], v[178:181], v[186:189], v[44:47]
	v_mfma_f32_16x16x32_bf16 v[32:35], v[156:159], v[190:193], v[32:35]
	v_mfma_f32_16x16x32_bf16 v[32:35], v[160:163], v[194:197], v[32:35]
	v_mfma_f32_16x16x32_bf16 v[28:31], v[164:167], v[190:193], v[28:31]
	v_mfma_f32_16x16x32_bf16 v[28:31], v[178:181], v[194:197], v[28:31]
	v_mfma_f32_16x16x32_bf16 v[16:19], v[156:159], v[208:211], v[16:19]
	v_mfma_f32_16x16x32_bf16 v[16:19], v[160:163], v[212:215], v[16:19]
	v_mfma_f32_16x16x32_bf16 v[12:15], v[164:167], v[208:211], v[12:15]
	v_mfma_f32_16x16x32_bf16 v[12:15], v[178:181], v[212:215], v[12:15]
	v_mfma_f32_16x16x32_bf16 v[8:11], v[156:159], v[216:219], v[8:11]
	v_mfma_f32_16x16x32_bf16 v[8:11], v[160:163], v[220:223], v[8:11]
	v_mfma_f32_16x16x32_bf16 v[4:7], v[164:167], v[216:219], v[4:7]
	v_mfma_f32_16x16x32_bf16 v[4:7], v[178:181], v[220:223], v[4:7]
	s_setprio 0
	s_barrier
	s_movk_i32 s46, 0x100
	s_andn2_b64 vcc, exec, s[42:43]
	s_mov_b64 s[44:45], -1
	s_mov_b64 s[42:43], 0
	s_cbranch_vccz .LBB0_722
	s_and_b64 vcc, exec, s[34:35]
	s_cbranch_vccz .LBB0_725
	s_barrier

.LBB0_748:
	s_add_u32 s42, s40, 0xfff00080
	s_addc_u32 s43, s41, -1
	s_add_i32 s61, 0, 0x10000
	s_cmp_eq_u32 s55, 60
	s_cselect_b32 s45, s27, s43
	s_cselect_b32 s44, s51, s42
	v_add_u32_e32 v142, s61, v144
	s_cselect_b32 s43, s13, s54
	s_cselect_b32 s42, s52, s53
	s_add_i32 s65, 0, 0x14000
	ds_read_b128 v[148:151], v142
	ds_read_b128 v[152:155], v142 offset:1024
	ds_read_b128 v[156:159], v142 offset:2048
	ds_read_b128 v[160:163], v142 offset:3072
	v_add_u32_e32 v142, s65, v144
	ds_read_b128 v[164:167], v142
	ds_read_b128 v[178:181], v142 offset:1024
	ds_read_b128 v[182:185], v142 offset:2048
	ds_read_b128 v[186:189], v142 offset:3072
	v_lshl_add_u64 v[142:143], s[40:41], 0, v[138:139]
	s_add_i32 m0, s21, 0xc000
	ds_read_b128 v[190:193], v146
	ds_read_b128 v[194:197], v146 offset:1024
	ds_read_b128 v[208:211], v146 offset:2048
	ds_read_b128 v[212:215], v146 offset:3072
	ds_read_b128 v[216:219], v146 offset:4096
	ds_read_b128 v[220:223], v146 offset:5120
	ds_read_b128 v[224:227], v146 offset:6144
	ds_read_b128 v[228:231], v146 offset:7168
	global_load_lds_dwordx4 v[142:143], off
	v_lshl_add_u64 v[142:143], s[40:41], 0, v[140:141]
	s_add_i32 m0, s21, 0xe000
	s_nop 0
	global_load_lds_dwordx4 v[142:143], off
	s_waitcnt vmcnt(8)
	s_waitcnt lgkmcnt(0)
	s_barrier
	s_setprio 1
	s_waitcnt lgkmcnt(0)
	v_mfma_f32_16x16x32_bf16 v[128:131], v[148:151], v[190:193], v[128:131]
	v_mfma_f32_16x16x32_bf16 v[128:131], v[152:155], v[194:197], v[128:131]
	v_mfma_f32_16x16x32_bf16 v[124:127], v[156:159], v[190:193], v[124:127]
	v_mfma_f32_16x16x32_bf16 v[124:127], v[160:163], v[194:197], v[124:127]
	v_mfma_f32_16x16x32_bf16 v[120:123], v[148:151], v[208:211], v[120:123]
	v_mfma_f32_16x16x32_bf16 v[120:123], v[152:155], v[212:215], v[120:123]
	v_mfma_f32_16x16x32_bf16 v[112:115], v[156:159], v[208:211], v[112:115]
	v_mfma_f32_16x16x32_bf16 v[112:115], v[160:163], v[212:215], v[112:115]
	v_mfma_f32_16x16x32_bf16 v[104:107], v[148:151], v[216:219], v[104:107]
	v_mfma_f32_16x16x32_bf16 v[104:107], v[152:155], v[220:223], v[104:107]
	v_mfma_f32_16x16x32_bf16 v[96:99], v[156:159], v[216:219], v[96:99]
	v_mfma_f32_16x16x32_bf16 v[96:99], v[160:163], v[220:223], v[96:99]
	v_mfma_f32_16x16x32_bf16 v[88:91], v[148:151], v[224:227], v[88:91]
	v_mfma_f32_16x16x32_bf16 v[88:91], v[152:155], v[228:231], v[88:91]
	v_mfma_f32_16x16x32_bf16 v[80:83], v[156:159], v[224:227], v[80:83]
	v_mfma_f32_16x16x32_bf16 v[80:83], v[160:163], v[228:231], v[80:83]
	s_setprio 0
	s_setprio 1
	v_mfma_f32_16x16x32_bf16 v[116:119], v[164:167], v[190:193], v[116:119]
	v_mfma_f32_16x16x32_bf16 v[116:119], v[178:181], v[194:197], v[116:119]
	v_mfma_f32_16x16x32_bf16 v[108:111], v[182:185], v[190:193], v[108:111]
	v_mfma_f32_16x16x32_bf16 v[108:111], v[186:189], v[194:197], v[108:111]
	v_mfma_f32_16x16x32_bf16 v[100:103], v[164:167], v[208:211], v[100:103]
	v_mfma_f32_16x16x32_bf16 v[100:103], v[178:181], v[212:215], v[100:103]
	v_mfma_f32_16x16x32_bf16 v[92:95], v[182:185], v[208:211], v[92:95]
	v_mfma_f32_16x16x32_bf16 v[92:95], v[186:189], v[212:215], v[92:95]
	v_mfma_f32_16x16x32_bf16 v[84:87], v[164:167], v[216:219], v[84:87]
	v_mfma_f32_16x16x32_bf16 v[84:87], v[178:181], v[220:223], v[84:87]
	v_mfma_f32_16x16x32_bf16 v[76:79], v[182:185], v[216:219], v[76:79]
	v_mfma_f32_16x16x32_bf16 v[76:79], v[186:189], v[220:223], v[76:79]
	v_mfma_f32_16x16x32_bf16 v[72:75], v[164:167], v[224:227], v[72:75]
	v_mfma_f32_16x16x32_bf16 v[72:75], v[178:181], v[228:231], v[72:75]
	v_mfma_f32_16x16x32_bf16 v[68:71], v[182:185], v[224:227], v[68:71]
	v_mfma_f32_16x16x32_bf16 v[68:71], v[186:189], v[228:231], v[68:71]
	s_setprio 0
	s_barrier
	s_add_i32 s61, s61, s11
	v_lshl_add_u64 v[142:143], s[42:43], 0, v[2:3]
	s_mov_b32 m0, s61
	ds_read_b128 v[190:193], v146 offset:16384
	ds_read_b128 v[194:197], v146 offset:17408
	ds_read_b128 v[208:211], v146 offset:18432
	ds_read_b128 v[212:215], v146 offset:19456
	ds_read_b128 v[216:219], v146 offset:20480
	ds_read_b128 v[220:223], v146 offset:21504
	ds_read_b128 v[224:227], v146 offset:22528
	ds_read_b128 v[228:231], v146 offset:23552
	global_load_lds_dwordx4 v[142:143], off
	s_add_i32 m0, s61, 0x2000
	s_add_u32 s62, s42, 0x100000
	v_lshl_add_u64 v[168:169], s[42:43], 0, v[136:137]
	s_addc_u32 s63, s43, 0
	s_add_i32 s61, s65, s11
	global_load_lds_dwordx4 v[168:169], off
	v_lshl_add_u64 v[232:233], s[62:63], 0, v[2:3]
	s_mov_b32 m0, s61
	v_lshl_add_u64 v[234:235], s[44:45], 0, v[134:135]
	global_load_lds_dwordx4 v[232:233], off
	v_lshl_add_u64 v[232:233], s[62:63], 0, v[136:137]
	s_add_i32 m0, s61, 0x2000
	s_nop 0
	global_load_lds_dwordx4 v[232:233], off
	v_lshl_add_u64 v[232:233], s[44:45], 0, v[132:133]
	s_mov_b32 m0, s21
	s_nop 0
	global_load_lds_dwordx4 v[232:233], off
	s_mov_b32 m0, s22
	s_nop 0
	global_load_lds_dwordx4 v[234:235], off
	s_waitcnt vmcnt(8)
	s_waitcnt lgkmcnt(0)
	s_barrier
	s_setprio 1
	s_waitcnt lgkmcnt(0)
	v_mfma_f32_16x16x32_bf16 v[64:67], v[148:151], v[190:193], v[64:67]
	v_mfma_f32_16x16x32_bf16 v[64:67], v[152:155], v[194:197], v[64:67]
	v_mfma_f32_16x16x32_bf16 v[60:63], v[156:159], v[190:193], v[60:63]
	v_mfma_f32_16x16x32_bf16 v[60:63], v[160:163], v[194:197], v[60:63]
	v_mfma_f32_16x16x32_bf16 v[56:59], v[148:151], v[208:211], v[56:59]
	v_mfma_f32_16x16x32_bf16 v[56:59], v[152:155], v[212:215], v[56:59]
	v_mfma_f32_16x16x32_bf16 v[48:51], v[156:159], v[208:211], v[48:51]
	v_mfma_f32_16x16x32_bf16 v[48:51], v[160:163], v[212:215], v[48:51]
	v_mfma_f32_16x16x32_bf16 v[40:43], v[148:151], v[216:219], v[40:43]
	v_mfma_f32_16x16x32_bf16 v[40:43], v[152:155], v[220:223], v[40:43]
	v_mfma_f32_16x16x32_bf16 v[32:35], v[156:159], v[216:219], v[32:35]
	v_mfma_f32_16x16x32_bf16 v[32:35], v[160:163], v[220:223], v[32:35]
	v_mfma_f32_16x16x32_bf16 v[24:27], v[148:151], v[224:227], v[24:27]
	v_mfma_f32_16x16x32_bf16 v[24:27], v[152:155], v[228:231], v[24:27]
	v_mfma_f32_16x16x32_bf16 v[16:19], v[156:159], v[224:227], v[16:19]
	v_mfma_f32_16x16x32_bf16 v[16:19], v[160:163], v[228:231], v[16:19]
	s_setprio 0
	s_setprio 1
	v_mfma_f32_16x16x32_bf16 v[52:55], v[164:167], v[190:193], v[52:55]
	v_mfma_f32_16x16x32_bf16 v[52:55], v[178:181], v[194:197], v[52:55]
	v_mfma_f32_16x16x32_bf16 v[44:47], v[182:185], v[190:193], v[44:47]
	v_mfma_f32_16x16x32_bf16 v[44:47], v[186:189], v[194:197], v[44:47]
	v_mfma_f32_16x16x32_bf16 v[36:39], v[164:167], v[208:211], v[36:39]
	v_mfma_f32_16x16x32_bf16 v[36:39], v[178:181], v[212:215], v[36:39]
	v_mfma_f32_16x16x32_bf16 v[28:31], v[182:185], v[208:211], v[28:31]
	v_mfma_f32_16x16x32_bf16 v[28:31], v[186:189], v[212:215], v[28:31]
	v_mfma_f32_16x16x32_bf16 v[20:23], v[164:167], v[216:219], v[20:23]
	v_mfma_f32_16x16x32_bf16 v[20:23], v[178:181], v[220:223], v[20:23]
	v_mfma_f32_16x16x32_bf16 v[12:15], v[182:185], v[216:219], v[12:15]
	v_mfma_f32_16x16x32_bf16 v[12:15], v[186:189], v[220:223], v[12:15]
	v_mfma_f32_16x16x32_bf16 v[8:11], v[164:167], v[224:227], v[8:11]
	v_mfma_f32_16x16x32_bf16 v[8:11], v[178:181], v[228:231], v[8:11]
	v_mfma_f32_16x16x32_bf16 v[4:7], v[182:185], v[224:227], v[4:7]
	v_mfma_f32_16x16x32_bf16 v[4:7], v[186:189], v[228:231], v[4:7]
	s_setprio 0
	s_barrier
	s_add_i32 s61, 0, 0x18000
	v_add_u32_e32 v147, s61, v144
	s_add_i32 s62, 0, 0x1c000
	ds_read_b128 v[148:151], v147
	ds_read_b128 v[152:155], v147 offset:1024
	ds_read_b128 v[156:159], v147 offset:2048
	ds_read_b128 v[160:163], v147 offset:3072
	v_add_u32_e32 v147, s62, v144
	ds_read_b128 v[164:167], v147
	ds_read_b128 v[178:181], v147 offset:1024
	ds_read_b128 v[182:185], v147 offset:2048
	ds_read_b128 v[186:189], v147 offset:3072
	s_add_u32 s44, s44, 0x100000
	s_addc_u32 s45, s45, 0
	s_mov_b32 m0, s33
	v_lshl_add_u64 v[236:237], s[44:45], 0, v[132:133]
	ds_read_b128 v[190:193], v146 offset:32768
	ds_read_b128 v[194:197], v146 offset:33792
	ds_read_b128 v[208:211], v146 offset:34816
	ds_read_b128 v[212:215], v146 offset:35840
	ds_read_b128 v[216:219], v146 offset:36864
	ds_read_b128 v[220:223], v146 offset:37888
	ds_read_b128 v[224:227], v146 offset:38912
	ds_read_b128 v[228:231], v146 offset:39936
	global_load_lds_dwordx4 v[236:237], off
	v_lshl_add_u64 v[236:237], s[44:45], 0, v[134:135]
	s_mov_b32 m0, s46
	s_nop 0
	global_load_lds_dwordx4 v[236:237], off
	s_waitcnt vmcnt(8)
	s_waitcnt lgkmcnt(0)
	s_barrier
	s_setprio 1
	s_waitcnt lgkmcnt(0)
	v_mfma_f32_16x16x32_bf16 v[128:131], v[148:151], v[190:193], v[128:131]
	v_mfma_f32_16x16x32_bf16 v[128:131], v[152:155], v[194:197], v[128:131]
	v_mfma_f32_16x16x32_bf16 v[124:127], v[156:159], v[190:193], v[124:127]
	v_mfma_f32_16x16x32_bf16 v[124:127], v[160:163], v[194:197], v[124:127]
	v_mfma_f32_16x16x32_bf16 v[120:123], v[148:151], v[208:211], v[120:123]
	v_mfma_f32_16x16x32_bf16 v[120:123], v[152:155], v[212:215], v[120:123]
	v_mfma_f32_16x16x32_bf16 v[112:115], v[156:159], v[208:211], v[112:115]
	v_mfma_f32_16x16x32_bf16 v[112:115], v[160:163], v[212:215], v[112:115]
	v_mfma_f32_16x16x32_bf16 v[104:107], v[148:151], v[216:219], v[104:107]
	v_mfma_f32_16x16x32_bf16 v[104:107], v[152:155], v[220:223], v[104:107]
	v_mfma_f32_16x16x32_bf16 v[96:99], v[156:159], v[216:219], v[96:99]
	v_mfma_f32_16x16x32_bf16 v[96:99], v[160:163], v[220:223], v[96:99]
	v_mfma_f32_16x16x32_bf16 v[88:91], v[148:151], v[224:227], v[88:91]
	v_mfma_f32_16x16x32_bf16 v[88:91], v[152:155], v[228:231], v[88:91]
	v_mfma_f32_16x16x32_bf16 v[80:83], v[156:159], v[224:227], v[80:83]
	v_mfma_f32_16x16x32_bf16 v[80:83], v[160:163], v[228:231], v[80:83]
	s_setprio 0
	s_setprio 1
	v_mfma_f32_16x16x32_bf16 v[116:119], v[164:167], v[190:193], v[116:119]
	v_mfma_f32_16x16x32_bf16 v[116:119], v[178:181], v[194:197], v[116:119]
	v_mfma_f32_16x16x32_bf16 v[108:111], v[182:185], v[190:193], v[108:111]
	v_mfma_f32_16x16x32_bf16 v[108:111], v[186:189], v[194:197], v[108:111]
	v_mfma_f32_16x16x32_bf16 v[100:103], v[164:167], v[208:211], v[100:103]
	v_mfma_f32_16x16x32_bf16 v[100:103], v[178:181], v[212:215], v[100:103]
	v_mfma_f32_16x16x32_bf16 v[92:95], v[182:185], v[208:211], v[92:95]
	v_mfma_f32_16x16x32_bf16 v[92:95], v[186:189], v[212:215], v[92:95]
	v_mfma_f32_16x16x32_bf16 v[84:87], v[164:167], v[216:219], v[84:87]
	v_mfma_f32_16x16x32_bf16 v[84:87], v[178:181], v[220:223], v[84:87]
	v_mfma_f32_16x16x32_bf16 v[76:79], v[182:185], v[216:219], v[76:79]
	v_mfma_f32_16x16x32_bf16 v[76:79], v[186:189], v[220:223], v[76:79]
	v_mfma_f32_16x16x32_bf16 v[72:75], v[164:167], v[224:227], v[72:75]
	v_mfma_f32_16x16x32_bf16 v[72:75], v[178:181], v[228:231], v[72:75]
	v_mfma_f32_16x16x32_bf16 v[68:71], v[182:185], v[224:227], v[68:71]
	v_mfma_f32_16x16x32_bf16 v[68:71], v[186:189], v[228:231], v[68:71]
	s_setprio 0
	s_barrier
	s_add_i32 s44, s61, s11
	v_lshl_add_u64 v[142:143], v[142:143], 0, s[18:19]
	s_mov_b32 m0, s44
	ds_read_b128 v[190:193], v146 offset:49152
	ds_read_b128 v[194:197], v146 offset:50176
	ds_read_b128 v[208:211], v146 offset:51200
	ds_read_b128 v[212:215], v146 offset:52224
	ds_read_b128 v[216:219], v146 offset:53248
	ds_read_b128 v[220:223], v146 offset:54272
	ds_read_b128 v[224:227], v146 offset:55296
	ds_read_b128 v[228:231], v146 offset:56320
	global_load_lds_dwordx4 v[142:143], off
	s_add_i32 m0, s44, 0x2000
	s_add_u32 s42, s42, 0x100080
	v_lshl_add_u64 v[142:143], v[168:169], 0, s[18:19]
	s_addc_u32 s43, s43, 0
	s_add_i32 s44, s62, s11
	global_load_lds_dwordx4 v[142:143], off
	v_lshl_add_u64 v[142:143], s[42:43], 0, v[2:3]
	s_mov_b32 m0, s44
	s_nop 0
	global_load_lds_dwordx4 v[142:143], off
	v_lshl_add_u64 v[142:143], s[42:43], 0, v[136:137]
	s_add_i32 m0, s44, 0x2000
	s_nop 0
	global_load_lds_dwordx4 v[142:143], off
	v_lshl_add_u64 v[142:143], v[232:233], 0, s[18:19]
	s_mov_b32 m0, s47
	s_nop 0
	global_load_lds_dwordx4 v[142:143], off
	v_lshl_add_u64 v[142:143], v[234:235], 0, s[18:19]
	s_mov_b32 m0, s48
	s_nop 0
	global_load_lds_dwordx4 v[142:143], off
	s_waitcnt vmcnt(8)
	s_waitcnt lgkmcnt(0)
	s_barrier
	s_setprio 1
	s_waitcnt lgkmcnt(0)
	v_mfma_f32_16x16x32_bf16 v[64:67], v[148:151], v[190:193], v[64:67]
	v_mfma_f32_16x16x32_bf16 v[64:67], v[152:155], v[194:197], v[64:67]
	v_mfma_f32_16x16x32_bf16 v[60:63], v[156:159], v[190:193], v[60:63]
	v_mfma_f32_16x16x32_bf16 v[60:63], v[160:163], v[194:197], v[60:63]
	v_mfma_f32_16x16x32_bf16 v[56:59], v[148:151], v[208:211], v[56:59]
	v_mfma_f32_16x16x32_bf16 v[56:59], v[152:155], v[212:215], v[56:59]
	v_mfma_f32_16x16x32_bf16 v[48:51], v[156:159], v[208:211], v[48:51]
	v_mfma_f32_16x16x32_bf16 v[48:51], v[160:163], v[212:215], v[48:51]
	v_mfma_f32_16x16x32_bf16 v[40:43], v[148:151], v[216:219], v[40:43]
	v_mfma_f32_16x16x32_bf16 v[40:43], v[152:155], v[220:223], v[40:43]
	v_mfma_f32_16x16x32_bf16 v[32:35], v[156:159], v[216:219], v[32:35]
	v_mfma_f32_16x16x32_bf16 v[32:35], v[160:163], v[220:223], v[32:35]
	v_mfma_f32_16x16x32_bf16 v[24:27], v[148:151], v[224:227], v[24:27]
	v_mfma_f32_16x16x32_bf16 v[24:27], v[152:155], v[228:231], v[24:27]
	v_mfma_f32_16x16x32_bf16 v[16:19], v[156:159], v[224:227], v[16:19]
	v_mfma_f32_16x16x32_bf16 v[16:19], v[160:163], v[228:231], v[16:19]
	s_setprio 0
	s_setprio 1
	v_mfma_f32_16x16x32_bf16 v[52:55], v[164:167], v[190:193], v[52:55]
	v_mfma_f32_16x16x32_bf16 v[52:55], v[178:181], v[194:197], v[52:55]
	v_mfma_f32_16x16x32_bf16 v[44:47], v[182:185], v[190:193], v[44:47]
	v_mfma_f32_16x16x32_bf16 v[44:47], v[186:189], v[194:197], v[44:47]
	v_mfma_f32_16x16x32_bf16 v[36:39], v[164:167], v[208:211], v[36:39]
	v_mfma_f32_16x16x32_bf16 v[36:39], v[178:181], v[212:215], v[36:39]
	v_mfma_f32_16x16x32_bf16 v[28:31], v[182:185], v[208:211], v[28:31]
	v_mfma_f32_16x16x32_bf16 v[28:31], v[186:189], v[212:215], v[28:31]
	v_mfma_f32_16x16x32_bf16 v[20:23], v[164:167], v[216:219], v[20:23]
	v_mfma_f32_16x16x32_bf16 v[20:23], v[178:181], v[220:223], v[20:23]
	v_mfma_f32_16x16x32_bf16 v[12:15], v[182:185], v[216:219], v[12:15]
	v_mfma_f32_16x16x32_bf16 v[12:15], v[186:189], v[220:223], v[12:15]
	v_mfma_f32_16x16x32_bf16 v[8:11], v[164:167], v[224:227], v[8:11]
	v_mfma_f32_16x16x32_bf16 v[8:11], v[178:181], v[228:231], v[8:11]
	v_mfma_f32_16x16x32_bf16 v[4:7], v[182:185], v[224:227], v[4:7]
	v_mfma_f32_16x16x32_bf16 v[4:7], v[186:189], v[228:231], v[4:7]
	s_setprio 0
	s_barrier
	s_add_i32 s55, s55, 2
	s_add_u32 s40, s40, 0x100
	s_addc_u32 s41, s41, 0
	s_add_u32 s53, s53, 0x100
	s_addc_u32 s54, s54, 0
	s_cmp_gt_u32 s55, 61
	s_cbranch_scc0 .LBB0_748
	s_and_b64 vcc, exec, s[8:9]
	s_cbranch_vccz .LBB0_751
	s_barrier

.LBB0_762:
	s_add_u32 s38, s36, 0xfff00080
	s_addc_u32 s39, s37, -1
	s_add_i32 s55, 0, 0x10000
	s_cmp_eq_u32 s54, 4
	s_cselect_b32 s41, s3, s39
	s_cselect_b32 s40, s49, s38
	v_add_u32_e32 v2, s55, v140
	s_cselect_b32 s39, s50, s53
	s_cselect_b32 s38, s51, s52
	s_add_i32 s58, 0, 0x14000
	ds_read_b128 v[144:147], v2
	ds_read_b128 v[148:151], v2 offset:1024
	ds_read_b128 v[152:155], v2 offset:2048
	ds_read_b128 v[156:159], v2 offset:3072
	v_add_u32_e32 v2, s58, v140
	ds_read_b128 v[160:163], v2
	ds_read_b128 v[164:167], v2 offset:1024
	ds_read_b128 v[178:181], v2 offset:2048
	ds_read_b128 v[182:185], v2 offset:3072
	v_lshl_add_u64 v[168:169], s[36:37], 0, v[136:137]
	s_add_i32 m0, s33, 0xc000
	ds_read_b128 v[186:189], v142
	ds_read_b128 v[190:193], v142 offset:1024
	ds_read_b128 v[194:197], v142 offset:2048
	ds_read_b128 v[208:211], v142 offset:3072
	ds_read_b128 v[212:215], v142 offset:4096
	ds_read_b128 v[216:219], v142 offset:5120
	ds_read_b128 v[220:223], v142 offset:6144
	ds_read_b128 v[224:227], v142 offset:7168
	global_load_lds_dwordx4 v[168:169], off
	v_lshl_add_u64 v[168:169], s[36:37], 0, v[138:139]
	s_add_i32 m0, s33, 0xe000
	s_nop 0
	global_load_lds_dwordx4 v[168:169], off
	s_waitcnt vmcnt(8)
	s_waitcnt lgkmcnt(0)
	s_barrier
	s_setprio 1
	s_waitcnt lgkmcnt(0)
	v_mfma_f32_16x16x32_bf16 v[128:131], v[144:147], v[186:189], v[128:131]
	v_mfma_f32_16x16x32_bf16 v[128:131], v[148:151], v[190:193], v[128:131]
	v_mfma_f32_16x16x32_bf16 v[124:127], v[152:155], v[186:189], v[124:127]
	v_mfma_f32_16x16x32_bf16 v[124:127], v[156:159], v[190:193], v[124:127]
	v_mfma_f32_16x16x32_bf16 v[120:123], v[144:147], v[194:197], v[120:123]
	v_mfma_f32_16x16x32_bf16 v[120:123], v[148:151], v[208:211], v[120:123]
	v_mfma_f32_16x16x32_bf16 v[116:119], v[152:155], v[194:197], v[116:119]
	v_mfma_f32_16x16x32_bf16 v[116:119], v[156:159], v[208:211], v[116:119]
	v_mfma_f32_16x16x32_bf16 v[108:111], v[144:147], v[212:215], v[108:111]
	v_mfma_f32_16x16x32_bf16 v[108:111], v[148:151], v[216:219], v[108:111]
	v_mfma_f32_16x16x32_bf16 v[100:103], v[152:155], v[212:215], v[100:103]
	v_mfma_f32_16x16x32_bf16 v[100:103], v[156:159], v[216:219], v[100:103]
	v_mfma_f32_16x16x32_bf16 v[92:95], v[144:147], v[220:223], v[92:95]
	v_mfma_f32_16x16x32_bf16 v[92:95], v[148:151], v[224:227], v[92:95]
	v_mfma_f32_16x16x32_bf16 v[84:87], v[152:155], v[220:223], v[84:87]
	v_mfma_f32_16x16x32_bf16 v[84:87], v[156:159], v[224:227], v[84:87]
	s_setprio 0
	s_setprio 1
	v_mfma_f32_16x16x32_bf16 v[112:115], v[160:163], v[186:189], v[112:115]
	v_mfma_f32_16x16x32_bf16 v[112:115], v[164:167], v[190:193], v[112:115]
	v_mfma_f32_16x16x32_bf16 v[104:107], v[178:181], v[186:189], v[104:107]
	v_mfma_f32_16x16x32_bf16 v[104:107], v[182:185], v[190:193], v[104:107]
	v_mfma_f32_16x16x32_bf16 v[96:99], v[160:163], v[194:197], v[96:99]
	v_mfma_f32_16x16x32_bf16 v[96:99], v[164:167], v[208:211], v[96:99]
	v_mfma_f32_16x16x32_bf16 v[88:91], v[178:181], v[194:197], v[88:91]
	v_mfma_f32_16x16x32_bf16 v[88:91], v[182:185], v[208:211], v[88:91]
	v_mfma_f32_16x16x32_bf16 v[80:83], v[160:163], v[212:215], v[80:83]
	v_mfma_f32_16x16x32_bf16 v[80:83], v[164:167], v[216:219], v[80:83]
	v_mfma_f32_16x16x32_bf16 v[76:79], v[178:181], v[212:215], v[76:79]
	v_mfma_f32_16x16x32_bf16 v[76:79], v[182:185], v[216:219], v[76:79]
	v_mfma_f32_16x16x32_bf16 v[72:75], v[160:163], v[220:223], v[72:75]
	v_mfma_f32_16x16x32_bf16 v[72:75], v[164:167], v[224:227], v[72:75]
	v_mfma_f32_16x16x32_bf16 v[68:71], v[178:181], v[220:223], v[68:71]
	v_mfma_f32_16x16x32_bf16 v[68:71], v[182:185], v[224:227], v[68:71]
	s_setprio 0
	s_barrier
	s_add_i32 s55, s55, s21
	v_lshl_add_u64 v[168:169], s[38:39], 0, v[134:135]
	s_mov_b32 m0, s55
	ds_read_b128 v[186:189], v142 offset:16384
	ds_read_b128 v[190:193], v142 offset:17408
	ds_read_b128 v[194:197], v142 offset:18432
	ds_read_b128 v[208:211], v142 offset:19456
	ds_read_b128 v[212:215], v142 offset:20480
	ds_read_b128 v[216:219], v142 offset:21504
	ds_read_b128 v[220:223], v142 offset:22528
	ds_read_b128 v[224:227], v142 offset:23552
	global_load_lds_dwordx4 v[168:169], off
	s_add_i32 m0, s55, 0x2000
	s_add_u32 s56, s38, 0x100000
	v_lshl_add_u64 v[228:229], s[38:39], 0, v[132:133]
	s_addc_u32 s57, s39, 0
	s_add_i32 s55, s58, s21
	global_load_lds_dwordx4 v[228:229], off
	v_lshl_add_u64 v[230:231], s[56:57], 0, v[134:135]
	s_mov_b32 m0, s55
	v_lshl_add_u64 v[232:233], s[40:41], 0, v[132:133]
	global_load_lds_dwordx4 v[230:231], off
	v_lshl_add_u64 v[230:231], s[56:57], 0, v[132:133]
	s_add_i32 m0, s55, 0x2000
	s_nop 0
	global_load_lds_dwordx4 v[230:231], off
	v_lshl_add_u64 v[230:231], s[40:41], 0, v[134:135]
	s_mov_b32 m0, s33
	s_nop 0
	global_load_lds_dwordx4 v[230:231], off
	s_mov_b32 m0, s42
	s_nop 0
	global_load_lds_dwordx4 v[232:233], off
	s_waitcnt vmcnt(8)
	s_waitcnt lgkmcnt(0)
	s_barrier
	s_setprio 1
	s_waitcnt lgkmcnt(0)
	v_mfma_f32_16x16x32_bf16 v[64:67], v[144:147], v[186:189], v[64:67]
	v_mfma_f32_16x16x32_bf16 v[64:67], v[148:151], v[190:193], v[64:67]
	v_mfma_f32_16x16x32_bf16 v[60:63], v[152:155], v[186:189], v[60:63]
	v_mfma_f32_16x16x32_bf16 v[60:63], v[156:159], v[190:193], v[60:63]
	v_mfma_f32_16x16x32_bf16 v[56:59], v[144:147], v[194:197], v[56:59]
	v_mfma_f32_16x16x32_bf16 v[56:59], v[148:151], v[208:211], v[56:59]
	v_mfma_f32_16x16x32_bf16 v[52:55], v[152:155], v[194:197], v[52:55]
	v_mfma_f32_16x16x32_bf16 v[52:55], v[156:159], v[208:211], v[52:55]
	v_mfma_f32_16x16x32_bf16 v[40:43], v[144:147], v[212:215], v[40:43]
	v_mfma_f32_16x16x32_bf16 v[40:43], v[148:151], v[216:219], v[40:43]
	v_mfma_f32_16x16x32_bf16 v[36:39], v[152:155], v[212:215], v[36:39]
	v_mfma_f32_16x16x32_bf16 v[36:39], v[156:159], v[216:219], v[36:39]
	v_mfma_f32_16x16x32_bf16 v[24:27], v[144:147], v[220:223], v[24:27]
	v_mfma_f32_16x16x32_bf16 v[24:27], v[148:151], v[224:227], v[24:27]
	v_mfma_f32_16x16x32_bf16 v[20:23], v[152:155], v[220:223], v[20:23]
	v_mfma_f32_16x16x32_bf16 v[20:23], v[156:159], v[224:227], v[20:23]
	s_setprio 0
	s_setprio 1
	v_mfma_f32_16x16x32_bf16 v[48:51], v[160:163], v[186:189], v[48:51]
	v_mfma_f32_16x16x32_bf16 v[48:51], v[164:167], v[190:193], v[48:51]
	v_mfma_f32_16x16x32_bf16 v[44:47], v[178:181], v[186:189], v[44:47]
	v_mfma_f32_16x16x32_bf16 v[44:47], v[182:185], v[190:193], v[44:47]
	v_mfma_f32_16x16x32_bf16 v[32:35], v[160:163], v[194:197], v[32:35]
	v_mfma_f32_16x16x32_bf16 v[32:35], v[164:167], v[208:211], v[32:35]
	v_mfma_f32_16x16x32_bf16 v[28:31], v[178:181], v[194:197], v[28:31]
	v_mfma_f32_16x16x32_bf16 v[28:31], v[182:185], v[208:211], v[28:31]
	v_mfma_f32_16x16x32_bf16 v[16:19], v[160:163], v[212:215], v[16:19]
	v_mfma_f32_16x16x32_bf16 v[16:19], v[164:167], v[216:219], v[16:19]
	v_mfma_f32_16x16x32_bf16 v[12:15], v[178:181], v[212:215], v[12:15]
	v_mfma_f32_16x16x32_bf16 v[12:15], v[182:185], v[216:219], v[12:15]
	v_mfma_f32_16x16x32_bf16 v[8:11], v[160:163], v[220:223], v[8:11]
	v_mfma_f32_16x16x32_bf16 v[8:11], v[164:167], v[224:227], v[8:11]
	v_mfma_f32_16x16x32_bf16 v[4:7], v[178:181], v[220:223], v[4:7]
	v_mfma_f32_16x16x32_bf16 v[4:7], v[182:185], v[224:227], v[4:7]
	s_setprio 0
	s_barrier
	s_add_i32 s55, 0, 0x18000
	v_add_u32_e32 v2, s55, v140
	s_add_i32 s56, 0, 0x1c000
	ds_read_b128 v[144:147], v2
	ds_read_b128 v[148:151], v2 offset:1024
	ds_read_b128 v[152:155], v2 offset:2048
	ds_read_b128 v[156:159], v2 offset:3072
	v_add_u32_e32 v2, s56, v140
	ds_read_b128 v[160:163], v2
	ds_read_b128 v[164:167], v2 offset:1024
	ds_read_b128 v[178:181], v2 offset:2048
	ds_read_b128 v[182:185], v2 offset:3072
	s_add_u32 s40, s40, 0x100000
	s_addc_u32 s41, s41, 0
	s_mov_b32 m0, s43
	v_lshl_add_u64 v[234:235], s[40:41], 0, v[134:135]
	ds_read_b128 v[186:189], v142 offset:32768
	ds_read_b128 v[190:193], v142 offset:33792
	ds_read_b128 v[194:197], v142 offset:34816
	ds_read_b128 v[208:211], v142 offset:35840
	ds_read_b128 v[212:215], v142 offset:36864
	ds_read_b128 v[216:219], v142 offset:37888
	ds_read_b128 v[220:223], v142 offset:38912
	ds_read_b128 v[224:227], v142 offset:39936
	global_load_lds_dwordx4 v[234:235], off
	v_lshl_add_u64 v[234:235], s[40:41], 0, v[132:133]
	s_mov_b32 m0, s44
	s_nop 0
	global_load_lds_dwordx4 v[234:235], off
	s_waitcnt vmcnt(8)
	s_waitcnt lgkmcnt(0)
	s_barrier
	s_setprio 1
	s_waitcnt lgkmcnt(0)
	v_mfma_f32_16x16x32_bf16 v[128:131], v[144:147], v[186:189], v[128:131]
	v_mfma_f32_16x16x32_bf16 v[128:131], v[148:151], v[190:193], v[128:131]
	v_mfma_f32_16x16x32_bf16 v[124:127], v[152:155], v[186:189], v[124:127]
	v_mfma_f32_16x16x32_bf16 v[124:127], v[156:159], v[190:193], v[124:127]
	v_mfma_f32_16x16x32_bf16 v[120:123], v[144:147], v[194:197], v[120:123]
	v_mfma_f32_16x16x32_bf16 v[120:123], v[148:151], v[208:211], v[120:123]
	v_mfma_f32_16x16x32_bf16 v[116:119], v[152:155], v[194:197], v[116:119]
	v_mfma_f32_16x16x32_bf16 v[116:119], v[156:159], v[208:211], v[116:119]
	v_mfma_f32_16x16x32_bf16 v[108:111], v[144:147], v[212:215], v[108:111]
	v_mfma_f32_16x16x32_bf16 v[108:111], v[148:151], v[216:219], v[108:111]
	v_mfma_f32_16x16x32_bf16 v[100:103], v[152:155], v[212:215], v[100:103]
	v_mfma_f32_16x16x32_bf16 v[100:103], v[156:159], v[216:219], v[100:103]
	v_mfma_f32_16x16x32_bf16 v[92:95], v[144:147], v[220:223], v[92:95]
	v_mfma_f32_16x16x32_bf16 v[92:95], v[148:151], v[224:227], v[92:95]
	v_mfma_f32_16x16x32_bf16 v[84:87], v[152:155], v[220:223], v[84:87]
	v_mfma_f32_16x16x32_bf16 v[84:87], v[156:159], v[224:227], v[84:87]
	s_setprio 0
	s_setprio 1
	v_mfma_f32_16x16x32_bf16 v[112:115], v[160:163], v[186:189], v[112:115]
	v_mfma_f32_16x16x32_bf16 v[112:115], v[164:167], v[190:193], v[112:115]
	v_mfma_f32_16x16x32_bf16 v[104:107], v[178:181], v[186:189], v[104:107]
	v_mfma_f32_16x16x32_bf16 v[104:107], v[182:185], v[190:193], v[104:107]
	v_mfma_f32_16x16x32_bf16 v[96:99], v[160:163], v[194:197], v[96:99]
	v_mfma_f32_16x16x32_bf16 v[96:99], v[164:167], v[208:211], v[96:99]
	v_mfma_f32_16x16x32_bf16 v[88:91], v[178:181], v[194:197], v[88:91]
	v_mfma_f32_16x16x32_bf16 v[88:91], v[182:185], v[208:211], v[88:91]
	v_mfma_f32_16x16x32_bf16 v[80:83], v[160:163], v[212:215], v[80:83]
	v_mfma_f32_16x16x32_bf16 v[80:83], v[164:167], v[216:219], v[80:83]
	v_mfma_f32_16x16x32_bf16 v[76:79], v[178:181], v[212:215], v[76:79]
	v_mfma_f32_16x16x32_bf16 v[76:79], v[182:185], v[216:219], v[76:79]
	v_mfma_f32_16x16x32_bf16 v[72:75], v[160:163], v[220:223], v[72:75]
	v_mfma_f32_16x16x32_bf16 v[72:75], v[164:167], v[224:227], v[72:75]
	v_mfma_f32_16x16x32_bf16 v[68:71], v[178:181], v[220:223], v[68:71]
	v_mfma_f32_16x16x32_bf16 v[68:71], v[182:185], v[224:227], v[68:71]
	s_setprio 0
	s_barrier
	s_add_i32 s40, s55, s21
	v_lshl_add_u64 v[168:169], v[168:169], 0, s[18:19]
	s_mov_b32 m0, s40
	ds_read_b128 v[186:189], v142 offset:49152
	ds_read_b128 v[190:193], v142 offset:50176
	ds_read_b128 v[194:197], v142 offset:51200
	ds_read_b128 v[208:211], v142 offset:52224
	ds_read_b128 v[212:215], v142 offset:53248
	ds_read_b128 v[216:219], v142 offset:54272
	ds_read_b128 v[220:223], v142 offset:55296
	ds_read_b128 v[224:227], v142 offset:56320
	global_load_lds_dwordx4 v[168:169], off
	s_add_i32 m0, s40, 0x2000
	s_add_u32 s38, s38, 0x100080
	v_lshl_add_u64 v[168:169], v[228:229], 0, s[18:19]
	s_addc_u32 s39, s39, 0
	s_add_i32 s40, s56, s21
	global_load_lds_dwordx4 v[168:169], off
	v_lshl_add_u64 v[168:169], s[38:39], 0, v[134:135]
	s_mov_b32 m0, s40
	s_nop 0
	global_load_lds_dwordx4 v[168:169], off
	v_lshl_add_u64 v[168:169], s[38:39], 0, v[132:133]
	s_add_i32 m0, s40, 0x2000
	s_nop 0
	global_load_lds_dwordx4 v[168:169], off
	v_lshl_add_u64 v[168:169], v[230:231], 0, s[18:19]
	s_mov_b32 m0, s25
	s_nop 0
	global_load_lds_dwordx4 v[168:169], off
	v_lshl_add_u64 v[168:169], v[232:233], 0, s[18:19]
	s_mov_b32 m0, s45
	s_nop 0
	global_load_lds_dwordx4 v[168:169], off
	s_waitcnt vmcnt(8)
	s_waitcnt lgkmcnt(0)
	s_barrier
	s_setprio 1
	s_waitcnt lgkmcnt(0)
	v_mfma_f32_16x16x32_bf16 v[64:67], v[144:147], v[186:189], v[64:67]
	v_mfma_f32_16x16x32_bf16 v[64:67], v[148:151], v[190:193], v[64:67]
	v_mfma_f32_16x16x32_bf16 v[60:63], v[152:155], v[186:189], v[60:63]
	v_mfma_f32_16x16x32_bf16 v[60:63], v[156:159], v[190:193], v[60:63]
	v_mfma_f32_16x16x32_bf16 v[56:59], v[144:147], v[194:197], v[56:59]
	v_mfma_f32_16x16x32_bf16 v[56:59], v[148:151], v[208:211], v[56:59]
	v_mfma_f32_16x16x32_bf16 v[52:55], v[152:155], v[194:197], v[52:55]
	v_mfma_f32_16x16x32_bf16 v[52:55], v[156:159], v[208:211], v[52:55]
	v_mfma_f32_16x16x32_bf16 v[40:43], v[144:147], v[212:215], v[40:43]
	v_mfma_f32_16x16x32_bf16 v[40:43], v[148:151], v[216:219], v[40:43]
	v_mfma_f32_16x16x32_bf16 v[36:39], v[152:155], v[212:215], v[36:39]
	v_mfma_f32_16x16x32_bf16 v[36:39], v[156:159], v[216:219], v[36:39]
	v_mfma_f32_16x16x32_bf16 v[24:27], v[144:147], v[220:223], v[24:27]
	v_mfma_f32_16x16x32_bf16 v[24:27], v[148:151], v[224:227], v[24:27]
	v_mfma_f32_16x16x32_bf16 v[20:23], v[152:155], v[220:223], v[20:23]
	v_mfma_f32_16x16x32_bf16 v[20:23], v[156:159], v[224:227], v[20:23]
	s_setprio 0
	s_setprio 1
	v_mfma_f32_16x16x32_bf16 v[48:51], v[160:163], v[186:189], v[48:51]
	v_mfma_f32_16x16x32_bf16 v[48:51], v[164:167], v[190:193], v[48:51]
	v_mfma_f32_16x16x32_bf16 v[44:47], v[178:181], v[186:189], v[44:47]
	v_mfma_f32_16x16x32_bf16 v[44:47], v[182:185], v[190:193], v[44:47]
	v_mfma_f32_16x16x32_bf16 v[32:35], v[160:163], v[194:197], v[32:35]
	v_mfma_f32_16x16x32_bf16 v[32:35], v[164:167], v[208:211], v[32:35]
	v_mfma_f32_16x16x32_bf16 v[28:31], v[178:181], v[194:197], v[28:31]
	v_mfma_f32_16x16x32_bf16 v[28:31], v[182:185], v[208:211], v[28:31]
	v_mfma_f32_16x16x32_bf16 v[16:19], v[160:163], v[212:215], v[16:19]
	v_mfma_f32_16x16x32_bf16 v[16:19], v[164:167], v[216:219], v[16:19]
	v_mfma_f32_16x16x32_bf16 v[12:15], v[178:181], v[212:215], v[12:15]
	v_mfma_f32_16x16x32_bf16 v[12:15], v[182:185], v[216:219], v[12:15]
	v_mfma_f32_16x16x32_bf16 v[8:11], v[160:163], v[220:223], v[8:11]
	v_mfma_f32_16x16x32_bf16 v[8:11], v[164:167], v[224:227], v[8:11]
	v_mfma_f32_16x16x32_bf16 v[4:7], v[178:181], v[220:223], v[4:7]
	v_mfma_f32_16x16x32_bf16 v[4:7], v[182:185], v[224:227], v[4:7]
	s_setprio 0
	s_barrier
	s_add_i32 s54, s54, 2
	s_add_u32 s36, s36, 0x100
	s_addc_u32 s37, s37, 0
	s_add_u32 s52, s52, 0x100
	s_addc_u32 s53, s53, 0
	s_cmp_gt_u32 s54, 5
	s_cbranch_scc0 .LBB0_762
	s_and_b64 vcc, exec, s[28:29]
	s_cbranch_vccz .LBB0_765
	s_barrier

.LBB0_901:
	s_add_u32 s12, s8, 0xfff80080
	s_addc_u32 s13, s9, -1
	s_add_i32 s47, 0, 0x10000
	s_cmp_eq_u32 s33, 28
	s_cselect_b32 s27, s5, s13
	s_cselect_b32 s26, s7, s12
	s_cselect_b32 s13, s10, s22
	s_cselect_b32 s12, s11, s21
	s_add_i32 s49, 0, 0x14000
	v_add_u32_e32 v158, s47, v151
	v_add_u32_e32 v182, s49, v151
	ds_read_b128 v[142:145], v158
	ds_read_b128 v[146:149], v158 offset:1024
	ds_read_b128 v[154:157], v158 offset:2048
	ds_read_b128 v[158:161], v158 offset:3072
	ds_read_b128 v[162:165], v182
	ds_read_b128 v[166:169], v182 offset:1024
	ds_read_b128 v[178:181], v182 offset:2048
	ds_read_b128 v[182:185], v182 offset:3072
	v_lshl_add_u64 v[228:229], s[8:9], 0, v[138:139]
	s_add_i32 m0, s57, 0xc000
	ds_read_b128 v[186:189], v153
	ds_read_b128 v[190:193], v153 offset:1024
	ds_read_b128 v[194:197], v153 offset:2048
	ds_read_b128 v[208:211], v153 offset:3072
	ds_read_b128 v[212:215], v153 offset:4096
	ds_read_b128 v[216:219], v153 offset:5120
	ds_read_b128 v[220:223], v153 offset:6144
	ds_read_b128 v[224:227], v153 offset:7168
	global_load_lds_dwordx4 v[228:229], off
	v_lshl_add_u64 v[228:229], s[8:9], 0, v[140:141]
	s_add_i32 m0, s57, 0xe000
	s_nop 0
	global_load_lds_dwordx4 v[228:229], off
	s_waitcnt vmcnt(8)
	s_waitcnt lgkmcnt(0)
	s_barrier
	s_setprio 1
	s_waitcnt lgkmcnt(0)
	v_mfma_f32_16x16x32_bf16 v[128:131], v[142:145], v[186:189], v[128:131]
	v_mfma_f32_16x16x32_bf16 v[128:131], v[146:149], v[190:193], v[128:131]
	v_mfma_f32_16x16x32_bf16 v[124:127], v[154:157], v[186:189], v[124:127]
	v_mfma_f32_16x16x32_bf16 v[124:127], v[158:161], v[190:193], v[124:127]
	v_mfma_f32_16x16x32_bf16 v[112:115], v[142:145], v[194:197], v[112:115]
	v_mfma_f32_16x16x32_bf16 v[112:115], v[146:149], v[208:211], v[112:115]
	v_mfma_f32_16x16x32_bf16 v[108:111], v[154:157], v[194:197], v[108:111]
	v_mfma_f32_16x16x32_bf16 v[108:111], v[158:161], v[208:211], v[108:111]
	v_mfma_f32_16x16x32_bf16 v[96:99], v[142:145], v[212:215], v[96:99]
	v_mfma_f32_16x16x32_bf16 v[96:99], v[146:149], v[216:219], v[96:99]
	v_mfma_f32_16x16x32_bf16 v[92:95], v[154:157], v[212:215], v[92:95]
	v_mfma_f32_16x16x32_bf16 v[92:95], v[158:161], v[216:219], v[92:95]
	v_mfma_f32_16x16x32_bf16 v[80:83], v[142:145], v[220:223], v[80:83]
	v_mfma_f32_16x16x32_bf16 v[80:83], v[146:149], v[224:227], v[80:83]
	v_mfma_f32_16x16x32_bf16 v[76:79], v[154:157], v[220:223], v[76:79]
	v_mfma_f32_16x16x32_bf16 v[76:79], v[158:161], v[224:227], v[76:79]
	s_setprio 0
	s_setprio 1
	v_mfma_f32_16x16x32_bf16 v[120:123], v[162:165], v[186:189], v[120:123]
	v_mfma_f32_16x16x32_bf16 v[120:123], v[166:169], v[190:193], v[120:123]
	v_mfma_f32_16x16x32_bf16 v[116:119], v[178:181], v[186:189], v[116:119]
	v_mfma_f32_16x16x32_bf16 v[116:119], v[182:185], v[190:193], v[116:119]
	v_mfma_f32_16x16x32_bf16 v[104:107], v[162:165], v[194:197], v[104:107]
	v_mfma_f32_16x16x32_bf16 v[104:107], v[166:169], v[208:211], v[104:107]
	v_mfma_f32_16x16x32_bf16 v[100:103], v[178:181], v[194:197], v[100:103]
	v_mfma_f32_16x16x32_bf16 v[100:103], v[182:185], v[208:211], v[100:103]
	v_mfma_f32_16x16x32_bf16 v[88:91], v[162:165], v[212:215], v[88:91]
	v_mfma_f32_16x16x32_bf16 v[88:91], v[166:169], v[216:219], v[88:91]
	v_mfma_f32_16x16x32_bf16 v[84:87], v[178:181], v[212:215], v[84:87]
	v_mfma_f32_16x16x32_bf16 v[84:87], v[182:185], v[216:219], v[84:87]
	v_mfma_f32_16x16x32_bf16 v[72:75], v[162:165], v[220:223], v[72:75]
	v_mfma_f32_16x16x32_bf16 v[72:75], v[166:169], v[224:227], v[72:75]
	v_mfma_f32_16x16x32_bf16 v[68:71], v[178:181], v[220:223], v[68:71]
	v_mfma_f32_16x16x32_bf16 v[68:71], v[182:185], v[224:227], v[68:71]
	s_setprio 0
	s_barrier
	s_add_i32 s47, s47, s55
	v_lshl_add_u64 v[228:229], s[12:13], 0, v[2:3]
	s_mov_b32 m0, s47
	ds_read_b128 v[186:189], v153 offset:16384
	ds_read_b128 v[190:193], v153 offset:17408
	ds_read_b128 v[194:197], v153 offset:18432
	ds_read_b128 v[208:211], v153 offset:19456
	ds_read_b128 v[212:215], v153 offset:20480
	ds_read_b128 v[216:219], v153 offset:21504
	ds_read_b128 v[220:223], v153 offset:22528
	ds_read_b128 v[224:227], v153 offset:23552
	global_load_lds_dwordx4 v[228:229], off
	s_add_i32 m0, s47, 0x2000
	s_add_u32 s66, s12, 0x80000
	v_lshl_add_u64 v[230:231], s[12:13], 0, v[132:133]
	s_addc_u32 s67, s13, 0
	s_add_i32 s47, s49, s55
	global_load_lds_dwordx4 v[230:231], off
	v_lshl_add_u64 v[232:233], s[66:67], 0, v[2:3]
	s_mov_b32 m0, s47
	v_lshl_add_u64 v[234:235], s[26:27], 0, v[134:135]
	global_load_lds_dwordx4 v[232:233], off
	v_lshl_add_u64 v[232:233], s[66:67], 0, v[132:133]
	s_add_i32 m0, s47, 0x2000
	s_nop 0
	global_load_lds_dwordx4 v[232:233], off
	v_lshl_add_u64 v[232:233], s[26:27], 0, v[136:137]
	s_mov_b32 m0, s57
	s_nop 0
	global_load_lds_dwordx4 v[232:233], off
	s_mov_b32 m0, s58
	s_nop 0
	global_load_lds_dwordx4 v[234:235], off
	s_waitcnt vmcnt(8)
	s_waitcnt lgkmcnt(0)
	s_barrier
	s_setprio 1
	s_waitcnt lgkmcnt(0)
	v_mfma_f32_16x16x32_bf16 v[64:67], v[142:145], v[186:189], v[64:67]
	v_mfma_f32_16x16x32_bf16 v[64:67], v[146:149], v[190:193], v[64:67]
	v_mfma_f32_16x16x32_bf16 v[60:63], v[154:157], v[186:189], v[60:63]
	v_mfma_f32_16x16x32_bf16 v[60:63], v[158:161], v[190:193], v[60:63]
	v_mfma_f32_16x16x32_bf16 v[48:51], v[142:145], v[194:197], v[48:51]
	v_mfma_f32_16x16x32_bf16 v[48:51], v[146:149], v[208:211], v[48:51]
	v_mfma_f32_16x16x32_bf16 v[44:47], v[154:157], v[194:197], v[44:47]
	v_mfma_f32_16x16x32_bf16 v[44:47], v[158:161], v[208:211], v[44:47]
	v_mfma_f32_16x16x32_bf16 v[32:35], v[142:145], v[212:215], v[32:35]
	v_mfma_f32_16x16x32_bf16 v[32:35], v[146:149], v[216:219], v[32:35]
	v_mfma_f32_16x16x32_bf16 v[28:31], v[154:157], v[212:215], v[28:31]
	v_mfma_f32_16x16x32_bf16 v[28:31], v[158:161], v[216:219], v[28:31]
	v_mfma_f32_16x16x32_bf16 v[16:19], v[142:145], v[220:223], v[16:19]
	v_mfma_f32_16x16x32_bf16 v[16:19], v[146:149], v[224:227], v[16:19]
	v_mfma_f32_16x16x32_bf16 v[12:15], v[154:157], v[220:223], v[12:15]
	v_mfma_f32_16x16x32_bf16 v[12:15], v[158:161], v[224:227], v[12:15]
	s_setprio 0
	s_setprio 1
	v_mfma_f32_16x16x32_bf16 v[56:59], v[162:165], v[186:189], v[56:59]
	v_mfma_f32_16x16x32_bf16 v[56:59], v[166:169], v[190:193], v[56:59]
	v_mfma_f32_16x16x32_bf16 v[52:55], v[178:181], v[186:189], v[52:55]
	v_mfma_f32_16x16x32_bf16 v[52:55], v[182:185], v[190:193], v[52:55]
	v_mfma_f32_16x16x32_bf16 v[40:43], v[162:165], v[194:197], v[40:43]
	v_mfma_f32_16x16x32_bf16 v[40:43], v[166:169], v[208:211], v[40:43]
	v_mfma_f32_16x16x32_bf16 v[36:39], v[178:181], v[194:197], v[36:39]
	v_mfma_f32_16x16x32_bf16 v[36:39], v[182:185], v[208:211], v[36:39]
	v_mfma_f32_16x16x32_bf16 v[24:27], v[162:165], v[212:215], v[24:27]
	v_mfma_f32_16x16x32_bf16 v[24:27], v[166:169], v[216:219], v[24:27]
	v_mfma_f32_16x16x32_bf16 v[20:23], v[178:181], v[212:215], v[20:23]
	v_mfma_f32_16x16x32_bf16 v[20:23], v[182:185], v[216:219], v[20:23]
	v_mfma_f32_16x16x32_bf16 v[8:11], v[162:165], v[220:223], v[8:11]
	v_mfma_f32_16x16x32_bf16 v[8:11], v[166:169], v[224:227], v[8:11]
	v_mfma_f32_16x16x32_bf16 v[4:7], v[178:181], v[220:223], v[4:7]
	v_mfma_f32_16x16x32_bf16 v[4:7], v[182:185], v[224:227], v[4:7]
	s_setprio 0
	s_barrier
	s_add_i32 s47, 0, 0x18000
	s_add_i32 s49, 0, 0x1c000
	v_add_u32_e32 v158, s47, v151
	v_add_u32_e32 v182, s49, v151
	ds_read_b128 v[142:145], v158
	ds_read_b128 v[146:149], v158 offset:1024
	ds_read_b128 v[154:157], v158 offset:2048
	ds_read_b128 v[158:161], v158 offset:3072
	ds_read_b128 v[162:165], v182
	ds_read_b128 v[166:169], v182 offset:1024
	ds_read_b128 v[178:181], v182 offset:2048
	ds_read_b128 v[182:185], v182 offset:3072
	s_add_u32 s26, s26, 0x80000
	s_addc_u32 s27, s27, 0
	s_mov_b32 m0, s59
	v_lshl_add_u64 v[236:237], s[26:27], 0, v[136:137]
	ds_read_b128 v[186:189], v153 offset:32768
	ds_read_b128 v[190:193], v153 offset:33792
	ds_read_b128 v[194:197], v153 offset:34816
	ds_read_b128 v[208:211], v153 offset:35840
	ds_read_b128 v[212:215], v153 offset:36864
	ds_read_b128 v[216:219], v153 offset:37888
	ds_read_b128 v[220:223], v153 offset:38912
	ds_read_b128 v[224:227], v153 offset:39936
	global_load_lds_dwordx4 v[236:237], off
	v_lshl_add_u64 v[236:237], s[26:27], 0, v[134:135]
	s_mov_b32 m0, s60
	s_nop 0
	global_load_lds_dwordx4 v[236:237], off
	s_waitcnt vmcnt(8)
	s_waitcnt lgkmcnt(0)
	s_barrier
	s_setprio 1
	s_waitcnt lgkmcnt(0)
	v_mfma_f32_16x16x32_bf16 v[128:131], v[142:145], v[186:189], v[128:131]
	v_mfma_f32_16x16x32_bf16 v[128:131], v[146:149], v[190:193], v[128:131]
	v_mfma_f32_16x16x32_bf16 v[124:127], v[154:157], v[186:189], v[124:127]
	v_mfma_f32_16x16x32_bf16 v[124:127], v[158:161], v[190:193], v[124:127]
	v_mfma_f32_16x16x32_bf16 v[112:115], v[142:145], v[194:197], v[112:115]
	v_mfma_f32_16x16x32_bf16 v[112:115], v[146:149], v[208:211], v[112:115]
	v_mfma_f32_16x16x32_bf16 v[108:111], v[154:157], v[194:197], v[108:111]
	v_mfma_f32_16x16x32_bf16 v[108:111], v[158:161], v[208:211], v[108:111]
	v_mfma_f32_16x16x32_bf16 v[96:99], v[142:145], v[212:215], v[96:99]
	v_mfma_f32_16x16x32_bf16 v[96:99], v[146:149], v[216:219], v[96:99]
	v_mfma_f32_16x16x32_bf16 v[92:95], v[154:157], v[212:215], v[92:95]
	v_mfma_f32_16x16x32_bf16 v[92:95], v[158:161], v[216:219], v[92:95]
	v_mfma_f32_16x16x32_bf16 v[80:83], v[142:145], v[220:223], v[80:83]
	v_mfma_f32_16x16x32_bf16 v[80:83], v[146:149], v[224:227], v[80:83]
	v_mfma_f32_16x16x32_bf16 v[76:79], v[154:157], v[220:223], v[76:79]
	v_mfma_f32_16x16x32_bf16 v[76:79], v[158:161], v[224:227], v[76:79]
	s_setprio 0
	s_setprio 1
	v_mfma_f32_16x16x32_bf16 v[120:123], v[162:165], v[186:189], v[120:123]
	v_mfma_f32_16x16x32_bf16 v[120:123], v[166:169], v[190:193], v[120:123]
	v_mfma_f32_16x16x32_bf16 v[116:119], v[178:181], v[186:189], v[116:119]
	v_mfma_f32_16x16x32_bf16 v[116:119], v[182:185], v[190:193], v[116:119]
	v_mfma_f32_16x16x32_bf16 v[104:107], v[162:165], v[194:197], v[104:107]
	v_mfma_f32_16x16x32_bf16 v[104:107], v[166:169], v[208:211], v[104:107]
	v_mfma_f32_16x16x32_bf16 v[100:103], v[178:181], v[194:197], v[100:103]
	v_mfma_f32_16x16x32_bf16 v[100:103], v[182:185], v[208:211], v[100:103]
	v_mfma_f32_16x16x32_bf16 v[88:91], v[162:165], v[212:215], v[88:91]
	v_mfma_f32_16x16x32_bf16 v[88:91], v[166:169], v[216:219], v[88:91]
	v_mfma_f32_16x16x32_bf16 v[84:87], v[178:181], v[212:215], v[84:87]
	v_mfma_f32_16x16x32_bf16 v[84:87], v[182:185], v[216:219], v[84:87]
	v_mfma_f32_16x16x32_bf16 v[72:75], v[162:165], v[220:223], v[72:75]
	v_mfma_f32_16x16x32_bf16 v[72:75], v[166:169], v[224:227], v[72:75]
	v_mfma_f32_16x16x32_bf16 v[68:71], v[178:181], v[220:223], v[68:71]
	v_mfma_f32_16x16x32_bf16 v[68:71], v[182:185], v[224:227], v[68:71]
	s_setprio 0
	s_barrier
	s_add_i32 s26, s47, s55
	v_lshl_add_u64 v[228:229], v[228:229], 0, s[18:19]
	s_mov_b32 m0, s26
	ds_read_b128 v[186:189], v153 offset:49152
	ds_read_b128 v[190:193], v153 offset:50176
	ds_read_b128 v[194:197], v153 offset:51200
	ds_read_b128 v[208:211], v153 offset:52224
	ds_read_b128 v[212:215], v153 offset:53248
	ds_read_b128 v[216:219], v153 offset:54272
	ds_read_b128 v[220:223], v153 offset:55296
	ds_read_b128 v[224:227], v153 offset:56320
	global_load_lds_dwordx4 v[228:229], off
	s_add_i32 m0, s26, 0x2000
	s_add_u32 s12, s12, 0x80080
	v_lshl_add_u64 v[228:229], v[230:231], 0, s[18:19]
	s_addc_u32 s13, s13, 0
	s_add_i32 s26, s49, s55
	global_load_lds_dwordx4 v[228:229], off
	v_lshl_add_u64 v[228:229], s[12:13], 0, v[2:3]
	s_mov_b32 m0, s26
	s_nop 0
	global_load_lds_dwordx4 v[228:229], off
	v_lshl_add_u64 v[228:229], s[12:13], 0, v[132:133]
	s_add_i32 m0, s26, 0x2000
	s_nop 0
	global_load_lds_dwordx4 v[228:229], off
	v_lshl_add_u64 v[228:229], v[232:233], 0, s[18:19]
	s_mov_b32 m0, s14
	s_nop 0
	global_load_lds_dwordx4 v[228:229], off
	v_lshl_add_u64 v[228:229], v[234:235], 0, s[18:19]
	s_mov_b32 m0, s61
	s_nop 0
	global_load_lds_dwordx4 v[228:229], off
	s_waitcnt vmcnt(8)
	s_waitcnt lgkmcnt(0)
	s_barrier
	s_setprio 1
	s_waitcnt lgkmcnt(0)
	v_mfma_f32_16x16x32_bf16 v[64:67], v[142:145], v[186:189], v[64:67]
	v_mfma_f32_16x16x32_bf16 v[64:67], v[146:149], v[190:193], v[64:67]
	v_mfma_f32_16x16x32_bf16 v[60:63], v[154:157], v[186:189], v[60:63]
	v_mfma_f32_16x16x32_bf16 v[60:63], v[158:161], v[190:193], v[60:63]
	v_mfma_f32_16x16x32_bf16 v[48:51], v[142:145], v[194:197], v[48:51]
	v_mfma_f32_16x16x32_bf16 v[48:51], v[146:149], v[208:211], v[48:51]
	v_mfma_f32_16x16x32_bf16 v[44:47], v[154:157], v[194:197], v[44:47]
	v_mfma_f32_16x16x32_bf16 v[44:47], v[158:161], v[208:211], v[44:47]
	v_mfma_f32_16x16x32_bf16 v[32:35], v[142:145], v[212:215], v[32:35]
	v_mfma_f32_16x16x32_bf16 v[32:35], v[146:149], v[216:219], v[32:35]
	v_mfma_f32_16x16x32_bf16 v[28:31], v[154:157], v[212:215], v[28:31]
	v_mfma_f32_16x16x32_bf16 v[28:31], v[158:161], v[216:219], v[28:31]
	v_mfma_f32_16x16x32_bf16 v[16:19], v[142:145], v[220:223], v[16:19]
	v_mfma_f32_16x16x32_bf16 v[16:19], v[146:149], v[224:227], v[16:19]
	v_mfma_f32_16x16x32_bf16 v[12:15], v[154:157], v[220:223], v[12:15]
	v_mfma_f32_16x16x32_bf16 v[12:15], v[158:161], v[224:227], v[12:15]
	s_setprio 0
	s_setprio 1
	v_mfma_f32_16x16x32_bf16 v[56:59], v[162:165], v[186:189], v[56:59]
	v_mfma_f32_16x16x32_bf16 v[56:59], v[166:169], v[190:193], v[56:59]
	v_mfma_f32_16x16x32_bf16 v[52:55], v[178:181], v[186:189], v[52:55]
	v_mfma_f32_16x16x32_bf16 v[52:55], v[182:185], v[190:193], v[52:55]
	v_mfma_f32_16x16x32_bf16 v[40:43], v[162:165], v[194:197], v[40:43]
	v_mfma_f32_16x16x32_bf16 v[40:43], v[166:169], v[208:211], v[40:43]
	v_mfma_f32_16x16x32_bf16 v[36:39], v[178:181], v[194:197], v[36:39]
	v_mfma_f32_16x16x32_bf16 v[36:39], v[182:185], v[208:211], v[36:39]
	v_mfma_f32_16x16x32_bf16 v[24:27], v[162:165], v[212:215], v[24:27]
	v_mfma_f32_16x16x32_bf16 v[24:27], v[166:169], v[216:219], v[24:27]
	v_mfma_f32_16x16x32_bf16 v[20:23], v[178:181], v[212:215], v[20:23]
	v_mfma_f32_16x16x32_bf16 v[20:23], v[182:185], v[216:219], v[20:23]
	v_mfma_f32_16x16x32_bf16 v[8:11], v[162:165], v[220:223], v[8:11]
	v_mfma_f32_16x16x32_bf16 v[8:11], v[166:169], v[224:227], v[8:11]
	v_mfma_f32_16x16x32_bf16 v[4:7], v[178:181], v[220:223], v[4:7]
	v_mfma_f32_16x16x32_bf16 v[4:7], v[182:185], v[224:227], v[4:7]
	s_setprio 0
	s_barrier
	s_add_i32 s33, s33, 2
	s_add_u32 s8, s8, 0x100
	s_addc_u32 s9, s9, 0
	s_add_u32 s21, s21, 0x100
	s_addc_u32 s22, s22, 0
	s_cmp_gt_u32 s33, 29
	s_cbranch_scc0 .LBB0_901
	s_and_b64 vcc, exec, s[44:45]
	s_cbranch_vccz .LBB0_904
	s_barrier

.LBB0_1074:
	s_add_u32 s42, s40, 0xffe00080
	s_addc_u32 s43, s41, -1
	s_add_i32 s59, 0, 0x10000
	s_cmpk_eq_i32 s58, 0x7c
	s_cselect_b32 s45, s27, s43
	s_cselect_b32 s44, s54, s42
	v_add_u32_e32 v142, s59, v144
	s_cselect_b32 s43, s13, s57
	s_cselect_b32 s42, s55, s56
	s_add_i32 s62, 0, 0x14000
	ds_read_b128 v[148:151], v142
	ds_read_b128 v[152:155], v142 offset:1024
	ds_read_b128 v[156:159], v142 offset:2048
	ds_read_b128 v[160:163], v142 offset:3072
	v_add_u32_e32 v142, s62, v144
	ds_read_b128 v[164:167], v142
	ds_read_b128 v[178:181], v142 offset:1024
	ds_read_b128 v[182:185], v142 offset:2048
	ds_read_b128 v[186:189], v142 offset:3072
	v_lshl_add_u64 v[142:143], s[40:41], 0, v[138:139]
	s_add_i32 m0, s46, 0xc000
	ds_read_b128 v[190:193], v146
	ds_read_b128 v[194:197], v146 offset:1024
	ds_read_b128 v[208:211], v146 offset:2048
	ds_read_b128 v[212:215], v146 offset:3072
	ds_read_b128 v[216:219], v146 offset:4096
	ds_read_b128 v[220:223], v146 offset:5120
	ds_read_b128 v[224:227], v146 offset:6144
	ds_read_b128 v[228:231], v146 offset:7168
	global_load_lds_dwordx4 v[142:143], off
	v_lshl_add_u64 v[142:143], s[40:41], 0, v[140:141]
	s_add_i32 m0, s46, 0xe000
	s_nop 0
	global_load_lds_dwordx4 v[142:143], off
	s_waitcnt vmcnt(8)
	s_waitcnt lgkmcnt(0)
	s_barrier
	s_setprio 1
	s_waitcnt lgkmcnt(0)
	v_mfma_f32_16x16x32_bf16 v[128:131], v[148:151], v[190:193], v[128:131]
	v_mfma_f32_16x16x32_bf16 v[128:131], v[152:155], v[194:197], v[128:131]
	v_mfma_f32_16x16x32_bf16 v[124:127], v[156:159], v[190:193], v[124:127]
	v_mfma_f32_16x16x32_bf16 v[124:127], v[160:163], v[194:197], v[124:127]
	v_mfma_f32_16x16x32_bf16 v[120:123], v[148:151], v[208:211], v[120:123]
	v_mfma_f32_16x16x32_bf16 v[120:123], v[152:155], v[212:215], v[120:123]
	v_mfma_f32_16x16x32_bf16 v[112:115], v[156:159], v[208:211], v[112:115]
	v_mfma_f32_16x16x32_bf16 v[112:115], v[160:163], v[212:215], v[112:115]
	v_mfma_f32_16x16x32_bf16 v[104:107], v[148:151], v[216:219], v[104:107]
	v_mfma_f32_16x16x32_bf16 v[104:107], v[152:155], v[220:223], v[104:107]
	v_mfma_f32_16x16x32_bf16 v[96:99], v[156:159], v[216:219], v[96:99]
	v_mfma_f32_16x16x32_bf16 v[96:99], v[160:163], v[220:223], v[96:99]
	v_mfma_f32_16x16x32_bf16 v[88:91], v[148:151], v[224:227], v[88:91]
	v_mfma_f32_16x16x32_bf16 v[88:91], v[152:155], v[228:231], v[88:91]
	v_mfma_f32_16x16x32_bf16 v[80:83], v[156:159], v[224:227], v[80:83]
	v_mfma_f32_16x16x32_bf16 v[80:83], v[160:163], v[228:231], v[80:83]
	s_setprio 0
	s_setprio 1
	v_mfma_f32_16x16x32_bf16 v[116:119], v[164:167], v[190:193], v[116:119]
	v_mfma_f32_16x16x32_bf16 v[116:119], v[178:181], v[194:197], v[116:119]
	v_mfma_f32_16x16x32_bf16 v[108:111], v[182:185], v[190:193], v[108:111]
	v_mfma_f32_16x16x32_bf16 v[108:111], v[186:189], v[194:197], v[108:111]
	v_mfma_f32_16x16x32_bf16 v[100:103], v[164:167], v[208:211], v[100:103]
	v_mfma_f32_16x16x32_bf16 v[100:103], v[178:181], v[212:215], v[100:103]
	v_mfma_f32_16x16x32_bf16 v[92:95], v[182:185], v[208:211], v[92:95]
	v_mfma_f32_16x16x32_bf16 v[92:95], v[186:189], v[212:215], v[92:95]
	v_mfma_f32_16x16x32_bf16 v[84:87], v[164:167], v[216:219], v[84:87]
	v_mfma_f32_16x16x32_bf16 v[84:87], v[178:181], v[220:223], v[84:87]
	v_mfma_f32_16x16x32_bf16 v[76:79], v[182:185], v[216:219], v[76:79]
	v_mfma_f32_16x16x32_bf16 v[76:79], v[186:189], v[220:223], v[76:79]
	v_mfma_f32_16x16x32_bf16 v[72:75], v[164:167], v[224:227], v[72:75]
	v_mfma_f32_16x16x32_bf16 v[72:75], v[178:181], v[228:231], v[72:75]
	v_mfma_f32_16x16x32_bf16 v[68:71], v[182:185], v[224:227], v[68:71]
	v_mfma_f32_16x16x32_bf16 v[68:71], v[186:189], v[228:231], v[68:71]
	s_setprio 0
	s_barrier
	s_add_i32 s59, s59, s33
	v_lshl_add_u64 v[142:143], s[42:43], 0, v[2:3]
	s_mov_b32 m0, s59
	ds_read_b128 v[190:193], v146 offset:16384
	ds_read_b128 v[194:197], v146 offset:17408
	ds_read_b128 v[208:211], v146 offset:18432
	ds_read_b128 v[212:215], v146 offset:19456
	ds_read_b128 v[216:219], v146 offset:20480
	ds_read_b128 v[220:223], v146 offset:21504
	ds_read_b128 v[224:227], v146 offset:22528
	ds_read_b128 v[228:231], v146 offset:23552
	global_load_lds_dwordx4 v[142:143], off
	s_add_i32 m0, s59, 0x2000
	s_add_u32 s60, s42, 0x200000
	v_lshl_add_u64 v[168:169], s[42:43], 0, v[136:137]
	s_addc_u32 s61, s43, 0
	s_add_i32 s59, s62, s33
	global_load_lds_dwordx4 v[168:169], off
	v_lshl_add_u64 v[232:233], s[60:61], 0, v[2:3]
	s_mov_b32 m0, s59
	v_lshl_add_u64 v[234:235], s[44:45], 0, v[134:135]
	global_load_lds_dwordx4 v[232:233], off
	v_lshl_add_u64 v[232:233], s[60:61], 0, v[136:137]
	s_add_i32 m0, s59, 0x2000
	s_nop 0
	global_load_lds_dwordx4 v[232:233], off
	v_lshl_add_u64 v[232:233], s[44:45], 0, v[132:133]
	s_mov_b32 m0, s46
	s_nop 0
	global_load_lds_dwordx4 v[232:233], off
	s_mov_b32 m0, s47
	s_nop 0
	global_load_lds_dwordx4 v[234:235], off
	s_waitcnt vmcnt(8)
	s_waitcnt lgkmcnt(0)
	s_barrier
	s_setprio 1
	s_waitcnt lgkmcnt(0)
	v_mfma_f32_16x16x32_bf16 v[64:67], v[148:151], v[190:193], v[64:67]
	v_mfma_f32_16x16x32_bf16 v[64:67], v[152:155], v[194:197], v[64:67]
	v_mfma_f32_16x16x32_bf16 v[60:63], v[156:159], v[190:193], v[60:63]
	v_mfma_f32_16x16x32_bf16 v[60:63], v[160:163], v[194:197], v[60:63]
	v_mfma_f32_16x16x32_bf16 v[56:59], v[148:151], v[208:211], v[56:59]
	v_mfma_f32_16x16x32_bf16 v[56:59], v[152:155], v[212:215], v[56:59]
	v_mfma_f32_16x16x32_bf16 v[48:51], v[156:159], v[208:211], v[48:51]
	v_mfma_f32_16x16x32_bf16 v[48:51], v[160:163], v[212:215], v[48:51]
	v_mfma_f32_16x16x32_bf16 v[40:43], v[148:151], v[216:219], v[40:43]
	v_mfma_f32_16x16x32_bf16 v[40:43], v[152:155], v[220:223], v[40:43]
	v_mfma_f32_16x16x32_bf16 v[32:35], v[156:159], v[216:219], v[32:35]
	v_mfma_f32_16x16x32_bf16 v[32:35], v[160:163], v[220:223], v[32:35]
	v_mfma_f32_16x16x32_bf16 v[24:27], v[148:151], v[224:227], v[24:27]
	v_mfma_f32_16x16x32_bf16 v[24:27], v[152:155], v[228:231], v[24:27]
	v_mfma_f32_16x16x32_bf16 v[16:19], v[156:159], v[224:227], v[16:19]
	v_mfma_f32_16x16x32_bf16 v[16:19], v[160:163], v[228:231], v[16:19]
	s_setprio 0
	s_setprio 1
	v_mfma_f32_16x16x32_bf16 v[52:55], v[164:167], v[190:193], v[52:55]
	v_mfma_f32_16x16x32_bf16 v[52:55], v[178:181], v[194:197], v[52:55]
	v_mfma_f32_16x16x32_bf16 v[44:47], v[182:185], v[190:193], v[44:47]
	v_mfma_f32_16x16x32_bf16 v[44:47], v[186:189], v[194:197], v[44:47]
	v_mfma_f32_16x16x32_bf16 v[36:39], v[164:167], v[208:211], v[36:39]
	v_mfma_f32_16x16x32_bf16 v[36:39], v[178:181], v[212:215], v[36:39]
	v_mfma_f32_16x16x32_bf16 v[28:31], v[182:185], v[208:211], v[28:31]
	v_mfma_f32_16x16x32_bf16 v[28:31], v[186:189], v[212:215], v[28:31]
	v_mfma_f32_16x16x32_bf16 v[20:23], v[164:167], v[216:219], v[20:23]
	v_mfma_f32_16x16x32_bf16 v[20:23], v[178:181], v[220:223], v[20:23]
	v_mfma_f32_16x16x32_bf16 v[12:15], v[182:185], v[216:219], v[12:15]
	v_mfma_f32_16x16x32_bf16 v[12:15], v[186:189], v[220:223], v[12:15]
	v_mfma_f32_16x16x32_bf16 v[8:11], v[164:167], v[224:227], v[8:11]
	v_mfma_f32_16x16x32_bf16 v[8:11], v[178:181], v[228:231], v[8:11]
	v_mfma_f32_16x16x32_bf16 v[4:7], v[182:185], v[224:227], v[4:7]
	v_mfma_f32_16x16x32_bf16 v[4:7], v[186:189], v[228:231], v[4:7]
	s_setprio 0
	s_barrier
	s_add_i32 s59, 0, 0x18000
	v_add_u32_e32 v147, s59, v144
	s_add_i32 s60, 0, 0x1c000
	ds_read_b128 v[148:151], v147
	ds_read_b128 v[152:155], v147 offset:1024
	ds_read_b128 v[156:159], v147 offset:2048
	ds_read_b128 v[160:163], v147 offset:3072
	v_add_u32_e32 v147, s60, v144
	ds_read_b128 v[164:167], v147
	ds_read_b128 v[178:181], v147 offset:1024
	ds_read_b128 v[182:185], v147 offset:2048
	ds_read_b128 v[186:189], v147 offset:3072
	s_add_u32 s44, s44, 0x200000
	s_addc_u32 s45, s45, 0
	s_mov_b32 m0, s48
	v_lshl_add_u64 v[236:237], s[44:45], 0, v[132:133]
	ds_read_b128 v[190:193], v146 offset:32768
	ds_read_b128 v[194:197], v146 offset:33792
	ds_read_b128 v[208:211], v146 offset:34816
	ds_read_b128 v[212:215], v146 offset:35840
	ds_read_b128 v[216:219], v146 offset:36864
	ds_read_b128 v[220:223], v146 offset:37888
	ds_read_b128 v[224:227], v146 offset:38912
	ds_read_b128 v[228:231], v146 offset:39936
	global_load_lds_dwordx4 v[236:237], off
	v_lshl_add_u64 v[236:237], s[44:45], 0, v[134:135]
	s_mov_b32 m0, s49
	s_nop 0
	global_load_lds_dwordx4 v[236:237], off
	s_waitcnt vmcnt(8)
	s_waitcnt lgkmcnt(0)
	s_barrier
	s_setprio 1
	s_waitcnt lgkmcnt(0)
	v_mfma_f32_16x16x32_bf16 v[128:131], v[148:151], v[190:193], v[128:131]
	v_mfma_f32_16x16x32_bf16 v[128:131], v[152:155], v[194:197], v[128:131]
	v_mfma_f32_16x16x32_bf16 v[124:127], v[156:159], v[190:193], v[124:127]
	v_mfma_f32_16x16x32_bf16 v[124:127], v[160:163], v[194:197], v[124:127]
	v_mfma_f32_16x16x32_bf16 v[120:123], v[148:151], v[208:211], v[120:123]
	v_mfma_f32_16x16x32_bf16 v[120:123], v[152:155], v[212:215], v[120:123]
	v_mfma_f32_16x16x32_bf16 v[112:115], v[156:159], v[208:211], v[112:115]
	v_mfma_f32_16x16x32_bf16 v[112:115], v[160:163], v[212:215], v[112:115]
	v_mfma_f32_16x16x32_bf16 v[104:107], v[148:151], v[216:219], v[104:107]
	v_mfma_f32_16x16x32_bf16 v[104:107], v[152:155], v[220:223], v[104:107]
	v_mfma_f32_16x16x32_bf16 v[96:99], v[156:159], v[216:219], v[96:99]
	v_mfma_f32_16x16x32_bf16 v[96:99], v[160:163], v[220:223], v[96:99]
	v_mfma_f32_16x16x32_bf16 v[88:91], v[148:151], v[224:227], v[88:91]
	v_mfma_f32_16x16x32_bf16 v[88:91], v[152:155], v[228:231], v[88:91]
	v_mfma_f32_16x16x32_bf16 v[80:83], v[156:159], v[224:227], v[80:83]
	v_mfma_f32_16x16x32_bf16 v[80:83], v[160:163], v[228:231], v[80:83]
	s_setprio 0
	s_setprio 1
	v_mfma_f32_16x16x32_bf16 v[116:119], v[164:167], v[190:193], v[116:119]
	v_mfma_f32_16x16x32_bf16 v[116:119], v[178:181], v[194:197], v[116:119]
	v_mfma_f32_16x16x32_bf16 v[108:111], v[182:185], v[190:193], v[108:111]
	v_mfma_f32_16x16x32_bf16 v[108:111], v[186:189], v[194:197], v[108:111]
	v_mfma_f32_16x16x32_bf16 v[100:103], v[164:167], v[208:211], v[100:103]
	v_mfma_f32_16x16x32_bf16 v[100:103], v[178:181], v[212:215], v[100:103]
	v_mfma_f32_16x16x32_bf16 v[92:95], v[182:185], v[208:211], v[92:95]
	v_mfma_f32_16x16x32_bf16 v[92:95], v[186:189], v[212:215], v[92:95]
	v_mfma_f32_16x16x32_bf16 v[84:87], v[164:167], v[216:219], v[84:87]
	v_mfma_f32_16x16x32_bf16 v[84:87], v[178:181], v[220:223], v[84:87]
	v_mfma_f32_16x16x32_bf16 v[76:79], v[182:185], v[216:219], v[76:79]
	v_mfma_f32_16x16x32_bf16 v[76:79], v[186:189], v[220:223], v[76:79]
	v_mfma_f32_16x16x32_bf16 v[72:75], v[164:167], v[224:227], v[72:75]
	v_mfma_f32_16x16x32_bf16 v[72:75], v[178:181], v[228:231], v[72:75]
	v_mfma_f32_16x16x32_bf16 v[68:71], v[182:185], v[224:227], v[68:71]
	v_mfma_f32_16x16x32_bf16 v[68:71], v[186:189], v[228:231], v[68:71]
	s_setprio 0
	s_barrier
	s_add_i32 s44, s59, s33
	v_lshl_add_u64 v[142:143], v[142:143], 0, s[18:19]
	s_mov_b32 m0, s44
	ds_read_b128 v[190:193], v146 offset:49152
	ds_read_b128 v[194:197], v146 offset:50176
	ds_read_b128 v[208:211], v146 offset:51200
	ds_read_b128 v[212:215], v146 offset:52224
	ds_read_b128 v[216:219], v146 offset:53248
	ds_read_b128 v[220:223], v146 offset:54272
	ds_read_b128 v[224:227], v146 offset:55296
	ds_read_b128 v[228:231], v146 offset:56320
	global_load_lds_dwordx4 v[142:143], off
	s_add_i32 m0, s44, 0x2000
	s_add_u32 s42, s42, 0x200080
	v_lshl_add_u64 v[142:143], v[168:169], 0, s[18:19]
	s_addc_u32 s43, s43, 0
	s_add_i32 s44, s60, s33
	global_load_lds_dwordx4 v[142:143], off
	v_lshl_add_u64 v[142:143], s[42:43], 0, v[2:3]
	s_mov_b32 m0, s44
	s_nop 0
	global_load_lds_dwordx4 v[142:143], off
	v_lshl_add_u64 v[142:143], s[42:43], 0, v[136:137]
	s_add_i32 m0, s44, 0x2000
	s_nop 0
	global_load_lds_dwordx4 v[142:143], off
	v_lshl_add_u64 v[142:143], v[232:233], 0, s[18:19]
	s_mov_b32 m0, s50
	s_nop 0
	global_load_lds_dwordx4 v[142:143], off
	v_lshl_add_u64 v[142:143], v[234:235], 0, s[18:19]
	s_mov_b32 m0, s51
	s_nop 0
	global_load_lds_dwordx4 v[142:143], off
	s_waitcnt vmcnt(8)
	s_waitcnt lgkmcnt(0)
	s_barrier
	s_setprio 1
	s_waitcnt lgkmcnt(0)
	v_mfma_f32_16x16x32_bf16 v[64:67], v[148:151], v[190:193], v[64:67]
	v_mfma_f32_16x16x32_bf16 v[64:67], v[152:155], v[194:197], v[64:67]
	v_mfma_f32_16x16x32_bf16 v[60:63], v[156:159], v[190:193], v[60:63]
	v_mfma_f32_16x16x32_bf16 v[60:63], v[160:163], v[194:197], v[60:63]
	v_mfma_f32_16x16x32_bf16 v[56:59], v[148:151], v[208:211], v[56:59]
	v_mfma_f32_16x16x32_bf16 v[56:59], v[152:155], v[212:215], v[56:59]
	v_mfma_f32_16x16x32_bf16 v[48:51], v[156:159], v[208:211], v[48:51]
	v_mfma_f32_16x16x32_bf16 v[48:51], v[160:163], v[212:215], v[48:51]
	v_mfma_f32_16x16x32_bf16 v[40:43], v[148:151], v[216:219], v[40:43]
	v_mfma_f32_16x16x32_bf16 v[40:43], v[152:155], v[220:223], v[40:43]
	v_mfma_f32_16x16x32_bf16 v[32:35], v[156:159], v[216:219], v[32:35]
	v_mfma_f32_16x16x32_bf16 v[32:35], v[160:163], v[220:223], v[32:35]
	v_mfma_f32_16x16x32_bf16 v[24:27], v[148:151], v[224:227], v[24:27]
	v_mfma_f32_16x16x32_bf16 v[24:27], v[152:155], v[228:231], v[24:27]
	v_mfma_f32_16x16x32_bf16 v[16:19], v[156:159], v[224:227], v[16:19]
	v_mfma_f32_16x16x32_bf16 v[16:19], v[160:163], v[228:231], v[16:19]
	s_setprio 0
	s_setprio 1
	v_mfma_f32_16x16x32_bf16 v[52:55], v[164:167], v[190:193], v[52:55]
	v_mfma_f32_16x16x32_bf16 v[52:55], v[178:181], v[194:197], v[52:55]
	v_mfma_f32_16x16x32_bf16 v[44:47], v[182:185], v[190:193], v[44:47]
	v_mfma_f32_16x16x32_bf16 v[44:47], v[186:189], v[194:197], v[44:47]
	v_mfma_f32_16x16x32_bf16 v[36:39], v[164:167], v[208:211], v[36:39]
	v_mfma_f32_16x16x32_bf16 v[36:39], v[178:181], v[212:215], v[36:39]
	v_mfma_f32_16x16x32_bf16 v[28:31], v[182:185], v[208:211], v[28:31]
	v_mfma_f32_16x16x32_bf16 v[28:31], v[186:189], v[212:215], v[28:31]
	v_mfma_f32_16x16x32_bf16 v[20:23], v[164:167], v[216:219], v[20:23]
	v_mfma_f32_16x16x32_bf16 v[20:23], v[178:181], v[220:223], v[20:23]
	v_mfma_f32_16x16x32_bf16 v[12:15], v[182:185], v[216:219], v[12:15]
	v_mfma_f32_16x16x32_bf16 v[12:15], v[186:189], v[220:223], v[12:15]
	v_mfma_f32_16x16x32_bf16 v[8:11], v[164:167], v[224:227], v[8:11]
	v_mfma_f32_16x16x32_bf16 v[8:11], v[178:181], v[228:231], v[8:11]
	v_mfma_f32_16x16x32_bf16 v[4:7], v[182:185], v[224:227], v[4:7]
	v_mfma_f32_16x16x32_bf16 v[4:7], v[186:189], v[228:231], v[4:7]
	s_setprio 0
	s_barrier
	s_add_i32 s58, s58, 2
	s_add_u32 s40, s40, 0x100
	s_addc_u32 s41, s41, 0
	s_add_u32 s56, s56, 0x100
	s_addc_u32 s57, s57, 0
	s_cmpk_gt_u32 s58, 0x7d
	s_cbranch_scc0 .LBB0_1074
	s_and_b64 vcc, exec, s[8:9]
	s_cbranch_vccz .LBB0_1077
	s_barrier

.LBB0_1088:
	s_add_u32 s38, s36, 0xffe00080
	s_addc_u32 s39, s37, -1
	s_add_i32 s55, 0, 0x10000
	s_cmp_eq_u32 s54, 12
	s_cselect_b32 s41, s3, s39
	s_cselect_b32 s40, s49, s38
	v_add_u32_e32 v2, s55, v140
	s_cselect_b32 s39, s50, s53
	s_cselect_b32 s38, s51, s52
	s_add_i32 s58, 0, 0x14000
	ds_read_b128 v[144:147], v2
	ds_read_b128 v[148:151], v2 offset:1024
	ds_read_b128 v[152:155], v2 offset:2048
	ds_read_b128 v[156:159], v2 offset:3072
	v_add_u32_e32 v2, s58, v140
	ds_read_b128 v[160:163], v2
	ds_read_b128 v[164:167], v2 offset:1024
	ds_read_b128 v[178:181], v2 offset:2048
	ds_read_b128 v[182:185], v2 offset:3072
	v_lshl_add_u64 v[168:169], s[36:37], 0, v[136:137]
	s_add_i32 m0, s42, 0xc000
	ds_read_b128 v[186:189], v142
	ds_read_b128 v[190:193], v142 offset:1024
	ds_read_b128 v[194:197], v142 offset:2048
	ds_read_b128 v[208:211], v142 offset:3072
	ds_read_b128 v[212:215], v142 offset:4096
	ds_read_b128 v[216:219], v142 offset:5120
	ds_read_b128 v[220:223], v142 offset:6144
	ds_read_b128 v[224:227], v142 offset:7168
	global_load_lds_dwordx4 v[168:169], off
	v_lshl_add_u64 v[168:169], s[36:37], 0, v[138:139]
	s_add_i32 m0, s42, 0xe000
	s_nop 0
	global_load_lds_dwordx4 v[168:169], off
	s_waitcnt vmcnt(8)
	s_waitcnt lgkmcnt(0)
	s_barrier
	s_setprio 1
	s_waitcnt lgkmcnt(0)
	v_mfma_f32_16x16x32_bf16 v[128:131], v[144:147], v[186:189], v[128:131]
	v_mfma_f32_16x16x32_bf16 v[128:131], v[148:151], v[190:193], v[128:131]
	v_mfma_f32_16x16x32_bf16 v[124:127], v[152:155], v[186:189], v[124:127]
	v_mfma_f32_16x16x32_bf16 v[124:127], v[156:159], v[190:193], v[124:127]
	v_mfma_f32_16x16x32_bf16 v[120:123], v[144:147], v[194:197], v[120:123]
	v_mfma_f32_16x16x32_bf16 v[120:123], v[148:151], v[208:211], v[120:123]
	v_mfma_f32_16x16x32_bf16 v[116:119], v[152:155], v[194:197], v[116:119]
	v_mfma_f32_16x16x32_bf16 v[116:119], v[156:159], v[208:211], v[116:119]
	v_mfma_f32_16x16x32_bf16 v[108:111], v[144:147], v[212:215], v[108:111]
	v_mfma_f32_16x16x32_bf16 v[108:111], v[148:151], v[216:219], v[108:111]
	v_mfma_f32_16x16x32_bf16 v[100:103], v[152:155], v[212:215], v[100:103]
	v_mfma_f32_16x16x32_bf16 v[100:103], v[156:159], v[216:219], v[100:103]
	v_mfma_f32_16x16x32_bf16 v[92:95], v[144:147], v[220:223], v[92:95]
	v_mfma_f32_16x16x32_bf16 v[92:95], v[148:151], v[224:227], v[92:95]
	v_mfma_f32_16x16x32_bf16 v[84:87], v[152:155], v[220:223], v[84:87]
	v_mfma_f32_16x16x32_bf16 v[84:87], v[156:159], v[224:227], v[84:87]
	s_setprio 0
	s_setprio 1
	v_mfma_f32_16x16x32_bf16 v[112:115], v[160:163], v[186:189], v[112:115]
	v_mfma_f32_16x16x32_bf16 v[112:115], v[164:167], v[190:193], v[112:115]
	v_mfma_f32_16x16x32_bf16 v[104:107], v[178:181], v[186:189], v[104:107]
	v_mfma_f32_16x16x32_bf16 v[104:107], v[182:185], v[190:193], v[104:107]
	v_mfma_f32_16x16x32_bf16 v[96:99], v[160:163], v[194:197], v[96:99]
	v_mfma_f32_16x16x32_bf16 v[96:99], v[164:167], v[208:211], v[96:99]
	v_mfma_f32_16x16x32_bf16 v[88:91], v[178:181], v[194:197], v[88:91]
	v_mfma_f32_16x16x32_bf16 v[88:91], v[182:185], v[208:211], v[88:91]
	v_mfma_f32_16x16x32_bf16 v[80:83], v[160:163], v[212:215], v[80:83]
	v_mfma_f32_16x16x32_bf16 v[80:83], v[164:167], v[216:219], v[80:83]
	v_mfma_f32_16x16x32_bf16 v[76:79], v[178:181], v[212:215], v[76:79]
	v_mfma_f32_16x16x32_bf16 v[76:79], v[182:185], v[216:219], v[76:79]
	v_mfma_f32_16x16x32_bf16 v[72:75], v[160:163], v[220:223], v[72:75]
	v_mfma_f32_16x16x32_bf16 v[72:75], v[164:167], v[224:227], v[72:75]
	v_mfma_f32_16x16x32_bf16 v[68:71], v[178:181], v[220:223], v[68:71]
	v_mfma_f32_16x16x32_bf16 v[68:71], v[182:185], v[224:227], v[68:71]
	s_setprio 0
	s_barrier
	s_add_i32 s55, s55, s25
	v_lshl_add_u64 v[168:169], s[38:39], 0, v[134:135]
	s_mov_b32 m0, s55
	ds_read_b128 v[186:189], v142 offset:16384
	ds_read_b128 v[190:193], v142 offset:17408
	ds_read_b128 v[194:197], v142 offset:18432
	ds_read_b128 v[208:211], v142 offset:19456
	ds_read_b128 v[212:215], v142 offset:20480
	ds_read_b128 v[216:219], v142 offset:21504
	ds_read_b128 v[220:223], v142 offset:22528
	ds_read_b128 v[224:227], v142 offset:23552
	global_load_lds_dwordx4 v[168:169], off
	s_add_i32 m0, s55, 0x2000
	s_add_u32 s56, s38, 0x200000
	v_lshl_add_u64 v[228:229], s[38:39], 0, v[132:133]
	s_addc_u32 s57, s39, 0
	s_add_i32 s55, s58, s25
	global_load_lds_dwordx4 v[228:229], off
	v_lshl_add_u64 v[230:231], s[56:57], 0, v[134:135]
	s_mov_b32 m0, s55
	v_lshl_add_u64 v[232:233], s[40:41], 0, v[132:133]
	global_load_lds_dwordx4 v[230:231], off
	v_lshl_add_u64 v[230:231], s[56:57], 0, v[132:133]
	s_add_i32 m0, s55, 0x2000
	s_nop 0
	global_load_lds_dwordx4 v[230:231], off
	v_lshl_add_u64 v[230:231], s[40:41], 0, v[134:135]
	s_mov_b32 m0, s42
	s_nop 0
	global_load_lds_dwordx4 v[230:231], off
	s_mov_b32 m0, s43
	s_nop 0
	global_load_lds_dwordx4 v[232:233], off
	s_waitcnt vmcnt(8)
	s_waitcnt lgkmcnt(0)
	s_barrier
	s_setprio 1
	s_waitcnt lgkmcnt(0)
	v_mfma_f32_16x16x32_bf16 v[64:67], v[144:147], v[186:189], v[64:67]
	v_mfma_f32_16x16x32_bf16 v[64:67], v[148:151], v[190:193], v[64:67]
	v_mfma_f32_16x16x32_bf16 v[60:63], v[152:155], v[186:189], v[60:63]
	v_mfma_f32_16x16x32_bf16 v[60:63], v[156:159], v[190:193], v[60:63]
	v_mfma_f32_16x16x32_bf16 v[56:59], v[144:147], v[194:197], v[56:59]
	v_mfma_f32_16x16x32_bf16 v[56:59], v[148:151], v[208:211], v[56:59]
	v_mfma_f32_16x16x32_bf16 v[52:55], v[152:155], v[194:197], v[52:55]
	v_mfma_f32_16x16x32_bf16 v[52:55], v[156:159], v[208:211], v[52:55]
	v_mfma_f32_16x16x32_bf16 v[40:43], v[144:147], v[212:215], v[40:43]
	v_mfma_f32_16x16x32_bf16 v[40:43], v[148:151], v[216:219], v[40:43]
	v_mfma_f32_16x16x32_bf16 v[36:39], v[152:155], v[212:215], v[36:39]
	v_mfma_f32_16x16x32_bf16 v[36:39], v[156:159], v[216:219], v[36:39]
	v_mfma_f32_16x16x32_bf16 v[24:27], v[144:147], v[220:223], v[24:27]
	v_mfma_f32_16x16x32_bf16 v[24:27], v[148:151], v[224:227], v[24:27]
	v_mfma_f32_16x16x32_bf16 v[20:23], v[152:155], v[220:223], v[20:23]
	v_mfma_f32_16x16x32_bf16 v[20:23], v[156:159], v[224:227], v[20:23]
	s_setprio 0
	s_setprio 1
	v_mfma_f32_16x16x32_bf16 v[48:51], v[160:163], v[186:189], v[48:51]
	v_mfma_f32_16x16x32_bf16 v[48:51], v[164:167], v[190:193], v[48:51]
	v_mfma_f32_16x16x32_bf16 v[44:47], v[178:181], v[186:189], v[44:47]
	v_mfma_f32_16x16x32_bf16 v[44:47], v[182:185], v[190:193], v[44:47]
	v_mfma_f32_16x16x32_bf16 v[32:35], v[160:163], v[194:197], v[32:35]
	v_mfma_f32_16x16x32_bf16 v[32:35], v[164:167], v[208:211], v[32:35]
	v_mfma_f32_16x16x32_bf16 v[28:31], v[178:181], v[194:197], v[28:31]
	v_mfma_f32_16x16x32_bf16 v[28:31], v[182:185], v[208:211], v[28:31]
	v_mfma_f32_16x16x32_bf16 v[16:19], v[160:163], v[212:215], v[16:19]
	v_mfma_f32_16x16x32_bf16 v[16:19], v[164:167], v[216:219], v[16:19]
	v_mfma_f32_16x16x32_bf16 v[12:15], v[178:181], v[212:215], v[12:15]
	v_mfma_f32_16x16x32_bf16 v[12:15], v[182:185], v[216:219], v[12:15]
	v_mfma_f32_16x16x32_bf16 v[8:11], v[160:163], v[220:223], v[8:11]
	v_mfma_f32_16x16x32_bf16 v[8:11], v[164:167], v[224:227], v[8:11]
	v_mfma_f32_16x16x32_bf16 v[4:7], v[178:181], v[220:223], v[4:7]
	v_mfma_f32_16x16x32_bf16 v[4:7], v[182:185], v[224:227], v[4:7]
	s_setprio 0
	s_barrier
	s_add_i32 s55, 0, 0x18000
	v_add_u32_e32 v2, s55, v140
	s_add_i32 s56, 0, 0x1c000
	ds_read_b128 v[144:147], v2
	ds_read_b128 v[148:151], v2 offset:1024
	ds_read_b128 v[152:155], v2 offset:2048
	ds_read_b128 v[156:159], v2 offset:3072
	v_add_u32_e32 v2, s56, v140
	ds_read_b128 v[160:163], v2
	ds_read_b128 v[164:167], v2 offset:1024
	ds_read_b128 v[178:181], v2 offset:2048
	ds_read_b128 v[182:185], v2 offset:3072
	s_add_u32 s40, s40, 0x200000
	s_addc_u32 s41, s41, 0
	s_mov_b32 m0, s44
	v_lshl_add_u64 v[234:235], s[40:41], 0, v[134:135]
	ds_read_b128 v[186:189], v142 offset:32768
	ds_read_b128 v[190:193], v142 offset:33792
	ds_read_b128 v[194:197], v142 offset:34816
	ds_read_b128 v[208:211], v142 offset:35840
	ds_read_b128 v[212:215], v142 offset:36864
	ds_read_b128 v[216:219], v142 offset:37888
	ds_read_b128 v[220:223], v142 offset:38912
	ds_read_b128 v[224:227], v142 offset:39936
	global_load_lds_dwordx4 v[234:235], off
	v_lshl_add_u64 v[234:235], s[40:41], 0, v[132:133]
	s_mov_b32 m0, s45
	s_nop 0
	global_load_lds_dwordx4 v[234:235], off
	s_waitcnt vmcnt(8)
	s_waitcnt lgkmcnt(0)
	s_barrier
	s_setprio 1
	s_waitcnt lgkmcnt(0)
	v_mfma_f32_16x16x32_bf16 v[128:131], v[144:147], v[186:189], v[128:131]
	v_mfma_f32_16x16x32_bf16 v[128:131], v[148:151], v[190:193], v[128:131]
	v_mfma_f32_16x16x32_bf16 v[124:127], v[152:155], v[186:189], v[124:127]
	v_mfma_f32_16x16x32_bf16 v[124:127], v[156:159], v[190:193], v[124:127]
	v_mfma_f32_16x16x32_bf16 v[120:123], v[144:147], v[194:197], v[120:123]
	v_mfma_f32_16x16x32_bf16 v[120:123], v[148:151], v[208:211], v[120:123]
	v_mfma_f32_16x16x32_bf16 v[116:119], v[152:155], v[194:197], v[116:119]
	v_mfma_f32_16x16x32_bf16 v[116:119], v[156:159], v[208:211], v[116:119]
	v_mfma_f32_16x16x32_bf16 v[108:111], v[144:147], v[212:215], v[108:111]
	v_mfma_f32_16x16x32_bf16 v[108:111], v[148:151], v[216:219], v[108:111]
	v_mfma_f32_16x16x32_bf16 v[100:103], v[152:155], v[212:215], v[100:103]
	v_mfma_f32_16x16x32_bf16 v[100:103], v[156:159], v[216:219], v[100:103]
	v_mfma_f32_16x16x32_bf16 v[92:95], v[144:147], v[220:223], v[92:95]
	v_mfma_f32_16x16x32_bf16 v[92:95], v[148:151], v[224:227], v[92:95]
	v_mfma_f32_16x16x32_bf16 v[84:87], v[152:155], v[220:223], v[84:87]
	v_mfma_f32_16x16x32_bf16 v[84:87], v[156:159], v[224:227], v[84:87]
	s_setprio 0
	s_setprio 1
	v_mfma_f32_16x16x32_bf16 v[112:115], v[160:163], v[186:189], v[112:115]
	v_mfma_f32_16x16x32_bf16 v[112:115], v[164:167], v[190:193], v[112:115]
	v_mfma_f32_16x16x32_bf16 v[104:107], v[178:181], v[186:189], v[104:107]
	v_mfma_f32_16x16x32_bf16 v[104:107], v[182:185], v[190:193], v[104:107]
	v_mfma_f32_16x16x32_bf16 v[96:99], v[160:163], v[194:197], v[96:99]
	v_mfma_f32_16x16x32_bf16 v[96:99], v[164:167], v[208:211], v[96:99]
	v_mfma_f32_16x16x32_bf16 v[88:91], v[178:181], v[194:197], v[88:91]
	v_mfma_f32_16x16x32_bf16 v[88:91], v[182:185], v[208:211], v[88:91]
	v_mfma_f32_16x16x32_bf16 v[80:83], v[160:163], v[212:215], v[80:83]
	v_mfma_f32_16x16x32_bf16 v[80:83], v[164:167], v[216:219], v[80:83]
	v_mfma_f32_16x16x32_bf16 v[76:79], v[178:181], v[212:215], v[76:79]
	v_mfma_f32_16x16x32_bf16 v[76:79], v[182:185], v[216:219], v[76:79]
	v_mfma_f32_16x16x32_bf16 v[72:75], v[160:163], v[220:223], v[72:75]
	v_mfma_f32_16x16x32_bf16 v[72:75], v[164:167], v[224:227], v[72:75]
	v_mfma_f32_16x16x32_bf16 v[68:71], v[178:181], v[220:223], v[68:71]
	v_mfma_f32_16x16x32_bf16 v[68:71], v[182:185], v[224:227], v[68:71]
	s_setprio 0
	s_barrier
	s_add_i32 s40, s55, s25
	v_lshl_add_u64 v[168:169], v[168:169], 0, s[18:19]
	s_mov_b32 m0, s40
	ds_read_b128 v[186:189], v142 offset:49152
	ds_read_b128 v[190:193], v142 offset:50176
	ds_read_b128 v[194:197], v142 offset:51200
	ds_read_b128 v[208:211], v142 offset:52224
	ds_read_b128 v[212:215], v142 offset:53248
	ds_read_b128 v[216:219], v142 offset:54272
	ds_read_b128 v[220:223], v142 offset:55296
	ds_read_b128 v[224:227], v142 offset:56320
	global_load_lds_dwordx4 v[168:169], off
	s_add_i32 m0, s40, 0x2000
	s_add_u32 s38, s38, 0x200080
	v_lshl_add_u64 v[168:169], v[228:229], 0, s[18:19]
	s_addc_u32 s39, s39, 0
	s_add_i32 s40, s56, s25
	global_load_lds_dwordx4 v[168:169], off
	v_lshl_add_u64 v[168:169], s[38:39], 0, v[134:135]
	s_mov_b32 m0, s40
	s_nop 0
	global_load_lds_dwordx4 v[168:169], off
	v_lshl_add_u64 v[168:169], s[38:39], 0, v[132:133]
	s_add_i32 m0, s40, 0x2000
	s_nop 0
	global_load_lds_dwordx4 v[168:169], off
	v_lshl_add_u64 v[168:169], v[230:231], 0, s[18:19]
	s_mov_b32 m0, s1
	s_nop 0
	global_load_lds_dwordx4 v[168:169], off
	v_lshl_add_u64 v[168:169], v[232:233], 0, s[18:19]
	s_mov_b32 m0, s7
	s_nop 0
	global_load_lds_dwordx4 v[168:169], off
	s_waitcnt vmcnt(8)
	s_waitcnt lgkmcnt(0)
	s_barrier
	s_setprio 1
	s_waitcnt lgkmcnt(0)
	v_mfma_f32_16x16x32_bf16 v[64:67], v[144:147], v[186:189], v[64:67]
	v_mfma_f32_16x16x32_bf16 v[64:67], v[148:151], v[190:193], v[64:67]
	v_mfma_f32_16x16x32_bf16 v[60:63], v[152:155], v[186:189], v[60:63]
	v_mfma_f32_16x16x32_bf16 v[60:63], v[156:159], v[190:193], v[60:63]
	v_mfma_f32_16x16x32_bf16 v[56:59], v[144:147], v[194:197], v[56:59]
	v_mfma_f32_16x16x32_bf16 v[56:59], v[148:151], v[208:211], v[56:59]
	v_mfma_f32_16x16x32_bf16 v[52:55], v[152:155], v[194:197], v[52:55]
	v_mfma_f32_16x16x32_bf16 v[52:55], v[156:159], v[208:211], v[52:55]
	v_mfma_f32_16x16x32_bf16 v[40:43], v[144:147], v[212:215], v[40:43]
	v_mfma_f32_16x16x32_bf16 v[40:43], v[148:151], v[216:219], v[40:43]
	v_mfma_f32_16x16x32_bf16 v[36:39], v[152:155], v[212:215], v[36:39]
	v_mfma_f32_16x16x32_bf16 v[36:39], v[156:159], v[216:219], v[36:39]
	v_mfma_f32_16x16x32_bf16 v[24:27], v[144:147], v[220:223], v[24:27]
	v_mfma_f32_16x16x32_bf16 v[24:27], v[148:151], v[224:227], v[24:27]
	v_mfma_f32_16x16x32_bf16 v[20:23], v[152:155], v[220:223], v[20:23]
	v_mfma_f32_16x16x32_bf16 v[20:23], v[156:159], v[224:227], v[20:23]
	s_setprio 0
	s_setprio 1
	v_mfma_f32_16x16x32_bf16 v[48:51], v[160:163], v[186:189], v[48:51]
	v_mfma_f32_16x16x32_bf16 v[48:51], v[164:167], v[190:193], v[48:51]
	v_mfma_f32_16x16x32_bf16 v[44:47], v[178:181], v[186:189], v[44:47]
	v_mfma_f32_16x16x32_bf16 v[44:47], v[182:185], v[190:193], v[44:47]
	v_mfma_f32_16x16x32_bf16 v[32:35], v[160:163], v[194:197], v[32:35]
	v_mfma_f32_16x16x32_bf16 v[32:35], v[164:167], v[208:211], v[32:35]
	v_mfma_f32_16x16x32_bf16 v[28:31], v[178:181], v[194:197], v[28:31]
	v_mfma_f32_16x16x32_bf16 v[28:31], v[182:185], v[208:211], v[28:31]
	v_mfma_f32_16x16x32_bf16 v[16:19], v[160:163], v[212:215], v[16:19]
	v_mfma_f32_16x16x32_bf16 v[16:19], v[164:167], v[216:219], v[16:19]
	v_mfma_f32_16x16x32_bf16 v[12:15], v[178:181], v[212:215], v[12:15]
	v_mfma_f32_16x16x32_bf16 v[12:15], v[182:185], v[216:219], v[12:15]
	v_mfma_f32_16x16x32_bf16 v[8:11], v[160:163], v[220:223], v[8:11]
	v_mfma_f32_16x16x32_bf16 v[8:11], v[164:167], v[224:227], v[8:11]
	v_mfma_f32_16x16x32_bf16 v[4:7], v[178:181], v[220:223], v[4:7]
	v_mfma_f32_16x16x32_bf16 v[4:7], v[182:185], v[224:227], v[4:7]
	s_setprio 0
	s_barrier
	s_add_i32 s54, s54, 2
	s_add_u32 s36, s36, 0x100
	s_addc_u32 s37, s37, 0
	s_add_u32 s52, s52, 0x100
	s_addc_u32 s53, s53, 0
	s_cmp_gt_u32 s54, 13
	s_cbranch_scc0 .LBB0_1088
	s_and_b64 vcc, exec, s[28:29]
	s_cbranch_vccz .LBB0_1091
	s_barrier

.LBB0_1184:
	s_add_u32 s8, s4, 0xfff80080
	s_addc_u32 s9, s5, -1
	s_add_i32 s26, 0, 0x10000
	s_cmp_eq_u32 s22, 28
	s_cselect_b32 s13, s1, s9
	s_cselect_b32 s12, s3, s8
	v_add_u32_e32 v1, s26, v162
	s_cselect_b32 s9, s7, s21
	s_cselect_b32 s8, s10, s11
	s_add_i32 s33, 0, 0x14000
	ds_read_b128 v[148:151], v1
	ds_read_b128 v[152:155], v1 offset:1024
	ds_read_b128 v[156:159], v1 offset:2048
	ds_read_b128 v[166:169], v1 offset:3072
	v_add_u32_e32 v1, s33, v162
	ds_read_b128 v[178:181], v1
	ds_read_b128 v[182:185], v1 offset:1024
	ds_read_b128 v[186:189], v1 offset:2048
	ds_read_b128 v[190:193], v1 offset:3072
	v_lshl_add_u64 v[236:237], s[4:5], 0, v[144:145]
	s_add_i32 m0, s47, 0xc000
	ds_read_b128 v[194:197], v165
	ds_read_b128 v[208:211], v165 offset:1024
	ds_read_b128 v[212:215], v165 offset:2048
	ds_read_b128 v[216:219], v165 offset:3072
	ds_read_b128 v[220:223], v165 offset:4096
	ds_read_b128 v[224:227], v165 offset:5120
	ds_read_b128 v[228:231], v165 offset:6144
	ds_read_b128 v[232:235], v165 offset:7168
	global_load_lds_dwordx4 v[236:237], off
	v_lshl_add_u64 v[236:237], s[4:5], 0, v[146:147]
	s_add_i32 m0, s47, 0xe000
	s_nop 0
	global_load_lds_dwordx4 v[236:237], off
	s_waitcnt vmcnt(8)
	s_waitcnt lgkmcnt(0)
	s_barrier
	s_setprio 1
	s_waitcnt lgkmcnt(0)
	v_mfma_f32_16x16x32_bf16 v[128:131], v[148:151], v[194:197], v[128:131]
	v_mfma_f32_16x16x32_bf16 v[128:131], v[152:155], v[208:211], v[128:131]
	v_mfma_f32_16x16x32_bf16 v[124:127], v[156:159], v[194:197], v[124:127]
	v_mfma_f32_16x16x32_bf16 v[124:127], v[166:169], v[208:211], v[124:127]
	v_mfma_f32_16x16x32_bf16 v[112:115], v[148:151], v[212:215], v[112:115]
	v_mfma_f32_16x16x32_bf16 v[112:115], v[152:155], v[216:219], v[112:115]
	v_mfma_f32_16x16x32_bf16 v[108:111], v[156:159], v[212:215], v[108:111]
	v_mfma_f32_16x16x32_bf16 v[108:111], v[166:169], v[216:219], v[108:111]
	v_mfma_f32_16x16x32_bf16 v[96:99], v[148:151], v[220:223], v[96:99]
	v_mfma_f32_16x16x32_bf16 v[96:99], v[152:155], v[224:227], v[96:99]
	v_mfma_f32_16x16x32_bf16 v[92:95], v[156:159], v[220:223], v[92:95]
	v_mfma_f32_16x16x32_bf16 v[92:95], v[166:169], v[224:227], v[92:95]
	v_mfma_f32_16x16x32_bf16 v[80:83], v[148:151], v[228:231], v[80:83]
	v_mfma_f32_16x16x32_bf16 v[80:83], v[152:155], v[232:235], v[80:83]
	v_mfma_f32_16x16x32_bf16 v[76:79], v[156:159], v[228:231], v[76:79]
	v_mfma_f32_16x16x32_bf16 v[76:79], v[166:169], v[232:235], v[76:79]
	s_setprio 0
	s_setprio 1
	v_mfma_f32_16x16x32_bf16 v[120:123], v[178:181], v[194:197], v[120:123]
	v_mfma_f32_16x16x32_bf16 v[120:123], v[182:185], v[208:211], v[120:123]
	v_mfma_f32_16x16x32_bf16 v[116:119], v[186:189], v[194:197], v[116:119]
	v_mfma_f32_16x16x32_bf16 v[116:119], v[190:193], v[208:211], v[116:119]
	v_mfma_f32_16x16x32_bf16 v[104:107], v[178:181], v[212:215], v[104:107]
	v_mfma_f32_16x16x32_bf16 v[104:107], v[182:185], v[216:219], v[104:107]
	v_mfma_f32_16x16x32_bf16 v[100:103], v[186:189], v[212:215], v[100:103]
	v_mfma_f32_16x16x32_bf16 v[100:103], v[190:193], v[216:219], v[100:103]
	v_mfma_f32_16x16x32_bf16 v[88:91], v[178:181], v[220:223], v[88:91]
	v_mfma_f32_16x16x32_bf16 v[88:91], v[182:185], v[224:227], v[88:91]
	v_mfma_f32_16x16x32_bf16 v[84:87], v[186:189], v[220:223], v[84:87]
	v_mfma_f32_16x16x32_bf16 v[84:87], v[190:193], v[224:227], v[84:87]
	v_mfma_f32_16x16x32_bf16 v[72:75], v[178:181], v[228:231], v[72:75]
	v_mfma_f32_16x16x32_bf16 v[72:75], v[182:185], v[232:235], v[72:75]
	v_mfma_f32_16x16x32_bf16 v[68:71], v[186:189], v[228:231], v[68:71]
	v_mfma_f32_16x16x32_bf16 v[68:71], v[190:193], v[232:235], v[68:71]
	s_setprio 0
	s_barrier
	s_add_i32 s26, s26, s65
	v_lshl_add_u64 v[236:237], s[8:9], 0, v[134:135]
	s_mov_b32 m0, s26
	ds_read_b128 v[194:197], v165 offset:16384
	ds_read_b128 v[208:211], v165 offset:17408
	ds_read_b128 v[212:215], v165 offset:18432
	ds_read_b128 v[216:219], v165 offset:19456
	ds_read_b128 v[220:223], v165 offset:20480
	ds_read_b128 v[224:227], v165 offset:21504
	ds_read_b128 v[228:231], v165 offset:22528
	ds_read_b128 v[232:235], v165 offset:23552
	global_load_lds_dwordx4 v[236:237], off
	s_add_i32 m0, s26, 0x2000
	s_add_u32 s26, s8, 0x80000
	v_lshl_add_u64 v[238:239], s[8:9], 0, v[138:139]
	s_addc_u32 s27, s9, 0
	s_add_i32 s33, s33, s65
	global_load_lds_dwordx4 v[238:239], off
	v_lshl_add_u64 v[240:241], s[26:27], 0, v[134:135]
	s_mov_b32 m0, s33
	v_lshl_add_u64 v[242:243], s[12:13], 0, v[136:137]
	global_load_lds_dwordx4 v[240:241], off
	v_lshl_add_u64 v[240:241], s[26:27], 0, v[138:139]
	s_add_i32 m0, s33, 0x2000
	s_nop 0
	global_load_lds_dwordx4 v[240:241], off
	v_lshl_add_u64 v[240:241], s[12:13], 0, v[132:133]
	s_mov_b32 m0, s47
	s_nop 0
	global_load_lds_dwordx4 v[240:241], off
	s_mov_b32 m0, s66
	s_nop 0
	global_load_lds_dwordx4 v[242:243], off
	s_waitcnt vmcnt(8)
	s_waitcnt lgkmcnt(0)
	s_barrier
	s_setprio 1
	s_waitcnt lgkmcnt(0)
	v_mfma_f32_16x16x32_bf16 v[64:67], v[148:151], v[194:197], v[64:67]
	v_mfma_f32_16x16x32_bf16 v[64:67], v[152:155], v[208:211], v[64:67]
	v_mfma_f32_16x16x32_bf16 v[60:63], v[156:159], v[194:197], v[60:63]
	v_mfma_f32_16x16x32_bf16 v[60:63], v[166:169], v[208:211], v[60:63]
	v_mfma_f32_16x16x32_bf16 v[48:51], v[148:151], v[212:215], v[48:51]
	v_mfma_f32_16x16x32_bf16 v[48:51], v[152:155], v[216:219], v[48:51]
	v_mfma_f32_16x16x32_bf16 v[44:47], v[156:159], v[212:215], v[44:47]
	v_mfma_f32_16x16x32_bf16 v[44:47], v[166:169], v[216:219], v[44:47]
	v_mfma_f32_16x16x32_bf16 v[32:35], v[148:151], v[220:223], v[32:35]
	v_mfma_f32_16x16x32_bf16 v[32:35], v[152:155], v[224:227], v[32:35]
	v_mfma_f32_16x16x32_bf16 v[28:31], v[156:159], v[220:223], v[28:31]
	v_mfma_f32_16x16x32_bf16 v[28:31], v[166:169], v[224:227], v[28:31]
	v_mfma_f32_16x16x32_bf16 v[16:19], v[148:151], v[228:231], v[16:19]
	v_mfma_f32_16x16x32_bf16 v[16:19], v[152:155], v[232:235], v[16:19]
	v_mfma_f32_16x16x32_bf16 v[12:15], v[156:159], v[228:231], v[12:15]
	v_mfma_f32_16x16x32_bf16 v[12:15], v[166:169], v[232:235], v[12:15]
	s_setprio 0
	s_setprio 1
	v_mfma_f32_16x16x32_bf16 v[56:59], v[178:181], v[194:197], v[56:59]
	v_mfma_f32_16x16x32_bf16 v[56:59], v[182:185], v[208:211], v[56:59]
	v_mfma_f32_16x16x32_bf16 v[52:55], v[186:189], v[194:197], v[52:55]
	v_mfma_f32_16x16x32_bf16 v[52:55], v[190:193], v[208:211], v[52:55]
	v_mfma_f32_16x16x32_bf16 v[40:43], v[178:181], v[212:215], v[40:43]
	v_mfma_f32_16x16x32_bf16 v[40:43], v[182:185], v[216:219], v[40:43]
	v_mfma_f32_16x16x32_bf16 v[36:39], v[186:189], v[212:215], v[36:39]
	v_mfma_f32_16x16x32_bf16 v[36:39], v[190:193], v[216:219], v[36:39]
	v_mfma_f32_16x16x32_bf16 v[24:27], v[178:181], v[220:223], v[24:27]
	v_mfma_f32_16x16x32_bf16 v[24:27], v[182:185], v[224:227], v[24:27]
	v_mfma_f32_16x16x32_bf16 v[20:23], v[186:189], v[220:223], v[20:23]
	v_mfma_f32_16x16x32_bf16 v[20:23], v[190:193], v[224:227], v[20:23]
	v_mfma_f32_16x16x32_bf16 v[8:11], v[178:181], v[228:231], v[8:11]
	v_mfma_f32_16x16x32_bf16 v[8:11], v[182:185], v[232:235], v[8:11]
	v_mfma_f32_16x16x32_bf16 v[4:7], v[186:189], v[228:231], v[4:7]
	v_mfma_f32_16x16x32_bf16 v[4:7], v[190:193], v[232:235], v[4:7]
	s_setprio 0
	s_barrier
	s_add_i32 s26, 0, 0x18000
	v_add_u32_e32 v1, s26, v162
	s_add_i32 s27, 0, 0x1c000
	ds_read_b128 v[148:151], v1
	ds_read_b128 v[152:155], v1 offset:1024
	ds_read_b128 v[156:159], v1 offset:2048
	ds_read_b128 v[166:169], v1 offset:3072
	v_add_u32_e32 v1, s27, v162
	ds_read_b128 v[178:181], v1
	ds_read_b128 v[182:185], v1 offset:1024
	ds_read_b128 v[186:189], v1 offset:2048
	ds_read_b128 v[190:193], v1 offset:3072
	s_add_u32 s12, s12, 0x80000
	s_addc_u32 s13, s13, 0
	s_mov_b32 m0, s67
	v_lshl_add_u64 v[244:245], s[12:13], 0, v[132:133]
	ds_read_b128 v[194:197], v165 offset:32768
	ds_read_b128 v[208:211], v165 offset:33792
	ds_read_b128 v[212:215], v165 offset:34816
	ds_read_b128 v[216:219], v165 offset:35840
	ds_read_b128 v[220:223], v165 offset:36864
	ds_read_b128 v[224:227], v165 offset:37888
	ds_read_b128 v[228:231], v165 offset:38912
	ds_read_b128 v[232:235], v165 offset:39936
	global_load_lds_dwordx4 v[244:245], off
	v_lshl_add_u64 v[244:245], s[12:13], 0, v[136:137]
	s_mov_b32 m0, s68
	s_nop 0
	global_load_lds_dwordx4 v[244:245], off
	s_waitcnt vmcnt(8)
	s_waitcnt lgkmcnt(0)
	s_barrier
	s_setprio 1
	s_waitcnt lgkmcnt(0)
	v_mfma_f32_16x16x32_bf16 v[128:131], v[148:151], v[194:197], v[128:131]
	v_mfma_f32_16x16x32_bf16 v[128:131], v[152:155], v[208:211], v[128:131]
	v_mfma_f32_16x16x32_bf16 v[124:127], v[156:159], v[194:197], v[124:127]
	v_mfma_f32_16x16x32_bf16 v[124:127], v[166:169], v[208:211], v[124:127]
	v_mfma_f32_16x16x32_bf16 v[112:115], v[148:151], v[212:215], v[112:115]
	v_mfma_f32_16x16x32_bf16 v[112:115], v[152:155], v[216:219], v[112:115]
	v_mfma_f32_16x16x32_bf16 v[108:111], v[156:159], v[212:215], v[108:111]
	v_mfma_f32_16x16x32_bf16 v[108:111], v[166:169], v[216:219], v[108:111]
	v_mfma_f32_16x16x32_bf16 v[96:99], v[148:151], v[220:223], v[96:99]
	v_mfma_f32_16x16x32_bf16 v[96:99], v[152:155], v[224:227], v[96:99]
	v_mfma_f32_16x16x32_bf16 v[92:95], v[156:159], v[220:223], v[92:95]
	v_mfma_f32_16x16x32_bf16 v[92:95], v[166:169], v[224:227], v[92:95]
	v_mfma_f32_16x16x32_bf16 v[80:83], v[148:151], v[228:231], v[80:83]
	v_mfma_f32_16x16x32_bf16 v[80:83], v[152:155], v[232:235], v[80:83]
	v_mfma_f32_16x16x32_bf16 v[76:79], v[156:159], v[228:231], v[76:79]
	v_mfma_f32_16x16x32_bf16 v[76:79], v[166:169], v[232:235], v[76:79]
	s_setprio 0
	s_setprio 1
	v_mfma_f32_16x16x32_bf16 v[120:123], v[178:181], v[194:197], v[120:123]
	v_mfma_f32_16x16x32_bf16 v[120:123], v[182:185], v[208:211], v[120:123]
	v_mfma_f32_16x16x32_bf16 v[116:119], v[186:189], v[194:197], v[116:119]
	v_mfma_f32_16x16x32_bf16 v[116:119], v[190:193], v[208:211], v[116:119]
	v_mfma_f32_16x16x32_bf16 v[104:107], v[178:181], v[212:215], v[104:107]
	v_mfma_f32_16x16x32_bf16 v[104:107], v[182:185], v[216:219], v[104:107]
	v_mfma_f32_16x16x32_bf16 v[100:103], v[186:189], v[212:215], v[100:103]
	v_mfma_f32_16x16x32_bf16 v[100:103], v[190:193], v[216:219], v[100:103]
	v_mfma_f32_16x16x32_bf16 v[88:91], v[178:181], v[220:223], v[88:91]
	v_mfma_f32_16x16x32_bf16 v[88:91], v[182:185], v[224:227], v[88:91]
	v_mfma_f32_16x16x32_bf16 v[84:87], v[186:189], v[220:223], v[84:87]
	v_mfma_f32_16x16x32_bf16 v[84:87], v[190:193], v[224:227], v[84:87]
	v_mfma_f32_16x16x32_bf16 v[72:75], v[178:181], v[228:231], v[72:75]
	v_mfma_f32_16x16x32_bf16 v[72:75], v[182:185], v[232:235], v[72:75]
	v_mfma_f32_16x16x32_bf16 v[68:71], v[186:189], v[228:231], v[68:71]
	v_mfma_f32_16x16x32_bf16 v[68:71], v[190:193], v[232:235], v[68:71]
	s_setprio 0
	s_barrier
	s_add_i32 s12, s26, s65
	v_lshl_add_u64 v[236:237], v[236:237], 0, s[18:19]
	s_mov_b32 m0, s12
	ds_read_b128 v[194:197], v165 offset:49152
	ds_read_b128 v[208:211], v165 offset:50176
	ds_read_b128 v[212:215], v165 offset:51200
	ds_read_b128 v[216:219], v165 offset:52224
	ds_read_b128 v[220:223], v165 offset:53248
	ds_read_b128 v[224:227], v165 offset:54272
	ds_read_b128 v[228:231], v165 offset:55296
	ds_read_b128 v[232:235], v165 offset:56320
	global_load_lds_dwordx4 v[236:237], off
	s_add_i32 m0, s12, 0x2000
	s_add_u32 s8, s8, 0x80080
	v_lshl_add_u64 v[236:237], v[238:239], 0, s[18:19]
	s_addc_u32 s9, s9, 0
	s_add_i32 s12, s27, s65
	global_load_lds_dwordx4 v[236:237], off
	v_lshl_add_u64 v[236:237], s[8:9], 0, v[134:135]
	s_mov_b32 m0, s12
	s_nop 0
	global_load_lds_dwordx4 v[236:237], off
	v_lshl_add_u64 v[236:237], s[8:9], 0, v[138:139]
	s_add_i32 m0, s12, 0x2000
	s_nop 0
	global_load_lds_dwordx4 v[236:237], off
	v_lshl_add_u64 v[236:237], v[240:241], 0, s[18:19]
	s_mov_b32 m0, s82
	s_nop 0
	global_load_lds_dwordx4 v[236:237], off
	v_lshl_add_u64 v[236:237], v[242:243], 0, s[18:19]
	s_mov_b32 m0, s83
	s_nop 0
	global_load_lds_dwordx4 v[236:237], off
	s_waitcnt vmcnt(8)
	s_waitcnt lgkmcnt(0)
	s_barrier
	s_setprio 1
	s_waitcnt lgkmcnt(0)
	v_mfma_f32_16x16x32_bf16 v[64:67], v[148:151], v[194:197], v[64:67]
	v_mfma_f32_16x16x32_bf16 v[64:67], v[152:155], v[208:211], v[64:67]
	v_mfma_f32_16x16x32_bf16 v[60:63], v[156:159], v[194:197], v[60:63]
	v_mfma_f32_16x16x32_bf16 v[60:63], v[166:169], v[208:211], v[60:63]
	v_mfma_f32_16x16x32_bf16 v[48:51], v[148:151], v[212:215], v[48:51]
	v_mfma_f32_16x16x32_bf16 v[48:51], v[152:155], v[216:219], v[48:51]
	v_mfma_f32_16x16x32_bf16 v[44:47], v[156:159], v[212:215], v[44:47]
	v_mfma_f32_16x16x32_bf16 v[44:47], v[166:169], v[216:219], v[44:47]
	v_mfma_f32_16x16x32_bf16 v[32:35], v[148:151], v[220:223], v[32:35]
	v_mfma_f32_16x16x32_bf16 v[32:35], v[152:155], v[224:227], v[32:35]
	v_mfma_f32_16x16x32_bf16 v[28:31], v[156:159], v[220:223], v[28:31]
	v_mfma_f32_16x16x32_bf16 v[28:31], v[166:169], v[224:227], v[28:31]
	v_mfma_f32_16x16x32_bf16 v[16:19], v[148:151], v[228:231], v[16:19]
	v_mfma_f32_16x16x32_bf16 v[16:19], v[152:155], v[232:235], v[16:19]
	v_mfma_f32_16x16x32_bf16 v[12:15], v[156:159], v[228:231], v[12:15]
	v_mfma_f32_16x16x32_bf16 v[12:15], v[166:169], v[232:235], v[12:15]
	s_setprio 0
	s_setprio 1
	v_mfma_f32_16x16x32_bf16 v[56:59], v[178:181], v[194:197], v[56:59]
	v_mfma_f32_16x16x32_bf16 v[56:59], v[182:185], v[208:211], v[56:59]
	v_mfma_f32_16x16x32_bf16 v[52:55], v[186:189], v[194:197], v[52:55]
	v_mfma_f32_16x16x32_bf16 v[52:55], v[190:193], v[208:211], v[52:55]
	v_mfma_f32_16x16x32_bf16 v[40:43], v[178:181], v[212:215], v[40:43]
	v_mfma_f32_16x16x32_bf16 v[40:43], v[182:185], v[216:219], v[40:43]
	v_mfma_f32_16x16x32_bf16 v[36:39], v[186:189], v[212:215], v[36:39]
	v_mfma_f32_16x16x32_bf16 v[36:39], v[190:193], v[216:219], v[36:39]
	v_mfma_f32_16x16x32_bf16 v[24:27], v[178:181], v[220:223], v[24:27]
	v_mfma_f32_16x16x32_bf16 v[24:27], v[182:185], v[224:227], v[24:27]
	v_mfma_f32_16x16x32_bf16 v[20:23], v[186:189], v[220:223], v[20:23]
	v_mfma_f32_16x16x32_bf16 v[20:23], v[190:193], v[224:227], v[20:23]
	v_mfma_f32_16x16x32_bf16 v[8:11], v[178:181], v[228:231], v[8:11]
	v_mfma_f32_16x16x32_bf16 v[8:11], v[182:185], v[232:235], v[8:11]
	v_mfma_f32_16x16x32_bf16 v[4:7], v[186:189], v[228:231], v[4:7]
	v_mfma_f32_16x16x32_bf16 v[4:7], v[190:193], v[232:235], v[4:7]
	s_setprio 0
	s_barrier
	s_add_i32 s22, s22, 2
	s_add_u32 s4, s4, 0x100
	s_addc_u32 s5, s5, 0
	s_add_u32 s11, s11, 0x100
	s_addc_u32 s21, s21, 0
	s_cmp_gt_u32 s22, 29
	s_cbranch_scc0 .LBB0_1184
	s_and_b64 vcc, exec, s[54:55]
	s_cbranch_vccz .LBB0_1187
	s_barrier
